# opt40: opt26 + GEMM compute segments lead with their MFMAs: s_setprio 1 moved in front of the opening barrier, redundant second lgkmcnt(0) wait deleted (32 sites)
# speedup vs baseline: 1.0113x; 1.0079x over previous
; #define PG8_STAGE(bufoff, gbase, voff) do { _Pragma("unroll") for (int _i = 0; _i < 2; ++_i) \
;         __builtin_amdgcn_global_load_lds((const unsigned*)((const char*)(gbase) + (voff)[_i]), (LAS unsigned*)(lds + (bufoff) + ldsw + _i * 8192), 16, 0, 0); } while (0)
; #define PG8_LDA(dst, b, h) do { _Pragma("unroll") for (int m = 0; m < 4; ++m) _Pragma("unroll") for (int k = 0; k < 2; ++k) dst[m][k] = *(const LAS bf16x8*)(lds + PG8_SA(b, h) + aoff + m * 2048 + k * 1024); } while (0)
; #define PG8_LDB(dst, b, h) do { _Pragma("unroll") for (int n = 0; n < 2; ++n) _Pragma("unroll") for (int k = 0; k < 2; ++k) dst[n][k] = *(const LAS bf16x8*)(lds + PG8_SB(b, h) + boff + n * 2048 + k * 1024); } while (0)
; #define PG8_MMA(ai, bj, At, Bt) do { __builtin_amdgcn_s_setprio(1); _Pragma("unroll") for (int m = 0; m < 4; ++m) _Pragma("unroll") for (int n = 0; n < 2; ++n) _Pragma("unroll") for (int k = 0; k < 2; ++k) \
;         acc[ai][bj][m][n] = __builtin_amdgcn_mfma_f32_16x16x32_bf16(Bt[n][k], At[m][k], acc[ai][bj][m][n], 0, 0, 0); __builtin_amdgcn_s_setprio(0); } while (0)
; #define PG8_WAIT_V(n) asm volatile("s_waitcnt vmcnt(" #n ")" ::: "memory")
; #define PG8_WAIT_L(n) asm volatile("s_waitcnt lgkmcnt(" #n ")" ::: "memory")
; #define PG8_BAR __builtin_amdgcn_s_barrier()
; #define PG8_SCHED __builtin_amdgcn_sched_barrier(0)
; template <class Epi>
; __device__ __forceinline__ void gemm_phase(LAS unsigned char* lds, const Gemm g, const StaticOrder& S, const Epi& E) {
;     ...
;             const bool last = (t == nt - 2);
;             if constexpr (Epi::HAS_MID) { if (t == nt1) E.mid(acc, cur, wr, wc, fr, fq); }
;             const char* a1 = cA + ((Epi::HAS_MID && t >= nt1) ? dA2 : 0) + (size_t)(t + 1) * kstep;
;             const char* a2 = last ? nA : cA + ((Epi::HAS_MID && t + 2 >= nt1) ? dA2 : 0) + (size_t)(t + 2) * kstep; const char* b2 = last ? nB : cB + ((Epi::HAS_MID && t + 2 >= nt1) ? dB2 : 0) + (size_t)(t + 2) * kstep;
;             const char* a3 = a2 + kstep; const char* b3 = b2 + kstep;
;             PG8_LDB(B0, 0, 0); PG8_LDB(B1, 0, 1); PG8_SCHED; PG8_LDA(At, 0, 0); PG8_STAGE(PG8_SA(1, 1), a1 + hsA, voffA);
;             PG8_WAIT_V(8); PG8_WAIT_L(0); PG8_BAR; PG8_MMA(0, 0, At, B0); PG8_MMA(0, 1, At, B1); PG8_BAR; PG8_SCHED;
.LBB0_214:
	ds_read_b128 v[144:147], v155
	ds_read_b128 v[148:151], v155 offset:1024
	ds_read_b128 v[162:165], v155 offset:2048
	ds_read_b128 v[166:169], v155 offset:3072
	ds_read_b128 v[180:183], v156
	ds_read_b128 v[184:187], v156 offset:1024
	ds_read_b128 v[188:191], v156 offset:2048
	ds_read_b128 v[192:195], v156 offset:3072
	s_add_u32 s38, s58, 0xfffc0080
	s_addc_u32 s39, s59, -1
	s_cmp_eq_u32 s37, 12
	s_cselect_b32 s63, s6, s39
	s_cselect_b32 s62, s7, s38
	s_cselect_b32 s61, s11, s36
	s_cselect_b32 s60, s13, s35
	s_add_i32 m0, s19, 0xc000
	ds_read_b128 v[196:199], v157
	ds_read_b128 v[200:203], v157 offset:1024
	ds_read_b128 v[204:207], v157 offset:2048
	ds_read_b128 v[208:211], v157 offset:3072
	ds_read_b128 v[212:215], v157 offset:4096
	ds_read_b128 v[216:219], v157 offset:5120
	ds_read_b128 v[220:223], v157 offset:6144
	ds_read_b128 v[224:227], v157 offset:7168
	global_load_lds_dwordx4 v136, s[58:59]
	s_add_i32 m0, s19, 0xe000
	s_nop 0
	global_load_lds_dwordx4 v138, s[58:59]
	s_waitcnt vmcnt(8)
	s_waitcnt lgkmcnt(0)
	s_setprio 1
	s_barrier

; #define PG8_STAGE(bufoff, gbase, voff) do { _Pragma("unroll") for (int _i = 0; _i < 2; ++_i) \
;         __builtin_amdgcn_global_load_lds((const unsigned*)((const char*)(gbase) + (voff)[_i]), (LAS unsigned*)(lds + (bufoff) + ldsw + _i * 8192), 16, 0, 0); } while (0)
; #define PG8_LDA(dst, b, h) do { _Pragma("unroll") for (int m = 0; m < 4; ++m) _Pragma("unroll") for (int k = 0; k < 2; ++k) dst[m][k] = *(const LAS bf16x8*)(lds + PG8_SA(b, h) + aoff + m * 2048 + k * 1024); } while (0)
; #define PG8_MMA(ai, bj, At, Bt) do { __builtin_amdgcn_s_setprio(1); _Pragma("unroll") for (int m = 0; m < 4; ++m) _Pragma("unroll") for (int n = 0; n < 2; ++n) _Pragma("unroll") for (int k = 0; k < 2; ++k) \
;         acc[ai][bj][m][n] = __builtin_amdgcn_mfma_f32_16x16x32_bf16(Bt[n][k], At[m][k], acc[ai][bj][m][n], 0, 0, 0); __builtin_amdgcn_s_setprio(0); } while (0)
; #define PG8_WAIT_V(n) asm volatile("s_waitcnt vmcnt(" #n ")" ::: "memory")
; #define PG8_WAIT_L(n) asm volatile("s_waitcnt lgkmcnt(" #n ")" ::: "memory")
; #define PG8_BAR __builtin_amdgcn_s_barrier()
; #define PG8_SCHED __builtin_amdgcn_sched_barrier(0)
; template <class Epi>
; __device__ __forceinline__ void gemm_phase(LAS unsigned char* lds, const Gemm g, const StaticOrder& S, const Epi& E) {
;     ...
;             PG8_WAIT_V(8); PG8_WAIT_L(0); PG8_BAR; PG8_MMA(0, 0, At, B0); PG8_MMA(0, 1, At, B1); PG8_BAR; PG8_SCHED;
;             PG8_LDA(At, 0, 1); PG8_STAGE(PG8_SB(0, 0), b2, voffB); PG8_STAGE(PG8_SB(0, 1), b2 + hsB, voffB); PG8_STAGE(PG8_SA(0, 0), a2, voffA);
;             PG8_WAIT_V(8); PG8_WAIT_L(0); PG8_BAR; PG8_MMA(1, 0, At, B0); PG8_MMA(1, 1, At, B1); PG8_BAR; PG8_SCHED;
	v_mfma_f32_16x16x32_bf16 v[124:127], v[144:147], v[196:199], v[124:127]
	v_mfma_f32_16x16x32_bf16 v[120:123], v[162:165], v[196:199], v[120:123]
	v_mfma_f32_16x16x32_bf16 v[108:111], v[144:147], v[204:207], v[108:111]
	v_mfma_f32_16x16x32_bf16 v[104:107], v[162:165], v[204:207], v[104:107]
	v_mfma_f32_16x16x32_bf16 v[92:95], v[144:147], v[212:215], v[92:95]
	v_mfma_f32_16x16x32_bf16 v[88:91], v[162:165], v[212:215], v[88:91]
	v_mfma_f32_16x16x32_bf16 v[76:79], v[144:147], v[220:223], v[76:79]
	v_mfma_f32_16x16x32_bf16 v[72:75], v[162:165], v[220:223], v[72:75]
	v_mfma_f32_16x16x32_bf16 v[124:127], v[148:151], v[200:203], v[124:127]
	v_mfma_f32_16x16x32_bf16 v[120:123], v[166:169], v[200:203], v[120:123]
	v_mfma_f32_16x16x32_bf16 v[108:111], v[148:151], v[208:211], v[108:111]
	v_mfma_f32_16x16x32_bf16 v[104:107], v[166:169], v[208:211], v[104:107]
	v_mfma_f32_16x16x32_bf16 v[92:95], v[148:151], v[216:219], v[92:95]
	v_mfma_f32_16x16x32_bf16 v[88:91], v[166:169], v[216:219], v[88:91]
	v_mfma_f32_16x16x32_bf16 v[76:79], v[148:151], v[224:227], v[76:79]
	v_mfma_f32_16x16x32_bf16 v[72:75], v[166:169], v[224:227], v[72:75]
	s_setprio 0
	s_setprio 1
	v_mfma_f32_16x16x32_bf16 v[116:119], v[180:183], v[196:199], v[116:119]
	v_mfma_f32_16x16x32_bf16 v[112:115], v[188:191], v[196:199], v[112:115]
	v_mfma_f32_16x16x32_bf16 v[100:103], v[180:183], v[204:207], v[100:103]
	v_mfma_f32_16x16x32_bf16 v[96:99], v[188:191], v[204:207], v[96:99]
	v_mfma_f32_16x16x32_bf16 v[84:87], v[180:183], v[212:215], v[84:87]
	v_mfma_f32_16x16x32_bf16 v[80:83], v[188:191], v[212:215], v[80:83]
	v_mfma_f32_16x16x32_bf16 v[68:71], v[180:183], v[220:223], v[68:71]
	v_mfma_f32_16x16x32_bf16 v[64:67], v[188:191], v[220:223], v[64:67]
	v_mfma_f32_16x16x32_bf16 v[116:119], v[184:187], v[200:203], v[116:119]
	v_mfma_f32_16x16x32_bf16 v[112:115], v[192:195], v[200:203], v[112:115]
	v_mfma_f32_16x16x32_bf16 v[100:103], v[184:187], v[208:211], v[100:103]
	v_mfma_f32_16x16x32_bf16 v[96:99], v[192:195], v[208:211], v[96:99]
	v_mfma_f32_16x16x32_bf16 v[84:87], v[184:187], v[216:219], v[84:87]
	v_mfma_f32_16x16x32_bf16 v[80:83], v[192:195], v[216:219], v[80:83]
	v_mfma_f32_16x16x32_bf16 v[68:71], v[184:187], v[224:227], v[68:71]
	v_mfma_f32_16x16x32_bf16 v[64:67], v[192:195], v[224:227], v[64:67]
	s_setprio 0
	s_barrier
	s_add_i32 s38, s30, s16
	s_mov_b32 m0, s38
	ds_read_b128 v[196:199], v157 offset:16384
	ds_read_b128 v[200:203], v157 offset:17408
	ds_read_b128 v[204:207], v157 offset:18432
	ds_read_b128 v[208:211], v157 offset:19456
	ds_read_b128 v[212:215], v157 offset:20480
	ds_read_b128 v[216:219], v157 offset:21504
	ds_read_b128 v[220:223], v157 offset:22528
	ds_read_b128 v[224:227], v157 offset:23552
	global_load_lds_dwordx4 v132, s[60:61]
	s_add_i32 m0, s38, 0x2000
	s_add_u32 s38, s60, 0x40000
	s_addc_u32 s39, s61, 0
	s_add_i32 s40, s31, s16
	global_load_lds_dwordx4 v128, s[60:61]
	s_mov_b32 m0, s40
	s_nop 0
	global_load_lds_dwordx4 v132, s[38:39]
	s_add_i32 m0, s40, 0x2000
	s_nop 0
	global_load_lds_dwordx4 v128, s[38:39]
	s_mov_b32 m0, s19
	s_nop 0
	global_load_lds_dwordx4 v134, s[62:63]
	s_mov_b32 m0, s22
	s_nop 0
	global_load_lds_dwordx4 v130, s[62:63]
	s_waitcnt vmcnt(8)
	s_waitcnt lgkmcnt(0)
	s_setprio 1
	s_barrier

; #define PG8_STAGE(bufoff, gbase, voff) do { _Pragma("unroll") for (int _i = 0; _i < 2; ++_i) \
;         __builtin_amdgcn_global_load_lds((const unsigned*)((const char*)(gbase) + (voff)[_i]), (LAS unsigned*)(lds + (bufoff) + ldsw + _i * 8192), 16, 0, 0); } while (0)
; #define PG8_LDA(dst, b, h) do { _Pragma("unroll") for (int m = 0; m < 4; ++m) _Pragma("unroll") for (int k = 0; k < 2; ++k) dst[m][k] = *(const LAS bf16x8*)(lds + PG8_SA(b, h) + aoff + m * 2048 + k * 1024); } while (0)
; #define PG8_LDB(dst, b, h) do { _Pragma("unroll") for (int n = 0; n < 2; ++n) _Pragma("unroll") for (int k = 0; k < 2; ++k) dst[n][k] = *(const LAS bf16x8*)(lds + PG8_SB(b, h) + boff + n * 2048 + k * 1024); } while (0)
; #define PG8_MMA(ai, bj, At, Bt) do { __builtin_amdgcn_s_setprio(1); _Pragma("unroll") for (int m = 0; m < 4; ++m) _Pragma("unroll") for (int n = 0; n < 2; ++n) _Pragma("unroll") for (int k = 0; k < 2; ++k) \
;         acc[ai][bj][m][n] = __builtin_amdgcn_mfma_f32_16x16x32_bf16(Bt[n][k], At[m][k], acc[ai][bj][m][n], 0, 0, 0); __builtin_amdgcn_s_setprio(0); } while (0)
; #define PG8_WAIT_V(n) asm volatile("s_waitcnt vmcnt(" #n ")" ::: "memory")
; #define PG8_WAIT_L(n) asm volatile("s_waitcnt lgkmcnt(" #n ")" ::: "memory")
; #define PG8_BAR __builtin_amdgcn_s_barrier()
; #define PG8_SCHED __builtin_amdgcn_sched_barrier(0)
; template <class Epi>
; __device__ __forceinline__ void gemm_phase(LAS unsigned char* lds, const Gemm g, const StaticOrder& S, const Epi& E) {
;     ...
;             PG8_WAIT_V(8); PG8_WAIT_L(0); PG8_BAR; PG8_MMA(1, 0, At, B0); PG8_MMA(1, 1, At, B1); PG8_BAR; PG8_SCHED;
;             PG8_LDB(B0, 1, 0); PG8_LDB(B1, 1, 1); PG8_SCHED; PG8_LDA(At, 1, 0); PG8_STAGE(PG8_SA(0, 1), a2 + hsA, voffA);
;             PG8_WAIT_V(8); PG8_WAIT_L(0); PG8_BAR; PG8_MMA(0, 0, At, B0); PG8_MMA(0, 1, At, B1); PG8_BAR; PG8_SCHED;
	v_mfma_f32_16x16x32_bf16 v[60:63], v[144:147], v[196:199], v[60:63]
	v_mfma_f32_16x16x32_bf16 v[56:59], v[162:165], v[196:199], v[56:59]
	v_mfma_f32_16x16x32_bf16 v[44:47], v[144:147], v[204:207], v[44:47]
	v_mfma_f32_16x16x32_bf16 v[40:43], v[162:165], v[204:207], v[40:43]
	v_mfma_f32_16x16x32_bf16 v[28:31], v[144:147], v[212:215], v[28:31]
	v_mfma_f32_16x16x32_bf16 v[24:27], v[162:165], v[212:215], v[24:27]
	v_mfma_f32_16x16x32_bf16 v[12:15], v[144:147], v[220:223], v[12:15]
	v_mfma_f32_16x16x32_bf16 v[8:11], v[162:165], v[220:223], v[8:11]
	v_mfma_f32_16x16x32_bf16 v[60:63], v[148:151], v[200:203], v[60:63]
	v_mfma_f32_16x16x32_bf16 v[56:59], v[166:169], v[200:203], v[56:59]
	v_mfma_f32_16x16x32_bf16 v[44:47], v[148:151], v[208:211], v[44:47]
	v_mfma_f32_16x16x32_bf16 v[40:43], v[166:169], v[208:211], v[40:43]
	v_mfma_f32_16x16x32_bf16 v[28:31], v[148:151], v[216:219], v[28:31]
	v_mfma_f32_16x16x32_bf16 v[24:27], v[166:169], v[216:219], v[24:27]
	v_mfma_f32_16x16x32_bf16 v[12:15], v[148:151], v[224:227], v[12:15]
	v_mfma_f32_16x16x32_bf16 v[8:11], v[166:169], v[224:227], v[8:11]
	s_setprio 0
	s_setprio 1
	v_mfma_f32_16x16x32_bf16 v[52:55], v[180:183], v[196:199], v[52:55]
	v_mfma_f32_16x16x32_bf16 v[48:51], v[188:191], v[196:199], v[48:51]
	v_mfma_f32_16x16x32_bf16 v[36:39], v[180:183], v[204:207], v[36:39]
	v_mfma_f32_16x16x32_bf16 v[32:35], v[188:191], v[204:207], v[32:35]
	v_mfma_f32_16x16x32_bf16 v[20:23], v[180:183], v[212:215], v[20:23]
	v_mfma_f32_16x16x32_bf16 v[16:19], v[188:191], v[212:215], v[16:19]
	v_mfma_f32_16x16x32_bf16 v[4:7], v[180:183], v[220:223], v[4:7]
	v_mfma_f32_16x16x32_bf16 v[0:3], v[188:191], v[220:223], v[0:3]
	v_mfma_f32_16x16x32_bf16 v[52:55], v[184:187], v[200:203], v[52:55]
	v_mfma_f32_16x16x32_bf16 v[48:51], v[192:195], v[200:203], v[48:51]
	v_mfma_f32_16x16x32_bf16 v[36:39], v[184:187], v[208:211], v[36:39]
	v_mfma_f32_16x16x32_bf16 v[32:35], v[192:195], v[208:211], v[32:35]
	v_mfma_f32_16x16x32_bf16 v[20:23], v[184:187], v[216:219], v[20:23]
	v_mfma_f32_16x16x32_bf16 v[16:19], v[192:195], v[216:219], v[16:19]
	v_mfma_f32_16x16x32_bf16 v[4:7], v[184:187], v[224:227], v[4:7]
	v_mfma_f32_16x16x32_bf16 v[0:3], v[192:195], v[224:227], v[0:3]
	s_setprio 0
	s_barrier
	s_add_i32 s40, 0, 0x18000
	v_add_u32_e32 v159, s40, v153
	s_add_i32 s41, 0, 0x1c000
	ds_read_b128 v[144:147], v159
	ds_read_b128 v[148:151], v159 offset:1024
	ds_read_b128 v[162:165], v159 offset:2048
	ds_read_b128 v[166:169], v159 offset:3072
	v_add_u32_e32 v159, s41, v153
	ds_read_b128 v[180:183], v159
	ds_read_b128 v[184:187], v159 offset:1024
	ds_read_b128 v[188:191], v159 offset:2048
	ds_read_b128 v[192:195], v159 offset:3072
	s_add_u32 s38, s62, 0x40000
	s_addc_u32 s39, s63, 0
	s_mov_b32 m0, s23
	ds_read_b128 v[196:199], v157 offset:32768
	ds_read_b128 v[200:203], v157 offset:33792
	ds_read_b128 v[204:207], v157 offset:34816
	ds_read_b128 v[208:211], v157 offset:35840
	ds_read_b128 v[212:215], v157 offset:36864
	ds_read_b128 v[216:219], v157 offset:37888
	ds_read_b128 v[220:223], v157 offset:38912
	ds_read_b128 v[224:227], v157 offset:39936
	global_load_lds_dwordx4 v134, s[38:39]
	s_mov_b32 m0, s24
	s_nop 0
	global_load_lds_dwordx4 v130, s[38:39]
	s_waitcnt vmcnt(8)
	s_waitcnt lgkmcnt(0)
	s_setprio 1
	s_barrier

; #define PG8_STAGE(bufoff, gbase, voff) do { _Pragma("unroll") for (int _i = 0; _i < 2; ++_i) \
;         __builtin_amdgcn_global_load_lds((const unsigned*)((const char*)(gbase) + (voff)[_i]), (LAS unsigned*)(lds + (bufoff) + ldsw + _i * 8192), 16, 0, 0); } while (0)
; #define PG8_LDA(dst, b, h) do { _Pragma("unroll") for (int m = 0; m < 4; ++m) _Pragma("unroll") for (int k = 0; k < 2; ++k) dst[m][k] = *(const LAS bf16x8*)(lds + PG8_SA(b, h) + aoff + m * 2048 + k * 1024); } while (0)
; #define PG8_MMA(ai, bj, At, Bt) do { __builtin_amdgcn_s_setprio(1); _Pragma("unroll") for (int m = 0; m < 4; ++m) _Pragma("unroll") for (int n = 0; n < 2; ++n) _Pragma("unroll") for (int k = 0; k < 2; ++k) \
;         acc[ai][bj][m][n] = __builtin_amdgcn_mfma_f32_16x16x32_bf16(Bt[n][k], At[m][k], acc[ai][bj][m][n], 0, 0, 0); __builtin_amdgcn_s_setprio(0); } while (0)
; #define PG8_WAIT_V(n) asm volatile("s_waitcnt vmcnt(" #n ")" ::: "memory")
; #define PG8_WAIT_L(n) asm volatile("s_waitcnt lgkmcnt(" #n ")" ::: "memory")
; #define PG8_BAR __builtin_amdgcn_s_barrier()
; #define PG8_SCHED __builtin_amdgcn_sched_barrier(0)
; template <class Epi>
; __device__ __forceinline__ void gemm_phase(LAS unsigned char* lds, const Gemm g, const StaticOrder& S, const Epi& E) {
;     ...
;             PG8_WAIT_V(8); PG8_WAIT_L(0); PG8_BAR; PG8_MMA(0, 0, At, B0); PG8_MMA(0, 1, At, B1); PG8_BAR; PG8_SCHED;
;             PG8_LDA(At, 1, 1); PG8_STAGE(PG8_SB(1, 0), b3, voffB); PG8_STAGE(PG8_SB(1, 1), b3 + hsB, voffB); PG8_STAGE(PG8_SA(1, 0), a3, voffA);
;             PG8_WAIT_V(8); PG8_WAIT_L(0); PG8_BAR; PG8_MMA(1, 0, At, B0); PG8_MMA(1, 1, At, B1); PG8_BAR; PG8_SCHED;
	v_mfma_f32_16x16x32_bf16 v[124:127], v[144:147], v[196:199], v[124:127]
	v_mfma_f32_16x16x32_bf16 v[120:123], v[162:165], v[196:199], v[120:123]
	v_mfma_f32_16x16x32_bf16 v[108:111], v[144:147], v[204:207], v[108:111]
	v_mfma_f32_16x16x32_bf16 v[104:107], v[162:165], v[204:207], v[104:107]
	v_mfma_f32_16x16x32_bf16 v[92:95], v[144:147], v[212:215], v[92:95]
	v_mfma_f32_16x16x32_bf16 v[88:91], v[162:165], v[212:215], v[88:91]
	v_mfma_f32_16x16x32_bf16 v[76:79], v[144:147], v[220:223], v[76:79]
	v_mfma_f32_16x16x32_bf16 v[72:75], v[162:165], v[220:223], v[72:75]
	v_mfma_f32_16x16x32_bf16 v[124:127], v[148:151], v[200:203], v[124:127]
	v_mfma_f32_16x16x32_bf16 v[120:123], v[166:169], v[200:203], v[120:123]
	v_mfma_f32_16x16x32_bf16 v[108:111], v[148:151], v[208:211], v[108:111]
	v_mfma_f32_16x16x32_bf16 v[104:107], v[166:169], v[208:211], v[104:107]
	v_mfma_f32_16x16x32_bf16 v[92:95], v[148:151], v[216:219], v[92:95]
	v_mfma_f32_16x16x32_bf16 v[88:91], v[166:169], v[216:219], v[88:91]
	v_mfma_f32_16x16x32_bf16 v[76:79], v[148:151], v[224:227], v[76:79]
	v_mfma_f32_16x16x32_bf16 v[72:75], v[166:169], v[224:227], v[72:75]
	s_setprio 0
	s_setprio 1
	v_mfma_f32_16x16x32_bf16 v[116:119], v[180:183], v[196:199], v[116:119]
	v_mfma_f32_16x16x32_bf16 v[112:115], v[188:191], v[196:199], v[112:115]
	v_mfma_f32_16x16x32_bf16 v[100:103], v[180:183], v[204:207], v[100:103]
	v_mfma_f32_16x16x32_bf16 v[96:99], v[188:191], v[204:207], v[96:99]
	v_mfma_f32_16x16x32_bf16 v[84:87], v[180:183], v[212:215], v[84:87]
	v_mfma_f32_16x16x32_bf16 v[80:83], v[188:191], v[212:215], v[80:83]
	v_mfma_f32_16x16x32_bf16 v[68:71], v[180:183], v[220:223], v[68:71]
	v_mfma_f32_16x16x32_bf16 v[64:67], v[188:191], v[220:223], v[64:67]
	v_mfma_f32_16x16x32_bf16 v[116:119], v[184:187], v[200:203], v[116:119]
	v_mfma_f32_16x16x32_bf16 v[112:115], v[192:195], v[200:203], v[112:115]
	v_mfma_f32_16x16x32_bf16 v[100:103], v[184:187], v[208:211], v[100:103]
	v_mfma_f32_16x16x32_bf16 v[96:99], v[192:195], v[208:211], v[96:99]
	v_mfma_f32_16x16x32_bf16 v[84:87], v[184:187], v[216:219], v[84:87]
	v_mfma_f32_16x16x32_bf16 v[80:83], v[192:195], v[216:219], v[80:83]
	v_mfma_f32_16x16x32_bf16 v[68:71], v[184:187], v[224:227], v[68:71]
	v_mfma_f32_16x16x32_bf16 v[64:67], v[192:195], v[224:227], v[64:67]
	s_setprio 0
	s_barrier
	s_add_u32 s98, s60, 0x80
	s_addc_u32 s99, s61, 0
	s_add_u32 s100, s62, 0x80
	s_addc_u32 s101, s63, 0
	s_add_i32 s38, s40, s16
	s_mov_b32 m0, s38
	ds_read_b128 v[196:199], v157 offset:49152
	ds_read_b128 v[200:203], v157 offset:50176
	ds_read_b128 v[204:207], v157 offset:51200
	ds_read_b128 v[208:211], v157 offset:52224
	ds_read_b128 v[212:215], v157 offset:53248
	ds_read_b128 v[216:219], v157 offset:54272
	ds_read_b128 v[220:223], v157 offset:55296
	ds_read_b128 v[224:227], v157 offset:56320
	global_load_lds_dwordx4 v132, s[98:99]
	s_add_i32 m0, s38, 0x2000
	s_add_u32 s38, s60, 0x40080
	s_addc_u32 s39, s61, 0
	s_add_i32 s40, s41, s16
	global_load_lds_dwordx4 v128, s[98:99]
	s_mov_b32 m0, s40
	s_nop 0
	global_load_lds_dwordx4 v132, s[38:39]
	s_add_i32 m0, s40, 0x2000
	s_nop 0
	global_load_lds_dwordx4 v128, s[38:39]
	s_mov_b32 m0, s25
	s_nop 0
	global_load_lds_dwordx4 v134, s[100:101]
	s_mov_b32 m0, s26
	s_nop 0
	global_load_lds_dwordx4 v130, s[100:101]
	s_waitcnt vmcnt(8)
	s_waitcnt lgkmcnt(0)
	s_setprio 1
	s_barrier

; #define PG8_MMA(ai, bj, At, Bt) do { __builtin_amdgcn_s_setprio(1); _Pragma("unroll") for (int m = 0; m < 4; ++m) _Pragma("unroll") for (int n = 0; n < 2; ++n) _Pragma("unroll") for (int k = 0; k < 2; ++k) \
;         acc[ai][bj][m][n] = __builtin_amdgcn_mfma_f32_16x16x32_bf16(Bt[n][k], At[m][k], acc[ai][bj][m][n], 0, 0, 0); __builtin_amdgcn_s_setprio(0); } while (0)
; #define PG8_WAIT_V(n) asm volatile("s_waitcnt vmcnt(" #n ")" ::: "memory")
; #define PG8_WAIT_L(n) asm volatile("s_waitcnt lgkmcnt(" #n ")" ::: "memory")
; #define PG8_BAR __builtin_amdgcn_s_barrier()
; #define PG8_SCHED __builtin_amdgcn_sched_barrier(0)
; template <class Epi>
; __device__ __forceinline__ void gemm_phase(LAS unsigned char* lds, const Gemm g, const StaticOrder& S, const Epi& E) {
;     ...
;             PG8_WAIT_V(8); PG8_WAIT_L(0); PG8_BAR; PG8_MMA(1, 0, At, B0); PG8_MMA(1, 1, At, B1); PG8_BAR; PG8_SCHED;
;         }
;         if (wr == 0) PG8_BAR;
	v_mfma_f32_16x16x32_bf16 v[60:63], v[144:147], v[196:199], v[60:63]
	v_mfma_f32_16x16x32_bf16 v[56:59], v[162:165], v[196:199], v[56:59]
	v_mfma_f32_16x16x32_bf16 v[44:47], v[144:147], v[204:207], v[44:47]
	v_mfma_f32_16x16x32_bf16 v[40:43], v[162:165], v[204:207], v[40:43]
	v_mfma_f32_16x16x32_bf16 v[28:31], v[144:147], v[212:215], v[28:31]
	v_mfma_f32_16x16x32_bf16 v[24:27], v[162:165], v[212:215], v[24:27]
	v_mfma_f32_16x16x32_bf16 v[12:15], v[144:147], v[220:223], v[12:15]
	v_mfma_f32_16x16x32_bf16 v[8:11], v[162:165], v[220:223], v[8:11]
	v_mfma_f32_16x16x32_bf16 v[60:63], v[148:151], v[200:203], v[60:63]
	v_mfma_f32_16x16x32_bf16 v[56:59], v[166:169], v[200:203], v[56:59]
	v_mfma_f32_16x16x32_bf16 v[44:47], v[148:151], v[208:211], v[44:47]
	v_mfma_f32_16x16x32_bf16 v[40:43], v[166:169], v[208:211], v[40:43]
	v_mfma_f32_16x16x32_bf16 v[28:31], v[148:151], v[216:219], v[28:31]
	v_mfma_f32_16x16x32_bf16 v[24:27], v[166:169], v[216:219], v[24:27]
	v_mfma_f32_16x16x32_bf16 v[12:15], v[148:151], v[224:227], v[12:15]
	v_mfma_f32_16x16x32_bf16 v[8:11], v[166:169], v[224:227], v[8:11]
	s_setprio 0
	s_setprio 1
	v_mfma_f32_16x16x32_bf16 v[52:55], v[180:183], v[196:199], v[52:55]
	v_mfma_f32_16x16x32_bf16 v[48:51], v[188:191], v[196:199], v[48:51]
	v_mfma_f32_16x16x32_bf16 v[36:39], v[180:183], v[204:207], v[36:39]
	v_mfma_f32_16x16x32_bf16 v[32:35], v[188:191], v[204:207], v[32:35]
	v_mfma_f32_16x16x32_bf16 v[20:23], v[180:183], v[212:215], v[20:23]
	v_mfma_f32_16x16x32_bf16 v[16:19], v[188:191], v[212:215], v[16:19]
	v_mfma_f32_16x16x32_bf16 v[4:7], v[180:183], v[220:223], v[4:7]
	v_mfma_f32_16x16x32_bf16 v[0:3], v[188:191], v[220:223], v[0:3]
	v_mfma_f32_16x16x32_bf16 v[52:55], v[184:187], v[200:203], v[52:55]
	v_mfma_f32_16x16x32_bf16 v[48:51], v[192:195], v[200:203], v[48:51]
	v_mfma_f32_16x16x32_bf16 v[36:39], v[184:187], v[208:211], v[36:39]
	v_mfma_f32_16x16x32_bf16 v[32:35], v[192:195], v[208:211], v[32:35]
	v_mfma_f32_16x16x32_bf16 v[20:23], v[184:187], v[216:219], v[20:23]
	v_mfma_f32_16x16x32_bf16 v[16:19], v[192:195], v[216:219], v[16:19]
	v_mfma_f32_16x16x32_bf16 v[4:7], v[184:187], v[224:227], v[4:7]
	v_mfma_f32_16x16x32_bf16 v[0:3], v[192:195], v[224:227], v[0:3]
	s_setprio 0
	s_barrier
	s_add_i32 s37, s37, 2
	s_add_u32 s58, s58, 0x100
	s_addc_u32 s59, s59, 0
	s_add_u32 s35, s35, 0x100
	s_addc_u32 s36, s36, 0
	s_cmp_gt_u32 s37, 13
	s_cbranch_scc0 .LBB0_214
	s_and_b64 vcc, exec, s[8:9]
	s_cbranch_vccz .LBB0_217
	s_barrier

; #define PG8_STAGE(bufoff, gbase, voff) do { _Pragma("unroll") for (int _i = 0; _i < 2; ++_i) \
;         __builtin_amdgcn_global_load_lds((const unsigned*)((const char*)(gbase) + (voff)[_i]), (LAS unsigned*)(lds + (bufoff) + ldsw + _i * 8192), 16, 0, 0); } while (0)
; #define PG8_LDA(dst, b, h) do { _Pragma("unroll") for (int m = 0; m < 4; ++m) _Pragma("unroll") for (int k = 0; k < 2; ++k) dst[m][k] = *(const LAS bf16x8*)(lds + PG8_SA(b, h) + aoff + m * 2048 + k * 1024); } while (0)
; #define PG8_LDB(dst, b, h) do { _Pragma("unroll") for (int n = 0; n < 2; ++n) _Pragma("unroll") for (int k = 0; k < 2; ++k) dst[n][k] = *(const LAS bf16x8*)(lds + PG8_SB(b, h) + boff + n * 2048 + k * 1024); } while (0)
; #define PG8_MMA(ai, bj, At, Bt) do { __builtin_amdgcn_s_setprio(1); _Pragma("unroll") for (int m = 0; m < 4; ++m) _Pragma("unroll") for (int n = 0; n < 2; ++n) _Pragma("unroll") for (int k = 0; k < 2; ++k) \
;         acc[ai][bj][m][n] = __builtin_amdgcn_mfma_f32_16x16x32_bf16(Bt[n][k], At[m][k], acc[ai][bj][m][n], 0, 0, 0); __builtin_amdgcn_s_setprio(0); } while (0)
; #define PG8_WAIT_V(n) asm volatile("s_waitcnt vmcnt(" #n ")" ::: "memory")
; #define PG8_WAIT_L(n) asm volatile("s_waitcnt lgkmcnt(" #n ")" ::: "memory")
; #define PG8_BAR __builtin_amdgcn_s_barrier()
; #define PG8_SCHED __builtin_amdgcn_sched_barrier(0)
; template <class Epi>
; __device__ __forceinline__ void gemm_phase(LAS unsigned char* lds, const Gemm g, const StaticOrder& S, const Epi& E) {
;     ...
;             const bool last = (t == nt - 2);
;             if constexpr (Epi::HAS_MID) { if (t == nt1) E.mid(acc, cur, wr, wc, fr, fq); }
;             const char* a1 = cA + ((Epi::HAS_MID && t >= nt1) ? dA2 : 0) + (size_t)(t + 1) * kstep;
;             const char* a2 = last ? nA : cA + ((Epi::HAS_MID && t + 2 >= nt1) ? dA2 : 0) + (size_t)(t + 2) * kstep; const char* b2 = last ? nB : cB + ((Epi::HAS_MID && t + 2 >= nt1) ? dB2 : 0) + (size_t)(t + 2) * kstep;
;             const char* a3 = a2 + kstep; const char* b3 = b2 + kstep;
;             PG8_LDB(B0, 0, 0); PG8_LDB(B1, 0, 1); PG8_SCHED; PG8_LDA(At, 0, 0); PG8_STAGE(PG8_SA(1, 1), a1 + hsA, voffA);
;             PG8_WAIT_V(8); PG8_WAIT_L(0); PG8_BAR; PG8_MMA(0, 0, At, B0); PG8_MMA(0, 1, At, B1); PG8_BAR; PG8_SCHED;
.LBB0_296:
	ds_read_b128 v[144:147], v157
	ds_read_b128 v[148:151], v157 offset:1024
	ds_read_b128 v[164:167], v157 offset:2048
	ds_read_b128 v[168:171], v157 offset:3072
	ds_read_b128 v[180:183], v158
	ds_read_b128 v[184:187], v158 offset:1024
	ds_read_b128 v[188:191], v158 offset:2048
	ds_read_b128 v[192:195], v158 offset:3072
	s_add_u32 s60, s12, 0x100
	s_addc_u32 s61, s13, 0
	s_cmp_eq_u32 s34, 40
	s_cselect_b32 s65, s1, s61
	s_cselect_b32 s64, s0, s60
	s_cselect_b32 s63, s59, s7
	s_cselect_b32 s62, s58, s6
	s_add_i32 m0, s5, 0xc000
	ds_read_b128 v[196:199], v159
	ds_read_b128 v[200:203], v159 offset:1024
	ds_read_b128 v[204:207], v159 offset:2048
	ds_read_b128 v[208:211], v159 offset:3072
	ds_read_b128 v[212:215], v159 offset:4096
	ds_read_b128 v[216:219], v159 offset:5120
	ds_read_b128 v[220:223], v159 offset:6144
	ds_read_b128 v[224:227], v159 offset:7168
	global_load_lds_dwordx4 v136, s[12:13]
	s_add_i32 m0, s5, 0xe000
	s_nop 0
	global_load_lds_dwordx4 v138, s[12:13]
	s_waitcnt vmcnt(8)
	s_waitcnt lgkmcnt(0)
	s_setprio 1
	s_barrier

; #define PG8_STAGE(bufoff, gbase, voff) do { _Pragma("unroll") for (int _i = 0; _i < 2; ++_i) \
;         __builtin_amdgcn_global_load_lds((const unsigned*)((const char*)(gbase) + (voff)[_i]), (LAS unsigned*)(lds + (bufoff) + ldsw + _i * 8192), 16, 0, 0); } while (0)
; #define PG8_LDA(dst, b, h) do { _Pragma("unroll") for (int m = 0; m < 4; ++m) _Pragma("unroll") for (int k = 0; k < 2; ++k) dst[m][k] = *(const LAS bf16x8*)(lds + PG8_SA(b, h) + aoff + m * 2048 + k * 1024); } while (0)
; #define PG8_MMA(ai, bj, At, Bt) do { __builtin_amdgcn_s_setprio(1); _Pragma("unroll") for (int m = 0; m < 4; ++m) _Pragma("unroll") for (int n = 0; n < 2; ++n) _Pragma("unroll") for (int k = 0; k < 2; ++k) \
;         acc[ai][bj][m][n] = __builtin_amdgcn_mfma_f32_16x16x32_bf16(Bt[n][k], At[m][k], acc[ai][bj][m][n], 0, 0, 0); __builtin_amdgcn_s_setprio(0); } while (0)
; #define PG8_WAIT_V(n) asm volatile("s_waitcnt vmcnt(" #n ")" ::: "memory")
; #define PG8_WAIT_L(n) asm volatile("s_waitcnt lgkmcnt(" #n ")" ::: "memory")
; #define PG8_BAR __builtin_amdgcn_s_barrier()
; #define PG8_SCHED __builtin_amdgcn_sched_barrier(0)
; template <class Epi>
; __device__ __forceinline__ void gemm_phase(LAS unsigned char* lds, const Gemm g, const StaticOrder& S, const Epi& E) {
;     ...
;             PG8_WAIT_V(8); PG8_WAIT_L(0); PG8_BAR; PG8_MMA(0, 0, At, B0); PG8_MMA(0, 1, At, B1); PG8_BAR; PG8_SCHED;
;             PG8_LDA(At, 0, 1); PG8_STAGE(PG8_SB(0, 0), b2, voffB); PG8_STAGE(PG8_SB(0, 1), b2 + hsB, voffB); PG8_STAGE(PG8_SA(0, 0), a2, voffA);
;             PG8_WAIT_V(8); PG8_WAIT_L(0); PG8_BAR; PG8_MMA(1, 0, At, B0); PG8_MMA(1, 1, At, B1); PG8_BAR; PG8_SCHED;
	v_mfma_f32_16x16x32_bf16 v[124:127], v[144:147], v[196:199], v[124:127]
	v_mfma_f32_16x16x32_bf16 v[120:123], v[164:167], v[196:199], v[120:123]
	v_mfma_f32_16x16x32_bf16 v[108:111], v[144:147], v[204:207], v[108:111]
	v_mfma_f32_16x16x32_bf16 v[104:107], v[164:167], v[204:207], v[104:107]
	v_mfma_f32_16x16x32_bf16 v[92:95], v[144:147], v[212:215], v[92:95]
	v_mfma_f32_16x16x32_bf16 v[88:91], v[164:167], v[212:215], v[88:91]
	v_mfma_f32_16x16x32_bf16 v[76:79], v[144:147], v[220:223], v[76:79]
	v_mfma_f32_16x16x32_bf16 v[72:75], v[164:167], v[220:223], v[72:75]
	v_mfma_f32_16x16x32_bf16 v[124:127], v[148:151], v[200:203], v[124:127]
	v_mfma_f32_16x16x32_bf16 v[120:123], v[168:171], v[200:203], v[120:123]
	v_mfma_f32_16x16x32_bf16 v[108:111], v[148:151], v[208:211], v[108:111]
	v_mfma_f32_16x16x32_bf16 v[104:107], v[168:171], v[208:211], v[104:107]
	v_mfma_f32_16x16x32_bf16 v[92:95], v[148:151], v[216:219], v[92:95]
	v_mfma_f32_16x16x32_bf16 v[88:91], v[168:171], v[216:219], v[88:91]
	v_mfma_f32_16x16x32_bf16 v[76:79], v[148:151], v[224:227], v[76:79]
	v_mfma_f32_16x16x32_bf16 v[72:75], v[168:171], v[224:227], v[72:75]
	s_setprio 0
	s_setprio 1
	v_mfma_f32_16x16x32_bf16 v[116:119], v[180:183], v[196:199], v[116:119]
	v_mfma_f32_16x16x32_bf16 v[112:115], v[188:191], v[196:199], v[112:115]
	v_mfma_f32_16x16x32_bf16 v[100:103], v[180:183], v[204:207], v[100:103]
	v_mfma_f32_16x16x32_bf16 v[96:99], v[188:191], v[204:207], v[96:99]
	v_mfma_f32_16x16x32_bf16 v[84:87], v[180:183], v[212:215], v[84:87]
	v_mfma_f32_16x16x32_bf16 v[80:83], v[188:191], v[212:215], v[80:83]
	v_mfma_f32_16x16x32_bf16 v[68:71], v[180:183], v[220:223], v[68:71]
	v_mfma_f32_16x16x32_bf16 v[64:67], v[188:191], v[220:223], v[64:67]
	v_mfma_f32_16x16x32_bf16 v[116:119], v[184:187], v[200:203], v[116:119]
	v_mfma_f32_16x16x32_bf16 v[112:115], v[192:195], v[200:203], v[112:115]
	v_mfma_f32_16x16x32_bf16 v[100:103], v[184:187], v[208:211], v[100:103]
	v_mfma_f32_16x16x32_bf16 v[96:99], v[192:195], v[208:211], v[96:99]
	v_mfma_f32_16x16x32_bf16 v[84:87], v[184:187], v[216:219], v[84:87]
	v_mfma_f32_16x16x32_bf16 v[80:83], v[192:195], v[216:219], v[80:83]
	v_mfma_f32_16x16x32_bf16 v[68:71], v[184:187], v[224:227], v[68:71]
	v_mfma_f32_16x16x32_bf16 v[64:67], v[192:195], v[224:227], v[64:67]
	s_setprio 0
	s_barrier
	s_add_i32 s12, s27, s4
	s_mov_b32 m0, s12
	ds_read_b128 v[196:199], v159 offset:16384
	ds_read_b128 v[200:203], v159 offset:17408
	ds_read_b128 v[204:207], v159 offset:18432
	ds_read_b128 v[208:211], v159 offset:19456
	ds_read_b128 v[212:215], v159 offset:20480
	ds_read_b128 v[216:219], v159 offset:21504
	ds_read_b128 v[220:223], v159 offset:22528
	ds_read_b128 v[224:227], v159 offset:23552
	global_load_lds_dwordx4 v130, s[62:63]
	s_add_i32 m0, s12, 0x2000
	s_add_u32 s12, s62, 0xb0000
	s_addc_u32 s13, s63, 0
	s_add_i32 s35, s28, s4
	global_load_lds_dwordx4 v134, s[62:63]
	s_mov_b32 m0, s35
	s_nop 0
	global_load_lds_dwordx4 v130, s[12:13]
	s_add_i32 m0, s35, 0x2000
	s_nop 0
	global_load_lds_dwordx4 v134, s[12:13]
	s_mov_b32 m0, s5
	s_nop 0
	global_load_lds_dwordx4 v128, s[64:65]
	s_mov_b32 m0, s16
	s_nop 0
	global_load_lds_dwordx4 v132, s[64:65]
	s_waitcnt vmcnt(8)
	s_waitcnt lgkmcnt(0)
	s_setprio 1
	s_barrier

; #define PG8_STAGE(bufoff, gbase, voff) do { _Pragma("unroll") for (int _i = 0; _i < 2; ++_i) \
;         __builtin_amdgcn_global_load_lds((const unsigned*)((const char*)(gbase) + (voff)[_i]), (LAS unsigned*)(lds + (bufoff) + ldsw + _i * 8192), 16, 0, 0); } while (0)
; #define PG8_LDA(dst, b, h) do { _Pragma("unroll") for (int m = 0; m < 4; ++m) _Pragma("unroll") for (int k = 0; k < 2; ++k) dst[m][k] = *(const LAS bf16x8*)(lds + PG8_SA(b, h) + aoff + m * 2048 + k * 1024); } while (0)
; #define PG8_LDB(dst, b, h) do { _Pragma("unroll") for (int n = 0; n < 2; ++n) _Pragma("unroll") for (int k = 0; k < 2; ++k) dst[n][k] = *(const LAS bf16x8*)(lds + PG8_SB(b, h) + boff + n * 2048 + k * 1024); } while (0)
; #define PG8_MMA(ai, bj, At, Bt) do { __builtin_amdgcn_s_setprio(1); _Pragma("unroll") for (int m = 0; m < 4; ++m) _Pragma("unroll") for (int n = 0; n < 2; ++n) _Pragma("unroll") for (int k = 0; k < 2; ++k) \
;         acc[ai][bj][m][n] = __builtin_amdgcn_mfma_f32_16x16x32_bf16(Bt[n][k], At[m][k], acc[ai][bj][m][n], 0, 0, 0); __builtin_amdgcn_s_setprio(0); } while (0)
; #define PG8_WAIT_V(n) asm volatile("s_waitcnt vmcnt(" #n ")" ::: "memory")
; #define PG8_WAIT_L(n) asm volatile("s_waitcnt lgkmcnt(" #n ")" ::: "memory")
; #define PG8_BAR __builtin_amdgcn_s_barrier()
; #define PG8_SCHED __builtin_amdgcn_sched_barrier(0)
; template <class Epi>
; __device__ __forceinline__ void gemm_phase(LAS unsigned char* lds, const Gemm g, const StaticOrder& S, const Epi& E) {
;     ...
;             PG8_WAIT_V(8); PG8_WAIT_L(0); PG8_BAR; PG8_MMA(1, 0, At, B0); PG8_MMA(1, 1, At, B1); PG8_BAR; PG8_SCHED;
;             PG8_LDB(B0, 1, 0); PG8_LDB(B1, 1, 1); PG8_SCHED; PG8_LDA(At, 1, 0); PG8_STAGE(PG8_SA(0, 1), a2 + hsA, voffA);
;             PG8_WAIT_V(8); PG8_WAIT_L(0); PG8_BAR; PG8_MMA(0, 0, At, B0); PG8_MMA(0, 1, At, B1); PG8_BAR; PG8_SCHED;
	v_mfma_f32_16x16x32_bf16 v[60:63], v[144:147], v[196:199], v[60:63]
	v_mfma_f32_16x16x32_bf16 v[56:59], v[164:167], v[196:199], v[56:59]
	v_mfma_f32_16x16x32_bf16 v[44:47], v[144:147], v[204:207], v[44:47]
	v_mfma_f32_16x16x32_bf16 v[40:43], v[164:167], v[204:207], v[40:43]
	v_mfma_f32_16x16x32_bf16 v[28:31], v[144:147], v[212:215], v[28:31]
	v_mfma_f32_16x16x32_bf16 v[24:27], v[164:167], v[212:215], v[24:27]
	v_mfma_f32_16x16x32_bf16 v[12:15], v[144:147], v[220:223], v[12:15]
	v_mfma_f32_16x16x32_bf16 v[8:11], v[164:167], v[220:223], v[8:11]
	v_mfma_f32_16x16x32_bf16 v[60:63], v[148:151], v[200:203], v[60:63]
	v_mfma_f32_16x16x32_bf16 v[56:59], v[168:171], v[200:203], v[56:59]
	v_mfma_f32_16x16x32_bf16 v[44:47], v[148:151], v[208:211], v[44:47]
	v_mfma_f32_16x16x32_bf16 v[40:43], v[168:171], v[208:211], v[40:43]
	v_mfma_f32_16x16x32_bf16 v[28:31], v[148:151], v[216:219], v[28:31]
	v_mfma_f32_16x16x32_bf16 v[24:27], v[168:171], v[216:219], v[24:27]
	v_mfma_f32_16x16x32_bf16 v[12:15], v[148:151], v[224:227], v[12:15]
	v_mfma_f32_16x16x32_bf16 v[8:11], v[168:171], v[224:227], v[8:11]
	s_setprio 0
	s_setprio 1
	v_mfma_f32_16x16x32_bf16 v[52:55], v[180:183], v[196:199], v[52:55]
	v_mfma_f32_16x16x32_bf16 v[48:51], v[188:191], v[196:199], v[48:51]
	v_mfma_f32_16x16x32_bf16 v[36:39], v[180:183], v[204:207], v[36:39]
	v_mfma_f32_16x16x32_bf16 v[32:35], v[188:191], v[204:207], v[32:35]
	v_mfma_f32_16x16x32_bf16 v[20:23], v[180:183], v[212:215], v[20:23]
	v_mfma_f32_16x16x32_bf16 v[16:19], v[188:191], v[212:215], v[16:19]
	v_mfma_f32_16x16x32_bf16 v[4:7], v[180:183], v[220:223], v[4:7]
	v_mfma_f32_16x16x32_bf16 v[0:3], v[188:191], v[220:223], v[0:3]
	v_mfma_f32_16x16x32_bf16 v[52:55], v[184:187], v[200:203], v[52:55]
	v_mfma_f32_16x16x32_bf16 v[48:51], v[192:195], v[200:203], v[48:51]
	v_mfma_f32_16x16x32_bf16 v[36:39], v[184:187], v[208:211], v[36:39]
	v_mfma_f32_16x16x32_bf16 v[32:35], v[192:195], v[208:211], v[32:35]
	v_mfma_f32_16x16x32_bf16 v[20:23], v[184:187], v[216:219], v[20:23]
	v_mfma_f32_16x16x32_bf16 v[16:19], v[192:195], v[216:219], v[16:19]
	v_mfma_f32_16x16x32_bf16 v[4:7], v[184:187], v[224:227], v[4:7]
	v_mfma_f32_16x16x32_bf16 v[0:3], v[192:195], v[224:227], v[0:3]
	s_setprio 0
	s_barrier
	s_add_i32 s35, 0, 0x18000
	v_add_u32_e32 v163, s35, v155
	s_add_i32 s36, 0, 0x1c000
	ds_read_b128 v[144:147], v163
	ds_read_b128 v[148:151], v163 offset:1024
	ds_read_b128 v[164:167], v163 offset:2048
	ds_read_b128 v[168:171], v163 offset:3072
	v_add_u32_e32 v163, s36, v155
	ds_read_b128 v[180:183], v163
	ds_read_b128 v[184:187], v163 offset:1024
	ds_read_b128 v[188:191], v163 offset:2048
	ds_read_b128 v[192:195], v163 offset:3072
	s_add_u32 s12, s64, 0xb0000
	s_addc_u32 s13, s65, 0
	s_mov_b32 m0, s17
	ds_read_b128 v[196:199], v159 offset:32768
	ds_read_b128 v[200:203], v159 offset:33792
	ds_read_b128 v[204:207], v159 offset:34816
	ds_read_b128 v[208:211], v159 offset:35840
	ds_read_b128 v[212:215], v159 offset:36864
	ds_read_b128 v[216:219], v159 offset:37888
	ds_read_b128 v[220:223], v159 offset:38912
	ds_read_b128 v[224:227], v159 offset:39936
	global_load_lds_dwordx4 v128, s[12:13]
	s_mov_b32 m0, s18
	s_nop 0
	global_load_lds_dwordx4 v132, s[12:13]
	s_waitcnt vmcnt(8)
	s_waitcnt lgkmcnt(0)
	s_setprio 1
	s_barrier

; #define PG8_STAGE(bufoff, gbase, voff) do { _Pragma("unroll") for (int _i = 0; _i < 2; ++_i) \
;         __builtin_amdgcn_global_load_lds((const unsigned*)((const char*)(gbase) + (voff)[_i]), (LAS unsigned*)(lds + (bufoff) + ldsw + _i * 8192), 16, 0, 0); } while (0)
; #define PG8_LDA(dst, b, h) do { _Pragma("unroll") for (int m = 0; m < 4; ++m) _Pragma("unroll") for (int k = 0; k < 2; ++k) dst[m][k] = *(const LAS bf16x8*)(lds + PG8_SA(b, h) + aoff + m * 2048 + k * 1024); } while (0)
; #define PG8_MMA(ai, bj, At, Bt) do { __builtin_amdgcn_s_setprio(1); _Pragma("unroll") for (int m = 0; m < 4; ++m) _Pragma("unroll") for (int n = 0; n < 2; ++n) _Pragma("unroll") for (int k = 0; k < 2; ++k) \
;         acc[ai][bj][m][n] = __builtin_amdgcn_mfma_f32_16x16x32_bf16(Bt[n][k], At[m][k], acc[ai][bj][m][n], 0, 0, 0); __builtin_amdgcn_s_setprio(0); } while (0)
; #define PG8_WAIT_V(n) asm volatile("s_waitcnt vmcnt(" #n ")" ::: "memory")
; #define PG8_WAIT_L(n) asm volatile("s_waitcnt lgkmcnt(" #n ")" ::: "memory")
; #define PG8_BAR __builtin_amdgcn_s_barrier()
; #define PG8_SCHED __builtin_amdgcn_sched_barrier(0)
; template <class Epi>
; __device__ __forceinline__ void gemm_phase(LAS unsigned char* lds, const Gemm g, const StaticOrder& S, const Epi& E) {
;     ...
;             PG8_WAIT_V(8); PG8_WAIT_L(0); PG8_BAR; PG8_MMA(0, 0, At, B0); PG8_MMA(0, 1, At, B1); PG8_BAR; PG8_SCHED;
;             PG8_LDA(At, 1, 1); PG8_STAGE(PG8_SB(1, 0), b3, voffB); PG8_STAGE(PG8_SB(1, 1), b3 + hsB, voffB); PG8_STAGE(PG8_SA(1, 0), a3, voffA);
;             PG8_WAIT_V(8); PG8_WAIT_L(0); PG8_BAR; PG8_MMA(1, 0, At, B0); PG8_MMA(1, 1, At, B1); PG8_BAR; PG8_SCHED;
	v_mfma_f32_16x16x32_bf16 v[124:127], v[144:147], v[196:199], v[124:127]
	v_mfma_f32_16x16x32_bf16 v[120:123], v[164:167], v[196:199], v[120:123]
	v_mfma_f32_16x16x32_bf16 v[108:111], v[144:147], v[204:207], v[108:111]
	v_mfma_f32_16x16x32_bf16 v[104:107], v[164:167], v[204:207], v[104:107]
	v_mfma_f32_16x16x32_bf16 v[92:95], v[144:147], v[212:215], v[92:95]
	v_mfma_f32_16x16x32_bf16 v[88:91], v[164:167], v[212:215], v[88:91]
	v_mfma_f32_16x16x32_bf16 v[76:79], v[144:147], v[220:223], v[76:79]
	v_mfma_f32_16x16x32_bf16 v[72:75], v[164:167], v[220:223], v[72:75]
	v_mfma_f32_16x16x32_bf16 v[124:127], v[148:151], v[200:203], v[124:127]
	v_mfma_f32_16x16x32_bf16 v[120:123], v[168:171], v[200:203], v[120:123]
	v_mfma_f32_16x16x32_bf16 v[108:111], v[148:151], v[208:211], v[108:111]
	v_mfma_f32_16x16x32_bf16 v[104:107], v[168:171], v[208:211], v[104:107]
	v_mfma_f32_16x16x32_bf16 v[92:95], v[148:151], v[216:219], v[92:95]
	v_mfma_f32_16x16x32_bf16 v[88:91], v[168:171], v[216:219], v[88:91]
	v_mfma_f32_16x16x32_bf16 v[76:79], v[148:151], v[224:227], v[76:79]
	v_mfma_f32_16x16x32_bf16 v[72:75], v[168:171], v[224:227], v[72:75]
	s_setprio 0
	s_setprio 1
	v_mfma_f32_16x16x32_bf16 v[116:119], v[180:183], v[196:199], v[116:119]
	v_mfma_f32_16x16x32_bf16 v[112:115], v[188:191], v[196:199], v[112:115]
	v_mfma_f32_16x16x32_bf16 v[100:103], v[180:183], v[204:207], v[100:103]
	v_mfma_f32_16x16x32_bf16 v[96:99], v[188:191], v[204:207], v[96:99]
	v_mfma_f32_16x16x32_bf16 v[84:87], v[180:183], v[212:215], v[84:87]
	v_mfma_f32_16x16x32_bf16 v[80:83], v[188:191], v[212:215], v[80:83]
	v_mfma_f32_16x16x32_bf16 v[68:71], v[180:183], v[220:223], v[68:71]
	v_mfma_f32_16x16x32_bf16 v[64:67], v[188:191], v[220:223], v[64:67]
	v_mfma_f32_16x16x32_bf16 v[116:119], v[184:187], v[200:203], v[116:119]
	v_mfma_f32_16x16x32_bf16 v[112:115], v[192:195], v[200:203], v[112:115]
	v_mfma_f32_16x16x32_bf16 v[100:103], v[184:187], v[208:211], v[100:103]
	v_mfma_f32_16x16x32_bf16 v[96:99], v[192:195], v[208:211], v[96:99]
	v_mfma_f32_16x16x32_bf16 v[84:87], v[184:187], v[216:219], v[84:87]
	v_mfma_f32_16x16x32_bf16 v[80:83], v[192:195], v[216:219], v[80:83]
	v_mfma_f32_16x16x32_bf16 v[68:71], v[184:187], v[224:227], v[68:71]
	v_mfma_f32_16x16x32_bf16 v[64:67], v[192:195], v[224:227], v[64:67]
	s_setprio 0
	s_barrier
	s_add_u32 s98, s62, 0x80
	s_addc_u32 s99, s63, 0
	s_add_u32 s100, s64, 0x80
	s_addc_u32 s101, s65, 0
	s_add_i32 s12, s35, s4
	s_mov_b32 m0, s12
	ds_read_b128 v[196:199], v159 offset:49152
	ds_read_b128 v[200:203], v159 offset:50176
	ds_read_b128 v[204:207], v159 offset:51200
	ds_read_b128 v[208:211], v159 offset:52224
	ds_read_b128 v[212:215], v159 offset:53248
	ds_read_b128 v[216:219], v159 offset:54272
	ds_read_b128 v[220:223], v159 offset:55296
	ds_read_b128 v[224:227], v159 offset:56320
	global_load_lds_dwordx4 v130, s[98:99]
	s_add_i32 m0, s12, 0x2000
	s_add_u32 s12, s62, 0xb0080
	s_addc_u32 s13, s63, 0
	s_add_i32 s35, s36, s4
	global_load_lds_dwordx4 v134, s[98:99]
	s_mov_b32 m0, s35
	s_nop 0
	global_load_lds_dwordx4 v130, s[12:13]
	s_add_i32 m0, s35, 0x2000
	s_nop 0
	global_load_lds_dwordx4 v134, s[12:13]
	s_mov_b32 m0, s22
	s_nop 0
	global_load_lds_dwordx4 v128, s[100:101]
	s_mov_b32 m0, s23
	s_nop 0
	global_load_lds_dwordx4 v132, s[100:101]
	s_waitcnt vmcnt(8)
	s_waitcnt lgkmcnt(0)
	s_setprio 1
	s_barrier

; #define PG8_MMA(ai, bj, At, Bt) do { __builtin_amdgcn_s_setprio(1); _Pragma("unroll") for (int m = 0; m < 4; ++m) _Pragma("unroll") for (int n = 0; n < 2; ++n) _Pragma("unroll") for (int k = 0; k < 2; ++k) \
;         acc[ai][bj][m][n] = __builtin_amdgcn_mfma_f32_16x16x32_bf16(Bt[n][k], At[m][k], acc[ai][bj][m][n], 0, 0, 0); __builtin_amdgcn_s_setprio(0); } while (0)
; #define PG8_WAIT_V(n) asm volatile("s_waitcnt vmcnt(" #n ")" ::: "memory")
; #define PG8_WAIT_L(n) asm volatile("s_waitcnt lgkmcnt(" #n ")" ::: "memory")
; #define PG8_BAR __builtin_amdgcn_s_barrier()
; #define PG8_SCHED __builtin_amdgcn_sched_barrier(0)
; template <class Epi>
; __device__ __forceinline__ void gemm_phase(LAS unsigned char* lds, const Gemm g, const StaticOrder& S, const Epi& E) {
;     ...
;             PG8_WAIT_V(8); PG8_WAIT_L(0); PG8_BAR; PG8_MMA(1, 0, At, B0); PG8_MMA(1, 1, At, B1); PG8_BAR; PG8_SCHED;
;         }
;         if (wr == 0) PG8_BAR;
	v_mfma_f32_16x16x32_bf16 v[60:63], v[144:147], v[196:199], v[60:63]
	v_mfma_f32_16x16x32_bf16 v[56:59], v[164:167], v[196:199], v[56:59]
	v_mfma_f32_16x16x32_bf16 v[44:47], v[144:147], v[204:207], v[44:47]
	v_mfma_f32_16x16x32_bf16 v[40:43], v[164:167], v[204:207], v[40:43]
	v_mfma_f32_16x16x32_bf16 v[28:31], v[144:147], v[212:215], v[28:31]
	v_mfma_f32_16x16x32_bf16 v[24:27], v[164:167], v[212:215], v[24:27]
	v_mfma_f32_16x16x32_bf16 v[12:15], v[144:147], v[220:223], v[12:15]
	v_mfma_f32_16x16x32_bf16 v[8:11], v[164:167], v[220:223], v[8:11]
	v_mfma_f32_16x16x32_bf16 v[60:63], v[148:151], v[200:203], v[60:63]
	v_mfma_f32_16x16x32_bf16 v[56:59], v[168:171], v[200:203], v[56:59]
	v_mfma_f32_16x16x32_bf16 v[44:47], v[148:151], v[208:211], v[44:47]
	v_mfma_f32_16x16x32_bf16 v[40:43], v[168:171], v[208:211], v[40:43]
	v_mfma_f32_16x16x32_bf16 v[28:31], v[148:151], v[216:219], v[28:31]
	v_mfma_f32_16x16x32_bf16 v[24:27], v[168:171], v[216:219], v[24:27]
	v_mfma_f32_16x16x32_bf16 v[12:15], v[148:151], v[224:227], v[12:15]
	v_mfma_f32_16x16x32_bf16 v[8:11], v[168:171], v[224:227], v[8:11]
	s_setprio 0
	s_setprio 1
	v_mfma_f32_16x16x32_bf16 v[52:55], v[180:183], v[196:199], v[52:55]
	v_mfma_f32_16x16x32_bf16 v[48:51], v[188:191], v[196:199], v[48:51]
	v_mfma_f32_16x16x32_bf16 v[36:39], v[180:183], v[204:207], v[36:39]
	v_mfma_f32_16x16x32_bf16 v[32:35], v[188:191], v[204:207], v[32:35]
	v_mfma_f32_16x16x32_bf16 v[20:23], v[180:183], v[212:215], v[20:23]
	v_mfma_f32_16x16x32_bf16 v[16:19], v[188:191], v[212:215], v[16:19]
	v_mfma_f32_16x16x32_bf16 v[4:7], v[180:183], v[220:223], v[4:7]
	v_mfma_f32_16x16x32_bf16 v[0:3], v[188:191], v[220:223], v[0:3]
	v_mfma_f32_16x16x32_bf16 v[52:55], v[184:187], v[200:203], v[52:55]
	v_mfma_f32_16x16x32_bf16 v[48:51], v[192:195], v[200:203], v[48:51]
	v_mfma_f32_16x16x32_bf16 v[36:39], v[184:187], v[208:211], v[36:39]
	v_mfma_f32_16x16x32_bf16 v[32:35], v[192:195], v[208:211], v[32:35]
	v_mfma_f32_16x16x32_bf16 v[20:23], v[184:187], v[216:219], v[20:23]
	v_mfma_f32_16x16x32_bf16 v[16:19], v[192:195], v[216:219], v[16:19]
	v_mfma_f32_16x16x32_bf16 v[4:7], v[184:187], v[224:227], v[4:7]
	v_mfma_f32_16x16x32_bf16 v[0:3], v[192:195], v[224:227], v[0:3]
	s_setprio 0
	s_barrier
	s_add_i32 s34, s34, 2
	s_add_u32 s6, s6, 0x100
	s_addc_u32 s7, s7, 0
	s_cmp_gt_u32 s34, 41
	s_mov_b64 s[12:13], s[60:61]
	s_cbranch_scc0 .LBB0_296
	s_and_b64 vcc, exec, s[42:43]
	s_cbranch_vccz .LBB0_299
	s_barrier

; #define PG8_STAGE(bufoff, gbase, voff) do { _Pragma("unroll") for (int _i = 0; _i < 2; ++_i) \
;         __builtin_amdgcn_global_load_lds((const unsigned*)((const char*)(gbase) + (voff)[_i]), (LAS unsigned*)(lds + (bufoff) + ldsw + _i * 8192), 16, 0, 0); } while (0)
; #define PG8_LDA(dst, b, h) do { _Pragma("unroll") for (int m = 0; m < 4; ++m) _Pragma("unroll") for (int k = 0; k < 2; ++k) dst[m][k] = *(const LAS bf16x8*)(lds + PG8_SA(b, h) + aoff + m * 2048 + k * 1024); } while (0)
; #define PG8_LDB(dst, b, h) do { _Pragma("unroll") for (int n = 0; n < 2; ++n) _Pragma("unroll") for (int k = 0; k < 2; ++k) dst[n][k] = *(const LAS bf16x8*)(lds + PG8_SB(b, h) + boff + n * 2048 + k * 1024); } while (0)
; #define PG8_MMA(ai, bj, At, Bt) do { __builtin_amdgcn_s_setprio(1); _Pragma("unroll") for (int m = 0; m < 4; ++m) _Pragma("unroll") for (int n = 0; n < 2; ++n) _Pragma("unroll") for (int k = 0; k < 2; ++k) \
;         acc[ai][bj][m][n] = __builtin_amdgcn_mfma_f32_16x16x32_bf16(Bt[n][k], At[m][k], acc[ai][bj][m][n], 0, 0, 0); __builtin_amdgcn_s_setprio(0); } while (0)
; #define PG8_WAIT_V(n) asm volatile("s_waitcnt vmcnt(" #n ")" ::: "memory")
; #define PG8_WAIT_L(n) asm volatile("s_waitcnt lgkmcnt(" #n ")" ::: "memory")
; #define PG8_BAR __builtin_amdgcn_s_barrier()
; #define PG8_SCHED __builtin_amdgcn_sched_barrier(0)
; template <class Epi>
; __device__ __forceinline__ void gemm_phase(LAS unsigned char* lds, const Gemm g, const StaticOrder& S, const Epi& E) {
;     ...
;             const bool last = (t == nt - 2);
;             if constexpr (Epi::HAS_MID) { if (t == nt1) E.mid(acc, cur, wr, wc, fr, fq); }
;             const char* a1 = cA + ((Epi::HAS_MID && t >= nt1) ? dA2 : 0) + (size_t)(t + 1) * kstep;
;             const char* a2 = last ? nA : cA + ((Epi::HAS_MID && t + 2 >= nt1) ? dA2 : 0) + (size_t)(t + 2) * kstep; const char* b2 = last ? nB : cB + ((Epi::HAS_MID && t + 2 >= nt1) ? dB2 : 0) + (size_t)(t + 2) * kstep;
;             const char* a3 = a2 + kstep; const char* b3 = b2 + kstep;
;             PG8_LDB(B0, 0, 0); PG8_LDB(B1, 0, 1); PG8_SCHED; PG8_LDA(At, 0, 0); PG8_STAGE(PG8_SA(1, 1), a1 + hsA, voffA);
;             PG8_WAIT_V(8); PG8_WAIT_L(0); PG8_BAR; PG8_MMA(0, 0, At, B0); PG8_MMA(0, 1, At, B1); PG8_BAR; PG8_SCHED;
.LBB0_414:
	ds_read_b128 v[152:155], v167
	ds_read_b128 v[156:159], v167 offset:1024
	ds_read_b128 v[162:165], v167 offset:2048
	ds_read_b128 v[180:183], v167 offset:3072
	ds_read_b128 v[184:187], v168
	ds_read_b128 v[188:191], v168 offset:1024
	ds_read_b128 v[192:195], v168 offset:2048
	ds_read_b128 v[196:199], v168 offset:3072
	s_add_u32 s12, s10, 0xfffc0080
	s_addc_u32 s13, s11, -1
	s_cmp_eq_u32 s17, 12
	s_cselect_b32 s87, s0, s13
	s_cselect_b32 s86, s2, s12
	s_cselect_b32 s13, s3, s15
	s_cselect_b32 s12, s6, s7
	s_add_i32 m0, s5, 0xc000
	ds_read_b128 v[200:203], v169
	ds_read_b128 v[204:207], v169 offset:1024
	ds_read_b128 v[208:211], v169 offset:2048
	ds_read_b128 v[212:215], v169 offset:3072
	ds_read_b128 v[216:219], v169 offset:4096
	ds_read_b128 v[220:223], v169 offset:5120
	ds_read_b128 v[224:227], v169 offset:6144
	ds_read_b128 v[228:231], v169 offset:7168
	global_load_lds_dwordx4 v144, s[10:11]
	s_add_i32 m0, s5, 0xe000
	s_nop 0
	global_load_lds_dwordx4 v146, s[10:11]
	s_waitcnt vmcnt(8)
	s_waitcnt lgkmcnt(0)
	s_setprio 1
	s_barrier

; #define PG8_STAGE(bufoff, gbase, voff) do { _Pragma("unroll") for (int _i = 0; _i < 2; ++_i) \
;         __builtin_amdgcn_global_load_lds((const unsigned*)((const char*)(gbase) + (voff)[_i]), (LAS unsigned*)(lds + (bufoff) + ldsw + _i * 8192), 16, 0, 0); } while (0)
; #define PG8_LDA(dst, b, h) do { _Pragma("unroll") for (int m = 0; m < 4; ++m) _Pragma("unroll") for (int k = 0; k < 2; ++k) dst[m][k] = *(const LAS bf16x8*)(lds + PG8_SA(b, h) + aoff + m * 2048 + k * 1024); } while (0)
; #define PG8_MMA(ai, bj, At, Bt) do { __builtin_amdgcn_s_setprio(1); _Pragma("unroll") for (int m = 0; m < 4; ++m) _Pragma("unroll") for (int n = 0; n < 2; ++n) _Pragma("unroll") for (int k = 0; k < 2; ++k) \
;         acc[ai][bj][m][n] = __builtin_amdgcn_mfma_f32_16x16x32_bf16(Bt[n][k], At[m][k], acc[ai][bj][m][n], 0, 0, 0); __builtin_amdgcn_s_setprio(0); } while (0)
; #define PG8_WAIT_V(n) asm volatile("s_waitcnt vmcnt(" #n ")" ::: "memory")
; #define PG8_WAIT_L(n) asm volatile("s_waitcnt lgkmcnt(" #n ")" ::: "memory")
; #define PG8_BAR __builtin_amdgcn_s_barrier()
; #define PG8_SCHED __builtin_amdgcn_sched_barrier(0)
; template <class Epi>
; __device__ __forceinline__ void gemm_phase(LAS unsigned char* lds, const Gemm g, const StaticOrder& S, const Epi& E) {
;     ...
;             PG8_WAIT_V(8); PG8_WAIT_L(0); PG8_BAR; PG8_MMA(0, 0, At, B0); PG8_MMA(0, 1, At, B1); PG8_BAR; PG8_SCHED;
;             PG8_LDA(At, 0, 1); PG8_STAGE(PG8_SB(0, 0), b2, voffB); PG8_STAGE(PG8_SB(0, 1), b2 + hsB, voffB); PG8_STAGE(PG8_SA(0, 0), a2, voffA);
;             PG8_WAIT_V(8); PG8_WAIT_L(0); PG8_BAR; PG8_MMA(1, 0, At, B0); PG8_MMA(1, 1, At, B1); PG8_BAR; PG8_SCHED;
	v_mfma_f32_16x16x32_bf16 v[124:127], v[152:155], v[200:203], v[124:127]
	v_mfma_f32_16x16x32_bf16 v[120:123], v[162:165], v[200:203], v[120:123]
	v_mfma_f32_16x16x32_bf16 v[108:111], v[152:155], v[208:211], v[108:111]
	v_mfma_f32_16x16x32_bf16 v[104:107], v[162:165], v[208:211], v[104:107]
	v_mfma_f32_16x16x32_bf16 v[92:95], v[152:155], v[216:219], v[92:95]
	v_mfma_f32_16x16x32_bf16 v[88:91], v[162:165], v[216:219], v[88:91]
	v_mfma_f32_16x16x32_bf16 v[76:79], v[152:155], v[224:227], v[76:79]
	v_mfma_f32_16x16x32_bf16 v[72:75], v[162:165], v[224:227], v[72:75]
	v_mfma_f32_16x16x32_bf16 v[124:127], v[156:159], v[204:207], v[124:127]
	v_mfma_f32_16x16x32_bf16 v[120:123], v[180:183], v[204:207], v[120:123]
	v_mfma_f32_16x16x32_bf16 v[108:111], v[156:159], v[212:215], v[108:111]
	v_mfma_f32_16x16x32_bf16 v[104:107], v[180:183], v[212:215], v[104:107]
	v_mfma_f32_16x16x32_bf16 v[92:95], v[156:159], v[220:223], v[92:95]
	v_mfma_f32_16x16x32_bf16 v[88:91], v[180:183], v[220:223], v[88:91]
	v_mfma_f32_16x16x32_bf16 v[76:79], v[156:159], v[228:231], v[76:79]
	v_mfma_f32_16x16x32_bf16 v[72:75], v[180:183], v[228:231], v[72:75]
	s_setprio 0
	s_setprio 1
	v_mfma_f32_16x16x32_bf16 v[116:119], v[184:187], v[200:203], v[116:119]
	v_mfma_f32_16x16x32_bf16 v[112:115], v[192:195], v[200:203], v[112:115]
	v_mfma_f32_16x16x32_bf16 v[100:103], v[184:187], v[208:211], v[100:103]
	v_mfma_f32_16x16x32_bf16 v[96:99], v[192:195], v[208:211], v[96:99]
	v_mfma_f32_16x16x32_bf16 v[84:87], v[184:187], v[216:219], v[84:87]
	v_mfma_f32_16x16x32_bf16 v[80:83], v[192:195], v[216:219], v[80:83]
	v_mfma_f32_16x16x32_bf16 v[68:71], v[184:187], v[224:227], v[68:71]
	v_mfma_f32_16x16x32_bf16 v[64:67], v[192:195], v[224:227], v[64:67]
	v_mfma_f32_16x16x32_bf16 v[116:119], v[188:191], v[204:207], v[116:119]
	v_mfma_f32_16x16x32_bf16 v[112:115], v[196:199], v[204:207], v[112:115]
	v_mfma_f32_16x16x32_bf16 v[100:103], v[188:191], v[212:215], v[100:103]
	v_mfma_f32_16x16x32_bf16 v[96:99], v[196:199], v[212:215], v[96:99]
	v_mfma_f32_16x16x32_bf16 v[84:87], v[188:191], v[220:223], v[84:87]
	v_mfma_f32_16x16x32_bf16 v[80:83], v[196:199], v[220:223], v[80:83]
	v_mfma_f32_16x16x32_bf16 v[68:71], v[188:191], v[228:231], v[68:71]
	v_mfma_f32_16x16x32_bf16 v[64:67], v[196:199], v[228:231], v[64:67]
	s_setprio 0
	s_barrier
	s_add_i32 s19, s65, s4
	s_mov_b32 m0, s19
	ds_read_b128 v[200:203], v169 offset:16384
	ds_read_b128 v[204:207], v169 offset:17408
	ds_read_b128 v[208:211], v169 offset:18432
	ds_read_b128 v[212:215], v169 offset:19456
	ds_read_b128 v[216:219], v169 offset:20480
	ds_read_b128 v[220:223], v169 offset:21504
	ds_read_b128 v[224:227], v169 offset:22528
	ds_read_b128 v[228:231], v169 offset:23552
	global_load_lds_dwordx4 v130, s[12:13]
	s_add_i32 m0, s19, 0x2000
	s_add_u32 s24, s12, 0x40000
	s_addc_u32 s25, s13, 0
	s_add_i32 s19, s76, s4
	global_load_lds_dwordx4 v134, s[12:13]
	s_mov_b32 m0, s19
	s_nop 0
	global_load_lds_dwordx4 v130, s[24:25]
	s_add_i32 m0, s19, 0x2000
	s_nop 0
	global_load_lds_dwordx4 v134, s[24:25]
	s_mov_b32 m0, s5
	s_nop 0
	global_load_lds_dwordx4 v128, s[86:87]
	s_mov_b32 m0, s62
	s_nop 0
	global_load_lds_dwordx4 v132, s[86:87]
	s_waitcnt vmcnt(8)
	s_waitcnt lgkmcnt(0)
	s_setprio 1
	s_barrier

; #define PG8_STAGE(bufoff, gbase, voff) do { _Pragma("unroll") for (int _i = 0; _i < 2; ++_i) \
;         __builtin_amdgcn_global_load_lds((const unsigned*)((const char*)(gbase) + (voff)[_i]), (LAS unsigned*)(lds + (bufoff) + ldsw + _i * 8192), 16, 0, 0); } while (0)
; #define PG8_LDA(dst, b, h) do { _Pragma("unroll") for (int m = 0; m < 4; ++m) _Pragma("unroll") for (int k = 0; k < 2; ++k) dst[m][k] = *(const LAS bf16x8*)(lds + PG8_SA(b, h) + aoff + m * 2048 + k * 1024); } while (0)
; #define PG8_LDB(dst, b, h) do { _Pragma("unroll") for (int n = 0; n < 2; ++n) _Pragma("unroll") for (int k = 0; k < 2; ++k) dst[n][k] = *(const LAS bf16x8*)(lds + PG8_SB(b, h) + boff + n * 2048 + k * 1024); } while (0)
; #define PG8_MMA(ai, bj, At, Bt) do { __builtin_amdgcn_s_setprio(1); _Pragma("unroll") for (int m = 0; m < 4; ++m) _Pragma("unroll") for (int n = 0; n < 2; ++n) _Pragma("unroll") for (int k = 0; k < 2; ++k) \
;         acc[ai][bj][m][n] = __builtin_amdgcn_mfma_f32_16x16x32_bf16(Bt[n][k], At[m][k], acc[ai][bj][m][n], 0, 0, 0); __builtin_amdgcn_s_setprio(0); } while (0)
; #define PG8_WAIT_V(n) asm volatile("s_waitcnt vmcnt(" #n ")" ::: "memory")
; #define PG8_WAIT_L(n) asm volatile("s_waitcnt lgkmcnt(" #n ")" ::: "memory")
; #define PG8_BAR __builtin_amdgcn_s_barrier()
; #define PG8_SCHED __builtin_amdgcn_sched_barrier(0)
; template <class Epi>
; __device__ __forceinline__ void gemm_phase(LAS unsigned char* lds, const Gemm g, const StaticOrder& S, const Epi& E) {
;     ...
;             PG8_WAIT_V(8); PG8_WAIT_L(0); PG8_BAR; PG8_MMA(1, 0, At, B0); PG8_MMA(1, 1, At, B1); PG8_BAR; PG8_SCHED;
;             PG8_LDB(B0, 1, 0); PG8_LDB(B1, 1, 1); PG8_SCHED; PG8_LDA(At, 1, 0); PG8_STAGE(PG8_SA(0, 1), a2 + hsA, voffA);
;             PG8_WAIT_V(8); PG8_WAIT_L(0); PG8_BAR; PG8_MMA(0, 0, At, B0); PG8_MMA(0, 1, At, B1); PG8_BAR; PG8_SCHED;
	v_mfma_f32_16x16x32_bf16 v[60:63], v[152:155], v[200:203], v[60:63]
	v_mfma_f32_16x16x32_bf16 v[56:59], v[162:165], v[200:203], v[56:59]
	v_mfma_f32_16x16x32_bf16 v[44:47], v[152:155], v[208:211], v[44:47]
	v_mfma_f32_16x16x32_bf16 v[40:43], v[162:165], v[208:211], v[40:43]
	v_mfma_f32_16x16x32_bf16 v[28:31], v[152:155], v[216:219], v[28:31]
	v_mfma_f32_16x16x32_bf16 v[24:27], v[162:165], v[216:219], v[24:27]
	v_mfma_f32_16x16x32_bf16 v[12:15], v[152:155], v[224:227], v[12:15]
	v_mfma_f32_16x16x32_bf16 v[8:11], v[162:165], v[224:227], v[8:11]
	v_mfma_f32_16x16x32_bf16 v[60:63], v[156:159], v[204:207], v[60:63]
	v_mfma_f32_16x16x32_bf16 v[56:59], v[180:183], v[204:207], v[56:59]
	v_mfma_f32_16x16x32_bf16 v[44:47], v[156:159], v[212:215], v[44:47]
	v_mfma_f32_16x16x32_bf16 v[40:43], v[180:183], v[212:215], v[40:43]
	v_mfma_f32_16x16x32_bf16 v[28:31], v[156:159], v[220:223], v[28:31]
	v_mfma_f32_16x16x32_bf16 v[24:27], v[180:183], v[220:223], v[24:27]
	v_mfma_f32_16x16x32_bf16 v[12:15], v[156:159], v[228:231], v[12:15]
	v_mfma_f32_16x16x32_bf16 v[8:11], v[180:183], v[228:231], v[8:11]
	s_setprio 0
	s_setprio 1
	v_mfma_f32_16x16x32_bf16 v[52:55], v[184:187], v[200:203], v[52:55]
	v_mfma_f32_16x16x32_bf16 v[48:51], v[192:195], v[200:203], v[48:51]
	v_mfma_f32_16x16x32_bf16 v[36:39], v[184:187], v[208:211], v[36:39]
	v_mfma_f32_16x16x32_bf16 v[32:35], v[192:195], v[208:211], v[32:35]
	v_mfma_f32_16x16x32_bf16 v[20:23], v[184:187], v[216:219], v[20:23]
	v_mfma_f32_16x16x32_bf16 v[16:19], v[192:195], v[216:219], v[16:19]
	v_mfma_f32_16x16x32_bf16 v[4:7], v[184:187], v[224:227], v[4:7]
	v_mfma_f32_16x16x32_bf16 v[0:3], v[192:195], v[224:227], v[0:3]
	v_mfma_f32_16x16x32_bf16 v[52:55], v[188:191], v[204:207], v[52:55]
	v_mfma_f32_16x16x32_bf16 v[48:51], v[196:199], v[204:207], v[48:51]
	v_mfma_f32_16x16x32_bf16 v[36:39], v[188:191], v[212:215], v[36:39]
	v_mfma_f32_16x16x32_bf16 v[32:35], v[196:199], v[212:215], v[32:35]
	v_mfma_f32_16x16x32_bf16 v[20:23], v[188:191], v[220:223], v[20:23]
	v_mfma_f32_16x16x32_bf16 v[16:19], v[196:199], v[220:223], v[16:19]
	v_mfma_f32_16x16x32_bf16 v[4:7], v[188:191], v[228:231], v[4:7]
	v_mfma_f32_16x16x32_bf16 v[0:3], v[196:199], v[228:231], v[0:3]
	s_setprio 0
	s_barrier
	s_add_i32 s19, 0, 0x18000
	v_add_u32_e32 v136, s19, v166
	s_add_i32 s22, 0, 0x1c000
	ds_read_b128 v[152:155], v136
	ds_read_b128 v[156:159], v136 offset:1024
	ds_read_b128 v[162:165], v136 offset:2048
	ds_read_b128 v[180:183], v136 offset:3072
	v_add_u32_e32 v136, s22, v166
	ds_read_b128 v[184:187], v136
	ds_read_b128 v[188:191], v136 offset:1024
	ds_read_b128 v[192:195], v136 offset:2048
	ds_read_b128 v[196:199], v136 offset:3072
	s_add_u32 s24, s86, 0x40000
	s_addc_u32 s25, s87, 0
	s_mov_b32 m0, s63
	ds_read_b128 v[200:203], v169 offset:32768
	ds_read_b128 v[204:207], v169 offset:33792
	ds_read_b128 v[208:211], v169 offset:34816
	ds_read_b128 v[212:215], v169 offset:35840
	ds_read_b128 v[216:219], v169 offset:36864
	ds_read_b128 v[220:223], v169 offset:37888
	ds_read_b128 v[224:227], v169 offset:38912
	ds_read_b128 v[228:231], v169 offset:39936
	global_load_lds_dwordx4 v128, s[24:25]
	s_mov_b32 m0, s74
	s_nop 0
	global_load_lds_dwordx4 v132, s[24:25]
	s_waitcnt vmcnt(8)
	s_waitcnt lgkmcnt(0)
	s_setprio 1
	s_barrier

; #define PG8_STAGE(bufoff, gbase, voff) do { _Pragma("unroll") for (int _i = 0; _i < 2; ++_i) \
;         __builtin_amdgcn_global_load_lds((const unsigned*)((const char*)(gbase) + (voff)[_i]), (LAS unsigned*)(lds + (bufoff) + ldsw + _i * 8192), 16, 0, 0); } while (0)
; #define PG8_LDA(dst, b, h) do { _Pragma("unroll") for (int m = 0; m < 4; ++m) _Pragma("unroll") for (int k = 0; k < 2; ++k) dst[m][k] = *(const LAS bf16x8*)(lds + PG8_SA(b, h) + aoff + m * 2048 + k * 1024); } while (0)
; #define PG8_MMA(ai, bj, At, Bt) do { __builtin_amdgcn_s_setprio(1); _Pragma("unroll") for (int m = 0; m < 4; ++m) _Pragma("unroll") for (int n = 0; n < 2; ++n) _Pragma("unroll") for (int k = 0; k < 2; ++k) \
;         acc[ai][bj][m][n] = __builtin_amdgcn_mfma_f32_16x16x32_bf16(Bt[n][k], At[m][k], acc[ai][bj][m][n], 0, 0, 0); __builtin_amdgcn_s_setprio(0); } while (0)
; #define PG8_WAIT_V(n) asm volatile("s_waitcnt vmcnt(" #n ")" ::: "memory")
; #define PG8_WAIT_L(n) asm volatile("s_waitcnt lgkmcnt(" #n ")" ::: "memory")
; #define PG8_BAR __builtin_amdgcn_s_barrier()
; #define PG8_SCHED __builtin_amdgcn_sched_barrier(0)
; template <class Epi>
; __device__ __forceinline__ void gemm_phase(LAS unsigned char* lds, const Gemm g, const StaticOrder& S, const Epi& E) {
;     ...
;             PG8_WAIT_V(8); PG8_WAIT_L(0); PG8_BAR; PG8_MMA(0, 0, At, B0); PG8_MMA(0, 1, At, B1); PG8_BAR; PG8_SCHED;
;             PG8_LDA(At, 1, 1); PG8_STAGE(PG8_SB(1, 0), b3, voffB); PG8_STAGE(PG8_SB(1, 1), b3 + hsB, voffB); PG8_STAGE(PG8_SA(1, 0), a3, voffA);
;             PG8_WAIT_V(8); PG8_WAIT_L(0); PG8_BAR; PG8_MMA(1, 0, At, B0); PG8_MMA(1, 1, At, B1); PG8_BAR; PG8_SCHED;
	v_mfma_f32_16x16x32_bf16 v[124:127], v[152:155], v[200:203], v[124:127]
	v_mfma_f32_16x16x32_bf16 v[120:123], v[162:165], v[200:203], v[120:123]
	v_mfma_f32_16x16x32_bf16 v[108:111], v[152:155], v[208:211], v[108:111]
	v_mfma_f32_16x16x32_bf16 v[104:107], v[162:165], v[208:211], v[104:107]
	v_mfma_f32_16x16x32_bf16 v[92:95], v[152:155], v[216:219], v[92:95]
	v_mfma_f32_16x16x32_bf16 v[88:91], v[162:165], v[216:219], v[88:91]
	v_mfma_f32_16x16x32_bf16 v[76:79], v[152:155], v[224:227], v[76:79]
	v_mfma_f32_16x16x32_bf16 v[72:75], v[162:165], v[224:227], v[72:75]
	v_mfma_f32_16x16x32_bf16 v[124:127], v[156:159], v[204:207], v[124:127]
	v_mfma_f32_16x16x32_bf16 v[120:123], v[180:183], v[204:207], v[120:123]
	v_mfma_f32_16x16x32_bf16 v[108:111], v[156:159], v[212:215], v[108:111]
	v_mfma_f32_16x16x32_bf16 v[104:107], v[180:183], v[212:215], v[104:107]
	v_mfma_f32_16x16x32_bf16 v[92:95], v[156:159], v[220:223], v[92:95]
	v_mfma_f32_16x16x32_bf16 v[88:91], v[180:183], v[220:223], v[88:91]
	v_mfma_f32_16x16x32_bf16 v[76:79], v[156:159], v[228:231], v[76:79]
	v_mfma_f32_16x16x32_bf16 v[72:75], v[180:183], v[228:231], v[72:75]
	s_setprio 0
	s_setprio 1
	v_mfma_f32_16x16x32_bf16 v[116:119], v[184:187], v[200:203], v[116:119]
	v_mfma_f32_16x16x32_bf16 v[112:115], v[192:195], v[200:203], v[112:115]
	v_mfma_f32_16x16x32_bf16 v[100:103], v[184:187], v[208:211], v[100:103]
	v_mfma_f32_16x16x32_bf16 v[96:99], v[192:195], v[208:211], v[96:99]
	v_mfma_f32_16x16x32_bf16 v[84:87], v[184:187], v[216:219], v[84:87]
	v_mfma_f32_16x16x32_bf16 v[80:83], v[192:195], v[216:219], v[80:83]
	v_mfma_f32_16x16x32_bf16 v[68:71], v[184:187], v[224:227], v[68:71]
	v_mfma_f32_16x16x32_bf16 v[64:67], v[192:195], v[224:227], v[64:67]
	v_mfma_f32_16x16x32_bf16 v[116:119], v[188:191], v[204:207], v[116:119]
	v_mfma_f32_16x16x32_bf16 v[112:115], v[196:199], v[204:207], v[112:115]
	v_mfma_f32_16x16x32_bf16 v[100:103], v[188:191], v[212:215], v[100:103]
	v_mfma_f32_16x16x32_bf16 v[96:99], v[196:199], v[212:215], v[96:99]
	v_mfma_f32_16x16x32_bf16 v[84:87], v[188:191], v[220:223], v[84:87]
	v_mfma_f32_16x16x32_bf16 v[80:83], v[196:199], v[220:223], v[80:83]
	v_mfma_f32_16x16x32_bf16 v[68:71], v[188:191], v[228:231], v[68:71]
	v_mfma_f32_16x16x32_bf16 v[64:67], v[196:199], v[228:231], v[64:67]
	s_setprio 0
	s_barrier
	s_add_u32 s98, s12, 0x80
	s_addc_u32 s99, s13, 0
	s_add_u32 s100, s86, 0x80
	s_addc_u32 s101, s87, 0
	s_add_i32 s19, s19, s4
	s_mov_b32 m0, s19
	ds_read_b128 v[200:203], v169 offset:49152
	ds_read_b128 v[204:207], v169 offset:50176
	ds_read_b128 v[208:211], v169 offset:51200
	ds_read_b128 v[212:215], v169 offset:52224
	ds_read_b128 v[216:219], v169 offset:53248
	ds_read_b128 v[220:223], v169 offset:54272
	ds_read_b128 v[224:227], v169 offset:55296
	ds_read_b128 v[228:231], v169 offset:56320
	global_load_lds_dwordx4 v130, s[98:99]
	s_add_i32 m0, s19, 0x2000
	s_add_u32 s12, s12, 0x40080
	s_addc_u32 s13, s13, 0
	s_add_i32 s19, s22, s4
	global_load_lds_dwordx4 v134, s[98:99]
	s_mov_b32 m0, s19
	s_nop 0
	global_load_lds_dwordx4 v130, s[12:13]
	s_add_i32 m0, s19, 0x2000
	s_nop 0
	global_load_lds_dwordx4 v134, s[12:13]
	s_mov_b32 m0, s16
	s_nop 0
	global_load_lds_dwordx4 v128, s[100:101]
	s_mov_b32 m0, s33
	s_nop 0
	global_load_lds_dwordx4 v132, s[100:101]
	s_waitcnt vmcnt(8)
	s_waitcnt lgkmcnt(0)
	s_setprio 1
	s_barrier

; #define PG8_MMA(ai, bj, At, Bt) do { __builtin_amdgcn_s_setprio(1); _Pragma("unroll") for (int m = 0; m < 4; ++m) _Pragma("unroll") for (int n = 0; n < 2; ++n) _Pragma("unroll") for (int k = 0; k < 2; ++k) \
;         acc[ai][bj][m][n] = __builtin_amdgcn_mfma_f32_16x16x32_bf16(Bt[n][k], At[m][k], acc[ai][bj][m][n], 0, 0, 0); __builtin_amdgcn_s_setprio(0); } while (0)
; #define PG8_WAIT_V(n) asm volatile("s_waitcnt vmcnt(" #n ")" ::: "memory")
; #define PG8_WAIT_L(n) asm volatile("s_waitcnt lgkmcnt(" #n ")" ::: "memory")
; #define PG8_BAR __builtin_amdgcn_s_barrier()
; #define PG8_SCHED __builtin_amdgcn_sched_barrier(0)
; template <class Epi>
; __device__ __forceinline__ void gemm_phase(LAS unsigned char* lds, const Gemm g, const StaticOrder& S, const Epi& E) {
;     ...
;             PG8_WAIT_V(8); PG8_WAIT_L(0); PG8_BAR; PG8_MMA(1, 0, At, B0); PG8_MMA(1, 1, At, B1); PG8_BAR; PG8_SCHED;
;         }
;         if (wr == 0) PG8_BAR;
	v_mfma_f32_16x16x32_bf16 v[60:63], v[152:155], v[200:203], v[60:63]
	v_mfma_f32_16x16x32_bf16 v[56:59], v[162:165], v[200:203], v[56:59]
	v_mfma_f32_16x16x32_bf16 v[44:47], v[152:155], v[208:211], v[44:47]
	v_mfma_f32_16x16x32_bf16 v[40:43], v[162:165], v[208:211], v[40:43]
	v_mfma_f32_16x16x32_bf16 v[28:31], v[152:155], v[216:219], v[28:31]
	v_mfma_f32_16x16x32_bf16 v[24:27], v[162:165], v[216:219], v[24:27]
	v_mfma_f32_16x16x32_bf16 v[12:15], v[152:155], v[224:227], v[12:15]
	v_mfma_f32_16x16x32_bf16 v[8:11], v[162:165], v[224:227], v[8:11]
	v_mfma_f32_16x16x32_bf16 v[60:63], v[156:159], v[204:207], v[60:63]
	v_mfma_f32_16x16x32_bf16 v[56:59], v[180:183], v[204:207], v[56:59]
	v_mfma_f32_16x16x32_bf16 v[44:47], v[156:159], v[212:215], v[44:47]
	v_mfma_f32_16x16x32_bf16 v[40:43], v[180:183], v[212:215], v[40:43]
	v_mfma_f32_16x16x32_bf16 v[28:31], v[156:159], v[220:223], v[28:31]
	v_mfma_f32_16x16x32_bf16 v[24:27], v[180:183], v[220:223], v[24:27]
	v_mfma_f32_16x16x32_bf16 v[12:15], v[156:159], v[228:231], v[12:15]
	v_mfma_f32_16x16x32_bf16 v[8:11], v[180:183], v[228:231], v[8:11]
	s_setprio 0
	s_setprio 1
	v_mfma_f32_16x16x32_bf16 v[52:55], v[184:187], v[200:203], v[52:55]
	v_mfma_f32_16x16x32_bf16 v[48:51], v[192:195], v[200:203], v[48:51]
	v_mfma_f32_16x16x32_bf16 v[36:39], v[184:187], v[208:211], v[36:39]
	v_mfma_f32_16x16x32_bf16 v[32:35], v[192:195], v[208:211], v[32:35]
	v_mfma_f32_16x16x32_bf16 v[20:23], v[184:187], v[216:219], v[20:23]
	v_mfma_f32_16x16x32_bf16 v[16:19], v[192:195], v[216:219], v[16:19]
	v_mfma_f32_16x16x32_bf16 v[4:7], v[184:187], v[224:227], v[4:7]
	v_mfma_f32_16x16x32_bf16 v[0:3], v[192:195], v[224:227], v[0:3]
	v_mfma_f32_16x16x32_bf16 v[52:55], v[188:191], v[204:207], v[52:55]
	v_mfma_f32_16x16x32_bf16 v[48:51], v[196:199], v[204:207], v[48:51]
	v_mfma_f32_16x16x32_bf16 v[36:39], v[188:191], v[212:215], v[36:39]
	v_mfma_f32_16x16x32_bf16 v[32:35], v[196:199], v[212:215], v[32:35]
	v_mfma_f32_16x16x32_bf16 v[20:23], v[188:191], v[220:223], v[20:23]
	v_mfma_f32_16x16x32_bf16 v[16:19], v[196:199], v[220:223], v[16:19]
	v_mfma_f32_16x16x32_bf16 v[4:7], v[188:191], v[228:231], v[4:7]
	v_mfma_f32_16x16x32_bf16 v[0:3], v[196:199], v[228:231], v[0:3]
	s_setprio 0
	s_barrier
	s_add_i32 s17, s17, 2
	s_add_u32 s10, s10, 0x100
	s_addc_u32 s11, s11, 0
	s_add_u32 s7, s7, 0x100
	s_addc_u32 s15, s15, 0
	s_cmp_gt_u32 s17, 13
	s_cbranch_scc0 .LBB0_414
	s_and_b64 vcc, exec, s[58:59]
	s_cbranch_vccz .LBB0_417
	s_barrier

; #define PG8_STAGE(bufoff, gbase, voff) do { _Pragma("unroll") for (int _i = 0; _i < 2; ++_i) \
;         __builtin_amdgcn_global_load_lds((const unsigned*)((const char*)(gbase) + (voff)[_i]), (LAS unsigned*)(lds + (bufoff) + ldsw + _i * 8192), 16, 0, 0); } while (0)
; #define PG8_LDA(dst, b, h) do { _Pragma("unroll") for (int m = 0; m < 4; ++m) _Pragma("unroll") for (int k = 0; k < 2; ++k) dst[m][k] = *(const LAS bf16x8*)(lds + PG8_SA(b, h) + aoff + m * 2048 + k * 1024); } while (0)
; #define PG8_LDB(dst, b, h) do { _Pragma("unroll") for (int n = 0; n < 2; ++n) _Pragma("unroll") for (int k = 0; k < 2; ++k) dst[n][k] = *(const LAS bf16x8*)(lds + PG8_SB(b, h) + boff + n * 2048 + k * 1024); } while (0)
; #define PG8_MMA(ai, bj, At, Bt) do { __builtin_amdgcn_s_setprio(1); _Pragma("unroll") for (int m = 0; m < 4; ++m) _Pragma("unroll") for (int n = 0; n < 2; ++n) _Pragma("unroll") for (int k = 0; k < 2; ++k) \
;         acc[ai][bj][m][n] = __builtin_amdgcn_mfma_f32_16x16x32_bf16(Bt[n][k], At[m][k], acc[ai][bj][m][n], 0, 0, 0); __builtin_amdgcn_s_setprio(0); } while (0)
; #define PG8_WAIT_V(n) asm volatile("s_waitcnt vmcnt(" #n ")" ::: "memory")
; #define PG8_WAIT_L(n) asm volatile("s_waitcnt lgkmcnt(" #n ")" ::: "memory")
; #define PG8_BAR __builtin_amdgcn_s_barrier()
; #define PG8_SCHED __builtin_amdgcn_sched_barrier(0)
; template <class Epi>
; __device__ __forceinline__ void gemm_phase(LAS unsigned char* lds, const Gemm g, const StaticOrder& S, const Epi& E) {
;     ...
;             const bool last = (t == nt - 2);
;             if constexpr (Epi::HAS_MID) { if (t == nt1) E.mid(acc, cur, wr, wc, fr, fq); }
;             const char* a1 = cA + ((Epi::HAS_MID && t >= nt1) ? dA2 : 0) + (size_t)(t + 1) * kstep;
;             const char* a2 = last ? nA : cA + ((Epi::HAS_MID && t + 2 >= nt1) ? dA2 : 0) + (size_t)(t + 2) * kstep; const char* b2 = last ? nB : cB + ((Epi::HAS_MID && t + 2 >= nt1) ? dB2 : 0) + (size_t)(t + 2) * kstep;
;             const char* a3 = a2 + kstep; const char* b3 = b2 + kstep;
;             PG8_LDB(B0, 0, 0); PG8_LDB(B1, 0, 1); PG8_SCHED; PG8_LDA(At, 0, 0); PG8_STAGE(PG8_SA(1, 1), a1 + hsA, voffA);
;             PG8_WAIT_V(8); PG8_WAIT_L(0); PG8_BAR; PG8_MMA(0, 0, At, B0); PG8_MMA(0, 1, At, B1); PG8_BAR; PG8_SCHED;
.LBB0_720:
	ds_read_b128 v[128:131], v182
	ds_read_b128 v[132:135], v182 offset:1024
	ds_read_b128 v[136:139], v182 offset:2048
	ds_read_b128 v[140:143], v182 offset:3072
	ds_read_b128 v[166:169], v183
	ds_read_b128 v[188:191], v183 offset:1024
	ds_read_b128 v[192:195], v183 offset:2048
	ds_read_b128 v[196:199], v183 offset:3072
	s_add_u32 s39, s62, 0xfffc0080
	s_addc_u32 s40, s63, -1
	s_cmp_eq_u32 s38, 12
	s_cselect_b32 s67, s6, s40
	s_cselect_b32 s66, s7, s39
	s_cselect_b32 s65, s15, s37
	s_cselect_b32 s64, s35, s36
	s_add_i32 m0, s4, 0xc000
	ds_read_b128 v[200:203], v184
	ds_read_b128 v[204:207], v184 offset:1024
	ds_read_b128 v[208:211], v184 offset:2048
	ds_read_b128 v[212:215], v184 offset:3072
	ds_read_b128 v[216:219], v184 offset:4096
	ds_read_b128 v[220:223], v184 offset:5120
	ds_read_b128 v[224:227], v184 offset:6144
	ds_read_b128 v[228:231], v184 offset:7168
	global_load_lds_dwordx4 v156, s[62:63]
	s_add_i32 m0, s4, 0xe000
	s_nop 0
	global_load_lds_dwordx4 v158, s[62:63]
	s_waitcnt vmcnt(8)
	s_waitcnt lgkmcnt(0)
	s_setprio 1
	s_barrier

; #define PG8_STAGE(bufoff, gbase, voff) do { _Pragma("unroll") for (int _i = 0; _i < 2; ++_i) \
;         __builtin_amdgcn_global_load_lds((const unsigned*)((const char*)(gbase) + (voff)[_i]), (LAS unsigned*)(lds + (bufoff) + ldsw + _i * 8192), 16, 0, 0); } while (0)
; #define PG8_LDA(dst, b, h) do { _Pragma("unroll") for (int m = 0; m < 4; ++m) _Pragma("unroll") for (int k = 0; k < 2; ++k) dst[m][k] = *(const LAS bf16x8*)(lds + PG8_SA(b, h) + aoff + m * 2048 + k * 1024); } while (0)
; #define PG8_MMA(ai, bj, At, Bt) do { __builtin_amdgcn_s_setprio(1); _Pragma("unroll") for (int m = 0; m < 4; ++m) _Pragma("unroll") for (int n = 0; n < 2; ++n) _Pragma("unroll") for (int k = 0; k < 2; ++k) \
;         acc[ai][bj][m][n] = __builtin_amdgcn_mfma_f32_16x16x32_bf16(Bt[n][k], At[m][k], acc[ai][bj][m][n], 0, 0, 0); __builtin_amdgcn_s_setprio(0); } while (0)
; #define PG8_WAIT_V(n) asm volatile("s_waitcnt vmcnt(" #n ")" ::: "memory")
; #define PG8_WAIT_L(n) asm volatile("s_waitcnt lgkmcnt(" #n ")" ::: "memory")
; #define PG8_BAR __builtin_amdgcn_s_barrier()
; #define PG8_SCHED __builtin_amdgcn_sched_barrier(0)
; template <class Epi>
; __device__ __forceinline__ void gemm_phase(LAS unsigned char* lds, const Gemm g, const StaticOrder& S, const Epi& E) {
;     ...
;             PG8_WAIT_V(8); PG8_WAIT_L(0); PG8_BAR; PG8_MMA(0, 0, At, B0); PG8_MMA(0, 1, At, B1); PG8_BAR; PG8_SCHED;
;             PG8_LDA(At, 0, 1); PG8_STAGE(PG8_SB(0, 0), b2, voffB); PG8_STAGE(PG8_SB(0, 1), b2 + hsB, voffB); PG8_STAGE(PG8_SA(0, 0), a2, voffA);
;             PG8_WAIT_V(8); PG8_WAIT_L(0); PG8_BAR; PG8_MMA(1, 0, At, B0); PG8_MMA(1, 1, At, B1); PG8_BAR; PG8_SCHED;
	v_mfma_f32_16x16x32_bf16 v[124:127], v[128:131], v[200:203], v[124:127]
	v_mfma_f32_16x16x32_bf16 v[120:123], v[136:139], v[200:203], v[120:123]
	v_mfma_f32_16x16x32_bf16 v[108:111], v[128:131], v[208:211], v[108:111]
	v_mfma_f32_16x16x32_bf16 v[104:107], v[136:139], v[208:211], v[104:107]
	v_mfma_f32_16x16x32_bf16 v[92:95], v[128:131], v[216:219], v[92:95]
	v_mfma_f32_16x16x32_bf16 v[88:91], v[136:139], v[216:219], v[88:91]
	v_mfma_f32_16x16x32_bf16 v[76:79], v[128:131], v[224:227], v[76:79]
	v_mfma_f32_16x16x32_bf16 v[72:75], v[136:139], v[224:227], v[72:75]
	v_mfma_f32_16x16x32_bf16 v[124:127], v[132:135], v[204:207], v[124:127]
	v_mfma_f32_16x16x32_bf16 v[120:123], v[140:143], v[204:207], v[120:123]
	v_mfma_f32_16x16x32_bf16 v[108:111], v[132:135], v[212:215], v[108:111]
	v_mfma_f32_16x16x32_bf16 v[104:107], v[140:143], v[212:215], v[104:107]
	v_mfma_f32_16x16x32_bf16 v[92:95], v[132:135], v[220:223], v[92:95]
	v_mfma_f32_16x16x32_bf16 v[88:91], v[140:143], v[220:223], v[88:91]
	v_mfma_f32_16x16x32_bf16 v[76:79], v[132:135], v[228:231], v[76:79]
	v_mfma_f32_16x16x32_bf16 v[72:75], v[140:143], v[228:231], v[72:75]
	s_setprio 0
	s_setprio 1
	v_mfma_f32_16x16x32_bf16 v[116:119], v[166:169], v[200:203], v[116:119]
	v_mfma_f32_16x16x32_bf16 v[112:115], v[192:195], v[200:203], v[112:115]
	v_mfma_f32_16x16x32_bf16 v[100:103], v[166:169], v[208:211], v[100:103]
	v_mfma_f32_16x16x32_bf16 v[96:99], v[192:195], v[208:211], v[96:99]
	v_mfma_f32_16x16x32_bf16 v[84:87], v[166:169], v[216:219], v[84:87]
	v_mfma_f32_16x16x32_bf16 v[80:83], v[192:195], v[216:219], v[80:83]
	v_mfma_f32_16x16x32_bf16 v[68:71], v[166:169], v[224:227], v[68:71]
	v_mfma_f32_16x16x32_bf16 v[64:67], v[192:195], v[224:227], v[64:67]
	v_mfma_f32_16x16x32_bf16 v[116:119], v[188:191], v[204:207], v[116:119]
	v_mfma_f32_16x16x32_bf16 v[112:115], v[196:199], v[204:207], v[112:115]
	v_mfma_f32_16x16x32_bf16 v[100:103], v[188:191], v[212:215], v[100:103]
	v_mfma_f32_16x16x32_bf16 v[96:99], v[196:199], v[212:215], v[96:99]
	v_mfma_f32_16x16x32_bf16 v[84:87], v[188:191], v[220:223], v[84:87]
	v_mfma_f32_16x16x32_bf16 v[80:83], v[196:199], v[220:223], v[80:83]
	v_mfma_f32_16x16x32_bf16 v[68:71], v[188:191], v[228:231], v[68:71]
	v_mfma_f32_16x16x32_bf16 v[64:67], v[196:199], v[228:231], v[64:67]
	s_setprio 0
	s_barrier
	s_add_i32 s39, s27, s3
	s_mov_b32 m0, s39
	ds_read_b128 v[200:203], v184 offset:16384
	ds_read_b128 v[204:207], v184 offset:17408
	ds_read_b128 v[208:211], v184 offset:18432
	ds_read_b128 v[212:215], v184 offset:19456
	ds_read_b128 v[216:219], v184 offset:20480
	ds_read_b128 v[220:223], v184 offset:21504
	ds_read_b128 v[224:227], v184 offset:22528
	ds_read_b128 v[228:231], v184 offset:23552
	global_load_lds_dwordx4 v146, s[64:65]
	s_add_i32 m0, s39, 0x2000
	s_add_u32 s40, s64, 0x40000
	s_addc_u32 s41, s65, 0
	s_add_i32 s39, s28, s3
	global_load_lds_dwordx4 v150, s[64:65]
	s_mov_b32 m0, s39
	s_nop 0
	global_load_lds_dwordx4 v146, s[40:41]
	s_add_i32 m0, s39, 0x2000
	s_nop 0
	global_load_lds_dwordx4 v150, s[40:41]
	s_mov_b32 m0, s4
	s_nop 0
	global_load_lds_dwordx4 v144, s[66:67]
	s_mov_b32 m0, s5
	s_nop 0
	global_load_lds_dwordx4 v148, s[66:67]
	s_waitcnt vmcnt(8)
	s_waitcnt lgkmcnt(0)
	s_setprio 1
	s_barrier

; #define PG8_STAGE(bufoff, gbase, voff) do { _Pragma("unroll") for (int _i = 0; _i < 2; ++_i) \
;         __builtin_amdgcn_global_load_lds((const unsigned*)((const char*)(gbase) + (voff)[_i]), (LAS unsigned*)(lds + (bufoff) + ldsw + _i * 8192), 16, 0, 0); } while (0)
; #define PG8_LDA(dst, b, h) do { _Pragma("unroll") for (int m = 0; m < 4; ++m) _Pragma("unroll") for (int k = 0; k < 2; ++k) dst[m][k] = *(const LAS bf16x8*)(lds + PG8_SA(b, h) + aoff + m * 2048 + k * 1024); } while (0)
; #define PG8_LDB(dst, b, h) do { _Pragma("unroll") for (int n = 0; n < 2; ++n) _Pragma("unroll") for (int k = 0; k < 2; ++k) dst[n][k] = *(const LAS bf16x8*)(lds + PG8_SB(b, h) + boff + n * 2048 + k * 1024); } while (0)
; #define PG8_MMA(ai, bj, At, Bt) do { __builtin_amdgcn_s_setprio(1); _Pragma("unroll") for (int m = 0; m < 4; ++m) _Pragma("unroll") for (int n = 0; n < 2; ++n) _Pragma("unroll") for (int k = 0; k < 2; ++k) \
;         acc[ai][bj][m][n] = __builtin_amdgcn_mfma_f32_16x16x32_bf16(Bt[n][k], At[m][k], acc[ai][bj][m][n], 0, 0, 0); __builtin_amdgcn_s_setprio(0); } while (0)
; #define PG8_WAIT_V(n) asm volatile("s_waitcnt vmcnt(" #n ")" ::: "memory")
; #define PG8_WAIT_L(n) asm volatile("s_waitcnt lgkmcnt(" #n ")" ::: "memory")
; #define PG8_BAR __builtin_amdgcn_s_barrier()
; #define PG8_SCHED __builtin_amdgcn_sched_barrier(0)
; template <class Epi>
; __device__ __forceinline__ void gemm_phase(LAS unsigned char* lds, const Gemm g, const StaticOrder& S, const Epi& E) {
;     ...
;             PG8_WAIT_V(8); PG8_WAIT_L(0); PG8_BAR; PG8_MMA(1, 0, At, B0); PG8_MMA(1, 1, At, B1); PG8_BAR; PG8_SCHED;
;             PG8_LDB(B0, 1, 0); PG8_LDB(B1, 1, 1); PG8_SCHED; PG8_LDA(At, 1, 0); PG8_STAGE(PG8_SA(0, 1), a2 + hsA, voffA);
;             PG8_WAIT_V(8); PG8_WAIT_L(0); PG8_BAR; PG8_MMA(0, 0, At, B0); PG8_MMA(0, 1, At, B1); PG8_BAR; PG8_SCHED;
	v_mfma_f32_16x16x32_bf16 v[60:63], v[128:131], v[200:203], v[60:63]
	v_mfma_f32_16x16x32_bf16 v[56:59], v[136:139], v[200:203], v[56:59]
	v_mfma_f32_16x16x32_bf16 v[44:47], v[128:131], v[208:211], v[44:47]
	v_mfma_f32_16x16x32_bf16 v[40:43], v[136:139], v[208:211], v[40:43]
	v_mfma_f32_16x16x32_bf16 v[28:31], v[128:131], v[216:219], v[28:31]
	v_mfma_f32_16x16x32_bf16 v[24:27], v[136:139], v[216:219], v[24:27]
	v_mfma_f32_16x16x32_bf16 v[12:15], v[128:131], v[224:227], v[12:15]
	v_mfma_f32_16x16x32_bf16 v[8:11], v[136:139], v[224:227], v[8:11]
	v_mfma_f32_16x16x32_bf16 v[60:63], v[132:135], v[204:207], v[60:63]
	v_mfma_f32_16x16x32_bf16 v[56:59], v[140:143], v[204:207], v[56:59]
	v_mfma_f32_16x16x32_bf16 v[44:47], v[132:135], v[212:215], v[44:47]
	v_mfma_f32_16x16x32_bf16 v[40:43], v[140:143], v[212:215], v[40:43]
	v_mfma_f32_16x16x32_bf16 v[28:31], v[132:135], v[220:223], v[28:31]
	v_mfma_f32_16x16x32_bf16 v[24:27], v[140:143], v[220:223], v[24:27]
	v_mfma_f32_16x16x32_bf16 v[12:15], v[132:135], v[228:231], v[12:15]
	v_mfma_f32_16x16x32_bf16 v[8:11], v[140:143], v[228:231], v[8:11]
	s_setprio 0
	s_setprio 1
	v_mfma_f32_16x16x32_bf16 v[52:55], v[166:169], v[200:203], v[52:55]
	v_mfma_f32_16x16x32_bf16 v[48:51], v[192:195], v[200:203], v[48:51]
	v_mfma_f32_16x16x32_bf16 v[36:39], v[166:169], v[208:211], v[36:39]
	v_mfma_f32_16x16x32_bf16 v[32:35], v[192:195], v[208:211], v[32:35]
	v_mfma_f32_16x16x32_bf16 v[20:23], v[166:169], v[216:219], v[20:23]
	v_mfma_f32_16x16x32_bf16 v[16:19], v[192:195], v[216:219], v[16:19]
	v_mfma_f32_16x16x32_bf16 v[4:7], v[166:169], v[224:227], v[4:7]
	v_mfma_f32_16x16x32_bf16 v[0:3], v[192:195], v[224:227], v[0:3]
	v_mfma_f32_16x16x32_bf16 v[52:55], v[188:191], v[204:207], v[52:55]
	v_mfma_f32_16x16x32_bf16 v[48:51], v[196:199], v[204:207], v[48:51]
	v_mfma_f32_16x16x32_bf16 v[36:39], v[188:191], v[212:215], v[36:39]
	v_mfma_f32_16x16x32_bf16 v[32:35], v[196:199], v[212:215], v[32:35]
	v_mfma_f32_16x16x32_bf16 v[20:23], v[188:191], v[220:223], v[20:23]
	v_mfma_f32_16x16x32_bf16 v[16:19], v[196:199], v[220:223], v[16:19]
	v_mfma_f32_16x16x32_bf16 v[4:7], v[188:191], v[228:231], v[4:7]
	v_mfma_f32_16x16x32_bf16 v[0:3], v[196:199], v[228:231], v[0:3]
	s_setprio 0
	s_barrier
	s_add_i32 s39, 0, 0x18000
	s_add_i32 s42, 0, 0x1c000
	v_add_u32_e32 v140, s39, v173
	v_add_u32_e32 v152, s42, v173
	ds_read_b128 v[128:131], v140
	ds_read_b128 v[132:135], v140 offset:1024
	ds_read_b128 v[136:139], v140 offset:2048
	ds_read_b128 v[140:143], v140 offset:3072
	ds_read_b128 v[166:169], v152
	ds_read_b128 v[188:191], v152 offset:1024
	ds_read_b128 v[192:195], v152 offset:2048
	ds_read_b128 v[196:199], v152 offset:3072
	s_add_u32 s40, s66, 0x40000
	s_addc_u32 s41, s67, 0
	s_mov_b32 m0, s16
	ds_read_b128 v[200:203], v184 offset:32768
	ds_read_b128 v[204:207], v184 offset:33792
	ds_read_b128 v[208:211], v184 offset:34816
	ds_read_b128 v[212:215], v184 offset:35840
	ds_read_b128 v[216:219], v184 offset:36864
	ds_read_b128 v[220:223], v184 offset:37888
	ds_read_b128 v[224:227], v184 offset:38912
	ds_read_b128 v[228:231], v184 offset:39936
	global_load_lds_dwordx4 v144, s[40:41]
	s_mov_b32 m0, s17
	s_nop 0
	global_load_lds_dwordx4 v148, s[40:41]
	s_waitcnt vmcnt(8)
	s_waitcnt lgkmcnt(0)
	s_setprio 1
	s_barrier

; #define PG8_STAGE(bufoff, gbase, voff) do { _Pragma("unroll") for (int _i = 0; _i < 2; ++_i) \
;         __builtin_amdgcn_global_load_lds((const unsigned*)((const char*)(gbase) + (voff)[_i]), (LAS unsigned*)(lds + (bufoff) + ldsw + _i * 8192), 16, 0, 0); } while (0)
; #define PG8_LDA(dst, b, h) do { _Pragma("unroll") for (int m = 0; m < 4; ++m) _Pragma("unroll") for (int k = 0; k < 2; ++k) dst[m][k] = *(const LAS bf16x8*)(lds + PG8_SA(b, h) + aoff + m * 2048 + k * 1024); } while (0)
; #define PG8_MMA(ai, bj, At, Bt) do { __builtin_amdgcn_s_setprio(1); _Pragma("unroll") for (int m = 0; m < 4; ++m) _Pragma("unroll") for (int n = 0; n < 2; ++n) _Pragma("unroll") for (int k = 0; k < 2; ++k) \
;         acc[ai][bj][m][n] = __builtin_amdgcn_mfma_f32_16x16x32_bf16(Bt[n][k], At[m][k], acc[ai][bj][m][n], 0, 0, 0); __builtin_amdgcn_s_setprio(0); } while (0)
; #define PG8_WAIT_V(n) asm volatile("s_waitcnt vmcnt(" #n ")" ::: "memory")
; #define PG8_WAIT_L(n) asm volatile("s_waitcnt lgkmcnt(" #n ")" ::: "memory")
; #define PG8_BAR __builtin_amdgcn_s_barrier()
; #define PG8_SCHED __builtin_amdgcn_sched_barrier(0)
; template <class Epi>
; __device__ __forceinline__ void gemm_phase(LAS unsigned char* lds, const Gemm g, const StaticOrder& S, const Epi& E) {
;     ...
;             PG8_WAIT_V(8); PG8_WAIT_L(0); PG8_BAR; PG8_MMA(0, 0, At, B0); PG8_MMA(0, 1, At, B1); PG8_BAR; PG8_SCHED;
;             PG8_LDA(At, 1, 1); PG8_STAGE(PG8_SB(1, 0), b3, voffB); PG8_STAGE(PG8_SB(1, 1), b3 + hsB, voffB); PG8_STAGE(PG8_SA(1, 0), a3, voffA);
;             PG8_WAIT_V(8); PG8_WAIT_L(0); PG8_BAR; PG8_MMA(1, 0, At, B0); PG8_MMA(1, 1, At, B1); PG8_BAR; PG8_SCHED;
	v_mfma_f32_16x16x32_bf16 v[124:127], v[128:131], v[200:203], v[124:127]
	v_mfma_f32_16x16x32_bf16 v[120:123], v[136:139], v[200:203], v[120:123]
	v_mfma_f32_16x16x32_bf16 v[108:111], v[128:131], v[208:211], v[108:111]
	v_mfma_f32_16x16x32_bf16 v[104:107], v[136:139], v[208:211], v[104:107]
	v_mfma_f32_16x16x32_bf16 v[92:95], v[128:131], v[216:219], v[92:95]
	v_mfma_f32_16x16x32_bf16 v[88:91], v[136:139], v[216:219], v[88:91]
	v_mfma_f32_16x16x32_bf16 v[76:79], v[128:131], v[224:227], v[76:79]
	v_mfma_f32_16x16x32_bf16 v[72:75], v[136:139], v[224:227], v[72:75]
	v_mfma_f32_16x16x32_bf16 v[124:127], v[132:135], v[204:207], v[124:127]
	v_mfma_f32_16x16x32_bf16 v[120:123], v[140:143], v[204:207], v[120:123]
	v_mfma_f32_16x16x32_bf16 v[108:111], v[132:135], v[212:215], v[108:111]
	v_mfma_f32_16x16x32_bf16 v[104:107], v[140:143], v[212:215], v[104:107]
	v_mfma_f32_16x16x32_bf16 v[92:95], v[132:135], v[220:223], v[92:95]
	v_mfma_f32_16x16x32_bf16 v[88:91], v[140:143], v[220:223], v[88:91]
	v_mfma_f32_16x16x32_bf16 v[76:79], v[132:135], v[228:231], v[76:79]
	v_mfma_f32_16x16x32_bf16 v[72:75], v[140:143], v[228:231], v[72:75]
	s_setprio 0
	s_setprio 1
	v_mfma_f32_16x16x32_bf16 v[116:119], v[166:169], v[200:203], v[116:119]
	v_mfma_f32_16x16x32_bf16 v[112:115], v[192:195], v[200:203], v[112:115]
	v_mfma_f32_16x16x32_bf16 v[100:103], v[166:169], v[208:211], v[100:103]
	v_mfma_f32_16x16x32_bf16 v[96:99], v[192:195], v[208:211], v[96:99]
	v_mfma_f32_16x16x32_bf16 v[84:87], v[166:169], v[216:219], v[84:87]
	v_mfma_f32_16x16x32_bf16 v[80:83], v[192:195], v[216:219], v[80:83]
	v_mfma_f32_16x16x32_bf16 v[68:71], v[166:169], v[224:227], v[68:71]
	v_mfma_f32_16x16x32_bf16 v[64:67], v[192:195], v[224:227], v[64:67]
	v_mfma_f32_16x16x32_bf16 v[116:119], v[188:191], v[204:207], v[116:119]
	v_mfma_f32_16x16x32_bf16 v[112:115], v[196:199], v[204:207], v[112:115]
	v_mfma_f32_16x16x32_bf16 v[100:103], v[188:191], v[212:215], v[100:103]
	v_mfma_f32_16x16x32_bf16 v[96:99], v[196:199], v[212:215], v[96:99]
	v_mfma_f32_16x16x32_bf16 v[84:87], v[188:191], v[220:223], v[84:87]
	v_mfma_f32_16x16x32_bf16 v[80:83], v[196:199], v[220:223], v[80:83]
	v_mfma_f32_16x16x32_bf16 v[68:71], v[188:191], v[228:231], v[68:71]
	v_mfma_f32_16x16x32_bf16 v[64:67], v[196:199], v[228:231], v[64:67]
	s_setprio 0
	s_barrier
	s_add_u32 s98, s64, 0x80
	s_addc_u32 s99, s65, 0
	s_add_u32 s100, s66, 0x80
	s_addc_u32 s101, s67, 0
	s_add_i32 s39, s39, s3
	s_mov_b32 m0, s39
	ds_read_b128 v[200:203], v184 offset:49152
	ds_read_b128 v[204:207], v184 offset:50176
	ds_read_b128 v[208:211], v184 offset:51200
	ds_read_b128 v[212:215], v184 offset:52224
	ds_read_b128 v[216:219], v184 offset:53248
	ds_read_b128 v[220:223], v184 offset:54272
	ds_read_b128 v[224:227], v184 offset:55296
	ds_read_b128 v[228:231], v184 offset:56320
	global_load_lds_dwordx4 v146, s[98:99]
	s_add_i32 m0, s39, 0x2000
	s_add_u32 s40, s64, 0x40080
	s_addc_u32 s41, s65, 0
	s_add_i32 s39, s42, s3
	global_load_lds_dwordx4 v150, s[98:99]
	s_mov_b32 m0, s39
	s_nop 0
	global_load_lds_dwordx4 v146, s[40:41]
	s_add_i32 m0, s39, 0x2000
	s_nop 0
	global_load_lds_dwordx4 v150, s[40:41]
	s_mov_b32 m0, s22
	s_nop 0
	global_load_lds_dwordx4 v144, s[100:101]
	s_mov_b32 m0, s23
	s_nop 0
	global_load_lds_dwordx4 v148, s[100:101]
	s_waitcnt vmcnt(8)
	s_waitcnt lgkmcnt(0)
	s_setprio 1
	s_barrier

; #define PG8_MMA(ai, bj, At, Bt) do { __builtin_amdgcn_s_setprio(1); _Pragma("unroll") for (int m = 0; m < 4; ++m) _Pragma("unroll") for (int n = 0; n < 2; ++n) _Pragma("unroll") for (int k = 0; k < 2; ++k) \
;         acc[ai][bj][m][n] = __builtin_amdgcn_mfma_f32_16x16x32_bf16(Bt[n][k], At[m][k], acc[ai][bj][m][n], 0, 0, 0); __builtin_amdgcn_s_setprio(0); } while (0)
; #define PG8_WAIT_V(n) asm volatile("s_waitcnt vmcnt(" #n ")" ::: "memory")
; #define PG8_WAIT_L(n) asm volatile("s_waitcnt lgkmcnt(" #n ")" ::: "memory")
; #define PG8_BAR __builtin_amdgcn_s_barrier()
; #define PG8_SCHED __builtin_amdgcn_sched_barrier(0)
; template <class Epi>
; __device__ __forceinline__ void gemm_phase(LAS unsigned char* lds, const Gemm g, const StaticOrder& S, const Epi& E) {
;     ...
;             PG8_WAIT_V(8); PG8_WAIT_L(0); PG8_BAR; PG8_MMA(1, 0, At, B0); PG8_MMA(1, 1, At, B1); PG8_BAR; PG8_SCHED;
;         }
;         if (wr == 0) PG8_BAR;
	v_mfma_f32_16x16x32_bf16 v[60:63], v[128:131], v[200:203], v[60:63]
	v_mfma_f32_16x16x32_bf16 v[56:59], v[136:139], v[200:203], v[56:59]
	v_mfma_f32_16x16x32_bf16 v[44:47], v[128:131], v[208:211], v[44:47]
	v_mfma_f32_16x16x32_bf16 v[40:43], v[136:139], v[208:211], v[40:43]
	v_mfma_f32_16x16x32_bf16 v[28:31], v[128:131], v[216:219], v[28:31]
	v_mfma_f32_16x16x32_bf16 v[24:27], v[136:139], v[216:219], v[24:27]
	v_mfma_f32_16x16x32_bf16 v[12:15], v[128:131], v[224:227], v[12:15]
	v_mfma_f32_16x16x32_bf16 v[8:11], v[136:139], v[224:227], v[8:11]
	v_mfma_f32_16x16x32_bf16 v[60:63], v[132:135], v[204:207], v[60:63]
	v_mfma_f32_16x16x32_bf16 v[56:59], v[140:143], v[204:207], v[56:59]
	v_mfma_f32_16x16x32_bf16 v[44:47], v[132:135], v[212:215], v[44:47]
	v_mfma_f32_16x16x32_bf16 v[40:43], v[140:143], v[212:215], v[40:43]
	v_mfma_f32_16x16x32_bf16 v[28:31], v[132:135], v[220:223], v[28:31]
	v_mfma_f32_16x16x32_bf16 v[24:27], v[140:143], v[220:223], v[24:27]
	v_mfma_f32_16x16x32_bf16 v[12:15], v[132:135], v[228:231], v[12:15]
	v_mfma_f32_16x16x32_bf16 v[8:11], v[140:143], v[228:231], v[8:11]
	s_setprio 0
	s_setprio 1
	v_mfma_f32_16x16x32_bf16 v[52:55], v[166:169], v[200:203], v[52:55]
	v_mfma_f32_16x16x32_bf16 v[48:51], v[192:195], v[200:203], v[48:51]
	v_mfma_f32_16x16x32_bf16 v[36:39], v[166:169], v[208:211], v[36:39]
	v_mfma_f32_16x16x32_bf16 v[32:35], v[192:195], v[208:211], v[32:35]
	v_mfma_f32_16x16x32_bf16 v[20:23], v[166:169], v[216:219], v[20:23]
	v_mfma_f32_16x16x32_bf16 v[16:19], v[192:195], v[216:219], v[16:19]
	v_mfma_f32_16x16x32_bf16 v[4:7], v[166:169], v[224:227], v[4:7]
	v_mfma_f32_16x16x32_bf16 v[0:3], v[192:195], v[224:227], v[0:3]
	v_mfma_f32_16x16x32_bf16 v[52:55], v[188:191], v[204:207], v[52:55]
	v_mfma_f32_16x16x32_bf16 v[48:51], v[196:199], v[204:207], v[48:51]
	v_mfma_f32_16x16x32_bf16 v[36:39], v[188:191], v[212:215], v[36:39]
	v_mfma_f32_16x16x32_bf16 v[32:35], v[196:199], v[212:215], v[32:35]
	v_mfma_f32_16x16x32_bf16 v[20:23], v[188:191], v[220:223], v[20:23]
	v_mfma_f32_16x16x32_bf16 v[16:19], v[196:199], v[220:223], v[16:19]
	v_mfma_f32_16x16x32_bf16 v[4:7], v[188:191], v[228:231], v[4:7]
	v_mfma_f32_16x16x32_bf16 v[0:3], v[196:199], v[228:231], v[0:3]
	s_setprio 0
	s_barrier
	s_add_i32 s38, s38, 2
	s_add_u32 s62, s62, 0x100
	s_addc_u32 s63, s63, 0
	s_add_u32 s36, s36, 0x100
	s_addc_u32 s37, s37, 0
	s_cmp_gt_u32 s38, 13
	s_cbranch_scc0 .LBB0_720
	s_and_b64 vcc, exec, s[12:13]
	s_cbranch_vccz .LBB0_723
	s_barrier

; #define PG8_STAGE(bufoff, gbase, voff) do { _Pragma("unroll") for (int _i = 0; _i < 2; ++_i) \
;         __builtin_amdgcn_global_load_lds((const unsigned*)((const char*)(gbase) + (voff)[_i]), (LAS unsigned*)(lds + (bufoff) + ldsw + _i * 8192), 16, 0, 0); } while (0)
; #define PG8_LDA(dst, b, h) do { _Pragma("unroll") for (int m = 0; m < 4; ++m) _Pragma("unroll") for (int k = 0; k < 2; ++k) dst[m][k] = *(const LAS bf16x8*)(lds + PG8_SA(b, h) + aoff + m * 2048 + k * 1024); } while (0)
; #define PG8_LDB(dst, b, h) do { _Pragma("unroll") for (int n = 0; n < 2; ++n) _Pragma("unroll") for (int k = 0; k < 2; ++k) dst[n][k] = *(const LAS bf16x8*)(lds + PG8_SB(b, h) + boff + n * 2048 + k * 1024); } while (0)
; #define PG8_MMA(ai, bj, At, Bt) do { __builtin_amdgcn_s_setprio(1); _Pragma("unroll") for (int m = 0; m < 4; ++m) _Pragma("unroll") for (int n = 0; n < 2; ++n) _Pragma("unroll") for (int k = 0; k < 2; ++k) \
;         acc[ai][bj][m][n] = __builtin_amdgcn_mfma_f32_16x16x32_bf16(Bt[n][k], At[m][k], acc[ai][bj][m][n], 0, 0, 0); __builtin_amdgcn_s_setprio(0); } while (0)
; #define PG8_WAIT_V(n) asm volatile("s_waitcnt vmcnt(" #n ")" ::: "memory")
; #define PG8_WAIT_L(n) asm volatile("s_waitcnt lgkmcnt(" #n ")" ::: "memory")
; #define PG8_BAR __builtin_amdgcn_s_barrier()
; #define PG8_SCHED __builtin_amdgcn_sched_barrier(0)
; template <class Epi>
; __device__ __forceinline__ void gemm_phase(LAS unsigned char* lds, const Gemm g, const StaticOrder& S, const Epi& E) {
;     ...
;         for (int t = 0; t < nt; t += 2) {
;             const bool last = (t == nt - 2);
;             if constexpr (Epi::HAS_MID) { if (t == nt1) E.mid(acc, cur, wr, wc, fr, fq); }
;             const char* a1 = cA + ((Epi::HAS_MID && t >= nt1) ? dA2 : 0) + (size_t)(t + 1) * kstep;
;             const char* a2 = last ? nA : cA + ((Epi::HAS_MID && t + 2 >= nt1) ? dA2 : 0) + (size_t)(t + 2) * kstep; const char* b2 = last ? nB : cB + ((Epi::HAS_MID && t + 2 >= nt1) ? dB2 : 0) + (size_t)(t + 2) * kstep;
;             const char* a3 = a2 + kstep; const char* b3 = b2 + kstep;
;             PG8_LDB(B0, 0, 0); PG8_LDB(B1, 0, 1); PG8_SCHED; PG8_LDA(At, 0, 0); PG8_STAGE(PG8_SA(1, 1), a1 + hsA, voffA);
;             PG8_WAIT_V(8); PG8_WAIT_L(0); PG8_BAR; PG8_MMA(0, 0, At, B0); PG8_MMA(0, 1, At, B1); PG8_BAR; PG8_SCHED;
.LBB0_1083:
	s_add_i32 s33, s33, 2
	s_add_u32 s0, s52, s54
	s_addc_u32 s1, s53, s55
	s_add_u32 s0, s0, 0x100
	v_add_u32_e32 v153, s74, v171
	s_addc_u32 s1, s1, 0
	ds_read_b128 v[128:131], v153
	ds_read_b128 v[132:135], v153 offset:1024
	ds_read_b128 v[164:167], v153 offset:2048
	ds_read_b128 v[184:187], v153 offset:3072
	v_add_u32_e32 v153, s75, v171
	s_cmp_gt_u32 s33, 13
	ds_read_b128 v[188:191], v153
	ds_read_b128 v[192:195], v153 offset:1024
	ds_read_b128 v[196:199], v153 offset:2048
	ds_read_b128 v[200:203], v153 offset:3072
	s_cselect_b32 s17, 0x1ff800, 0
	s_add_u32 s17, s17, s54
	s_addc_u32 s24, 0, s55
	s_add_u32 s17, s22, s17
	s_addc_u32 s24, s23, s24
	s_cmpk_eq_i32 s54, 0xf00
	s_cselect_b32 s59, s6, s1
	s_cselect_b32 s58, s7, s0
	s_cselect_b32 s57, s16, s24
	s_cselect_b32 s56, s18, s17
	v_lshl_add_u64 v[168:169], v[158:159], 0, s[54:55]
	s_add_i32 m0, s61, 0xc000
	ds_read_b128 v[204:207], v173
	ds_read_b128 v[208:211], v173 offset:1024
	ds_read_b128 v[212:215], v173 offset:2048
	ds_read_b128 v[216:219], v173 offset:3072
	ds_read_b128 v[220:223], v173 offset:4096
	ds_read_b128 v[224:227], v173 offset:5120
	ds_read_b128 v[228:231], v173 offset:6144
	ds_read_b128 v[232:235], v173 offset:7168
	global_load_lds_dwordx4 v[168:169], off
	v_lshl_add_u64 v[168:169], v[162:163], 0, s[54:55]
	s_add_i32 m0, s61, 0xe000
	s_nop 0
	global_load_lds_dwordx4 v[168:169], off
	s_waitcnt vmcnt(8)
	s_waitcnt lgkmcnt(0)
	s_setprio 1
	s_barrier

; #define PG8_STAGE(bufoff, gbase, voff) do { _Pragma("unroll") for (int _i = 0; _i < 2; ++_i) \
;         __builtin_amdgcn_global_load_lds((const unsigned*)((const char*)(gbase) + (voff)[_i]), (LAS unsigned*)(lds + (bufoff) + ldsw + _i * 8192), 16, 0, 0); } while (0)
; #define PG8_LDA(dst, b, h) do { _Pragma("unroll") for (int m = 0; m < 4; ++m) _Pragma("unroll") for (int k = 0; k < 2; ++k) dst[m][k] = *(const LAS bf16x8*)(lds + PG8_SA(b, h) + aoff + m * 2048 + k * 1024); } while (0)
; #define PG8_MMA(ai, bj, At, Bt) do { __builtin_amdgcn_s_setprio(1); _Pragma("unroll") for (int m = 0; m < 4; ++m) _Pragma("unroll") for (int n = 0; n < 2; ++n) _Pragma("unroll") for (int k = 0; k < 2; ++k) \
;         acc[ai][bj][m][n] = __builtin_amdgcn_mfma_f32_16x16x32_bf16(Bt[n][k], At[m][k], acc[ai][bj][m][n], 0, 0, 0); __builtin_amdgcn_s_setprio(0); } while (0)
; #define PG8_WAIT_V(n) asm volatile("s_waitcnt vmcnt(" #n ")" ::: "memory")
; #define PG8_WAIT_L(n) asm volatile("s_waitcnt lgkmcnt(" #n ")" ::: "memory")
; #define PG8_BAR __builtin_amdgcn_s_barrier()
; #define PG8_SCHED __builtin_amdgcn_sched_barrier(0)
; template <class Epi>
; __device__ __forceinline__ void gemm_phase(LAS unsigned char* lds, const Gemm g, const StaticOrder& S, const Epi& E) {
;     ...
;             PG8_WAIT_V(8); PG8_WAIT_L(0); PG8_BAR; PG8_MMA(0, 0, At, B0); PG8_MMA(0, 1, At, B1); PG8_BAR; PG8_SCHED;
;             PG8_LDA(At, 0, 1); PG8_STAGE(PG8_SB(0, 0), b2, voffB); PG8_STAGE(PG8_SB(0, 1), b2 + hsB, voffB); PG8_STAGE(PG8_SA(0, 0), a2, voffA);
;             PG8_WAIT_V(8); PG8_WAIT_L(0); PG8_BAR; PG8_MMA(1, 0, At, B0); PG8_MMA(1, 1, At, B1); PG8_BAR; PG8_SCHED;
	v_mfma_f32_16x16x32_bf16 v[124:127], v[128:131], v[204:207], v[124:127]
	v_mfma_f32_16x16x32_bf16 v[120:123], v[164:167], v[204:207], v[120:123]
	v_mfma_f32_16x16x32_bf16 v[108:111], v[128:131], v[212:215], v[108:111]
	v_mfma_f32_16x16x32_bf16 v[104:107], v[164:167], v[212:215], v[104:107]
	v_mfma_f32_16x16x32_bf16 v[92:95], v[128:131], v[220:223], v[92:95]
	v_mfma_f32_16x16x32_bf16 v[88:91], v[164:167], v[220:223], v[88:91]
	v_mfma_f32_16x16x32_bf16 v[76:79], v[128:131], v[228:231], v[76:79]
	v_mfma_f32_16x16x32_bf16 v[72:75], v[164:167], v[228:231], v[72:75]
	v_mfma_f32_16x16x32_bf16 v[124:127], v[132:135], v[208:211], v[124:127]
	v_mfma_f32_16x16x32_bf16 v[120:123], v[184:187], v[208:211], v[120:123]
	v_mfma_f32_16x16x32_bf16 v[108:111], v[132:135], v[216:219], v[108:111]
	v_mfma_f32_16x16x32_bf16 v[104:107], v[184:187], v[216:219], v[104:107]
	v_mfma_f32_16x16x32_bf16 v[92:95], v[132:135], v[224:227], v[92:95]
	v_mfma_f32_16x16x32_bf16 v[88:91], v[184:187], v[224:227], v[88:91]
	v_mfma_f32_16x16x32_bf16 v[76:79], v[132:135], v[232:235], v[76:79]
	v_mfma_f32_16x16x32_bf16 v[72:75], v[184:187], v[232:235], v[72:75]
	s_setprio 0
	s_setprio 1
	v_mfma_f32_16x16x32_bf16 v[116:119], v[188:191], v[204:207], v[116:119]
	v_mfma_f32_16x16x32_bf16 v[112:115], v[196:199], v[204:207], v[112:115]
	v_mfma_f32_16x16x32_bf16 v[100:103], v[188:191], v[212:215], v[100:103]
	v_mfma_f32_16x16x32_bf16 v[96:99], v[196:199], v[212:215], v[96:99]
	v_mfma_f32_16x16x32_bf16 v[84:87], v[188:191], v[220:223], v[84:87]
	v_mfma_f32_16x16x32_bf16 v[80:83], v[196:199], v[220:223], v[80:83]
	v_mfma_f32_16x16x32_bf16 v[68:71], v[188:191], v[228:231], v[68:71]
	v_mfma_f32_16x16x32_bf16 v[64:67], v[196:199], v[228:231], v[64:67]
	v_mfma_f32_16x16x32_bf16 v[116:119], v[192:195], v[208:211], v[116:119]
	v_mfma_f32_16x16x32_bf16 v[112:115], v[200:203], v[208:211], v[112:115]
	v_mfma_f32_16x16x32_bf16 v[100:103], v[192:195], v[216:219], v[100:103]
	v_mfma_f32_16x16x32_bf16 v[96:99], v[200:203], v[216:219], v[96:99]
	v_mfma_f32_16x16x32_bf16 v[84:87], v[192:195], v[224:227], v[84:87]
	v_mfma_f32_16x16x32_bf16 v[80:83], v[200:203], v[224:227], v[80:83]
	v_mfma_f32_16x16x32_bf16 v[68:71], v[192:195], v[232:235], v[68:71]
	v_mfma_f32_16x16x32_bf16 v[64:67], v[200:203], v[232:235], v[64:67]
	s_setprio 0
	s_barrier
	s_add_i32 s0, s74, s60
	v_lshl_add_u64 v[168:169], s[56:57], 0, v[138:139]
	s_mov_b32 m0, s0
	ds_read_b128 v[204:207], v173 offset:16384
	ds_read_b128 v[208:211], v173 offset:17408
	ds_read_b128 v[212:215], v173 offset:18432
	ds_read_b128 v[216:219], v173 offset:19456
	ds_read_b128 v[220:223], v173 offset:20480
	ds_read_b128 v[224:227], v173 offset:21504
	ds_read_b128 v[228:231], v173 offset:22528
	ds_read_b128 v[232:235], v173 offset:23552
	global_load_lds_dwordx4 v[168:169], off
	s_add_i32 m0, s0, 0x2000
	s_add_u32 s0, s56, 0x40000
	v_lshl_add_u64 v[236:237], s[56:57], 0, v[142:143]
	s_addc_u32 s1, s57, 0
	s_add_i32 s17, s75, s60
	global_load_lds_dwordx4 v[236:237], off
	v_lshl_add_u64 v[238:239], s[0:1], 0, v[138:139]
	s_mov_b32 m0, s17
	v_lshl_add_u64 v[240:241], s[58:59], 0, v[140:141]
	global_load_lds_dwordx4 v[238:239], off
	v_lshl_add_u64 v[238:239], s[0:1], 0, v[142:143]
	s_add_i32 m0, s17, 0x2000
	s_nop 0
	global_load_lds_dwordx4 v[238:239], off
	v_lshl_add_u64 v[238:239], s[58:59], 0, v[136:137]
	s_mov_b32 m0, s61
	s_nop 0
	global_load_lds_dwordx4 v[238:239], off
	s_mov_b32 m0, s4
	s_nop 0
	global_load_lds_dwordx4 v[240:241], off
	s_waitcnt vmcnt(8)
	s_waitcnt lgkmcnt(0)
	s_setprio 1
	s_barrier

; #define PG8_STAGE(bufoff, gbase, voff) do { _Pragma("unroll") for (int _i = 0; _i < 2; ++_i) \
;         __builtin_amdgcn_global_load_lds((const unsigned*)((const char*)(gbase) + (voff)[_i]), (LAS unsigned*)(lds + (bufoff) + ldsw + _i * 8192), 16, 0, 0); } while (0)
; #define PG8_LDA(dst, b, h) do { _Pragma("unroll") for (int m = 0; m < 4; ++m) _Pragma("unroll") for (int k = 0; k < 2; ++k) dst[m][k] = *(const LAS bf16x8*)(lds + PG8_SA(b, h) + aoff + m * 2048 + k * 1024); } while (0)
; #define PG8_LDB(dst, b, h) do { _Pragma("unroll") for (int n = 0; n < 2; ++n) _Pragma("unroll") for (int k = 0; k < 2; ++k) dst[n][k] = *(const LAS bf16x8*)(lds + PG8_SB(b, h) + boff + n * 2048 + k * 1024); } while (0)
; #define PG8_MMA(ai, bj, At, Bt) do { __builtin_amdgcn_s_setprio(1); _Pragma("unroll") for (int m = 0; m < 4; ++m) _Pragma("unroll") for (int n = 0; n < 2; ++n) _Pragma("unroll") for (int k = 0; k < 2; ++k) \
;         acc[ai][bj][m][n] = __builtin_amdgcn_mfma_f32_16x16x32_bf16(Bt[n][k], At[m][k], acc[ai][bj][m][n], 0, 0, 0); __builtin_amdgcn_s_setprio(0); } while (0)
; #define PG8_WAIT_V(n) asm volatile("s_waitcnt vmcnt(" #n ")" ::: "memory")
; #define PG8_WAIT_L(n) asm volatile("s_waitcnt lgkmcnt(" #n ")" ::: "memory")
; #define PG8_BAR __builtin_amdgcn_s_barrier()
; #define PG8_SCHED __builtin_amdgcn_sched_barrier(0)
; template <class Epi>
; __device__ __forceinline__ void gemm_phase(LAS unsigned char* lds, const Gemm g, const StaticOrder& S, const Epi& E) {
;     ...
;             PG8_WAIT_V(8); PG8_WAIT_L(0); PG8_BAR; PG8_MMA(1, 0, At, B0); PG8_MMA(1, 1, At, B1); PG8_BAR; PG8_SCHED;
;             PG8_LDB(B0, 1, 0); PG8_LDB(B1, 1, 1); PG8_SCHED; PG8_LDA(At, 1, 0); PG8_STAGE(PG8_SA(0, 1), a2 + hsA, voffA);
;             PG8_WAIT_V(8); PG8_WAIT_L(0); PG8_BAR; PG8_MMA(0, 0, At, B0); PG8_MMA(0, 1, At, B1); PG8_BAR; PG8_SCHED;
	v_mfma_f32_16x16x32_bf16 v[60:63], v[128:131], v[204:207], v[60:63]
	v_mfma_f32_16x16x32_bf16 v[56:59], v[164:167], v[204:207], v[56:59]
	v_mfma_f32_16x16x32_bf16 v[44:47], v[128:131], v[212:215], v[44:47]
	v_mfma_f32_16x16x32_bf16 v[40:43], v[164:167], v[212:215], v[40:43]
	v_mfma_f32_16x16x32_bf16 v[28:31], v[128:131], v[220:223], v[28:31]
	v_mfma_f32_16x16x32_bf16 v[24:27], v[164:167], v[220:223], v[24:27]
	v_mfma_f32_16x16x32_bf16 v[12:15], v[128:131], v[228:231], v[12:15]
	v_mfma_f32_16x16x32_bf16 v[8:11], v[164:167], v[228:231], v[8:11]
	v_mfma_f32_16x16x32_bf16 v[60:63], v[132:135], v[208:211], v[60:63]
	v_mfma_f32_16x16x32_bf16 v[56:59], v[184:187], v[208:211], v[56:59]
	v_mfma_f32_16x16x32_bf16 v[44:47], v[132:135], v[216:219], v[44:47]
	v_mfma_f32_16x16x32_bf16 v[40:43], v[184:187], v[216:219], v[40:43]
	v_mfma_f32_16x16x32_bf16 v[28:31], v[132:135], v[224:227], v[28:31]
	v_mfma_f32_16x16x32_bf16 v[24:27], v[184:187], v[224:227], v[24:27]
	v_mfma_f32_16x16x32_bf16 v[12:15], v[132:135], v[232:235], v[12:15]
	v_mfma_f32_16x16x32_bf16 v[8:11], v[184:187], v[232:235], v[8:11]
	s_setprio 0
	s_setprio 1
	v_mfma_f32_16x16x32_bf16 v[52:55], v[188:191], v[204:207], v[52:55]
	v_mfma_f32_16x16x32_bf16 v[48:51], v[196:199], v[204:207], v[48:51]
	v_mfma_f32_16x16x32_bf16 v[36:39], v[188:191], v[212:215], v[36:39]
	v_mfma_f32_16x16x32_bf16 v[32:35], v[196:199], v[212:215], v[32:35]
	v_mfma_f32_16x16x32_bf16 v[20:23], v[188:191], v[220:223], v[20:23]
	v_mfma_f32_16x16x32_bf16 v[16:19], v[196:199], v[220:223], v[16:19]
	v_mfma_f32_16x16x32_bf16 v[4:7], v[188:191], v[228:231], v[4:7]
	v_mfma_f32_16x16x32_bf16 v[0:3], v[196:199], v[228:231], v[0:3]
	v_mfma_f32_16x16x32_bf16 v[52:55], v[192:195], v[208:211], v[52:55]
	v_mfma_f32_16x16x32_bf16 v[48:51], v[200:203], v[208:211], v[48:51]
	v_mfma_f32_16x16x32_bf16 v[36:39], v[192:195], v[216:219], v[36:39]
	v_mfma_f32_16x16x32_bf16 v[32:35], v[200:203], v[216:219], v[32:35]
	v_mfma_f32_16x16x32_bf16 v[20:23], v[192:195], v[224:227], v[20:23]
	v_mfma_f32_16x16x32_bf16 v[16:19], v[200:203], v[224:227], v[16:19]
	v_mfma_f32_16x16x32_bf16 v[4:7], v[192:195], v[232:235], v[4:7]
	v_mfma_f32_16x16x32_bf16 v[0:3], v[200:203], v[232:235], v[0:3]
	s_setprio 0
	s_barrier
	s_add_i32 s17, 0, 0x18000
	v_add_u32_e32 v153, s17, v171
	s_add_i32 s24, 0, 0x1c000
	ds_read_b128 v[128:131], v153
	ds_read_b128 v[132:135], v153 offset:1024
	ds_read_b128 v[164:167], v153 offset:2048
	ds_read_b128 v[184:187], v153 offset:3072
	v_add_u32_e32 v153, s24, v171
	ds_read_b128 v[188:191], v153
	ds_read_b128 v[192:195], v153 offset:1024
	ds_read_b128 v[196:199], v153 offset:2048
	ds_read_b128 v[200:203], v153 offset:3072
	s_add_u32 s0, s58, 0x100000
	s_addc_u32 s1, s59, 0
	s_mov_b32 m0, s5
	v_lshl_add_u64 v[242:243], s[0:1], 0, v[136:137]
	ds_read_b128 v[204:207], v173 offset:32768
	ds_read_b128 v[208:211], v173 offset:33792
	ds_read_b128 v[212:215], v173 offset:34816
	ds_read_b128 v[216:219], v173 offset:35840
	ds_read_b128 v[220:223], v173 offset:36864
	ds_read_b128 v[224:227], v173 offset:37888
	ds_read_b128 v[228:231], v173 offset:38912
	ds_read_b128 v[232:235], v173 offset:39936
	global_load_lds_dwordx4 v[242:243], off
	v_lshl_add_u64 v[242:243], s[0:1], 0, v[140:141]
	s_mov_b32 m0, s62
	s_nop 0
	global_load_lds_dwordx4 v[242:243], off
	s_waitcnt vmcnt(8)
	s_waitcnt lgkmcnt(0)
	s_setprio 1
	s_barrier

; #define PG8_STAGE(bufoff, gbase, voff) do { _Pragma("unroll") for (int _i = 0; _i < 2; ++_i) \
;         __builtin_amdgcn_global_load_lds((const unsigned*)((const char*)(gbase) + (voff)[_i]), (LAS unsigned*)(lds + (bufoff) + ldsw + _i * 8192), 16, 0, 0); } while (0)
; #define PG8_LDA(dst, b, h) do { _Pragma("unroll") for (int m = 0; m < 4; ++m) _Pragma("unroll") for (int k = 0; k < 2; ++k) dst[m][k] = *(const LAS bf16x8*)(lds + PG8_SA(b, h) + aoff + m * 2048 + k * 1024); } while (0)
; #define PG8_MMA(ai, bj, At, Bt) do { __builtin_amdgcn_s_setprio(1); _Pragma("unroll") for (int m = 0; m < 4; ++m) _Pragma("unroll") for (int n = 0; n < 2; ++n) _Pragma("unroll") for (int k = 0; k < 2; ++k) \
;         acc[ai][bj][m][n] = __builtin_amdgcn_mfma_f32_16x16x32_bf16(Bt[n][k], At[m][k], acc[ai][bj][m][n], 0, 0, 0); __builtin_amdgcn_s_setprio(0); } while (0)
; #define PG8_WAIT_V(n) asm volatile("s_waitcnt vmcnt(" #n ")" ::: "memory")
; #define PG8_WAIT_L(n) asm volatile("s_waitcnt lgkmcnt(" #n ")" ::: "memory")
; #define PG8_BAR __builtin_amdgcn_s_barrier()
; #define PG8_SCHED __builtin_amdgcn_sched_barrier(0)
; template <class Epi>
; __device__ __forceinline__ void gemm_phase(LAS unsigned char* lds, const Gemm g, const StaticOrder& S, const Epi& E) {
;     ...
;             PG8_WAIT_V(8); PG8_WAIT_L(0); PG8_BAR; PG8_MMA(0, 0, At, B0); PG8_MMA(0, 1, At, B1); PG8_BAR; PG8_SCHED;
;             PG8_LDA(At, 1, 1); PG8_STAGE(PG8_SB(1, 0), b3, voffB); PG8_STAGE(PG8_SB(1, 1), b3 + hsB, voffB); PG8_STAGE(PG8_SA(1, 0), a3, voffA);
;             PG8_WAIT_V(8); PG8_WAIT_L(0); PG8_BAR; PG8_MMA(1, 0, At, B0); PG8_MMA(1, 1, At, B1); PG8_BAR; PG8_SCHED;
	v_mfma_f32_16x16x32_bf16 v[124:127], v[128:131], v[204:207], v[124:127]
	v_mfma_f32_16x16x32_bf16 v[120:123], v[164:167], v[204:207], v[120:123]
	v_mfma_f32_16x16x32_bf16 v[108:111], v[128:131], v[212:215], v[108:111]
	v_mfma_f32_16x16x32_bf16 v[104:107], v[164:167], v[212:215], v[104:107]
	v_mfma_f32_16x16x32_bf16 v[92:95], v[128:131], v[220:223], v[92:95]
	v_mfma_f32_16x16x32_bf16 v[88:91], v[164:167], v[220:223], v[88:91]
	v_mfma_f32_16x16x32_bf16 v[76:79], v[128:131], v[228:231], v[76:79]
	v_mfma_f32_16x16x32_bf16 v[72:75], v[164:167], v[228:231], v[72:75]
	v_mfma_f32_16x16x32_bf16 v[124:127], v[132:135], v[208:211], v[124:127]
	v_mfma_f32_16x16x32_bf16 v[120:123], v[184:187], v[208:211], v[120:123]
	v_mfma_f32_16x16x32_bf16 v[108:111], v[132:135], v[216:219], v[108:111]
	v_mfma_f32_16x16x32_bf16 v[104:107], v[184:187], v[216:219], v[104:107]
	v_mfma_f32_16x16x32_bf16 v[92:95], v[132:135], v[224:227], v[92:95]
	v_mfma_f32_16x16x32_bf16 v[88:91], v[184:187], v[224:227], v[88:91]
	v_mfma_f32_16x16x32_bf16 v[76:79], v[132:135], v[232:235], v[76:79]
	v_mfma_f32_16x16x32_bf16 v[72:75], v[184:187], v[232:235], v[72:75]
	s_setprio 0
	s_setprio 1
	v_mfma_f32_16x16x32_bf16 v[116:119], v[188:191], v[204:207], v[116:119]
	v_mfma_f32_16x16x32_bf16 v[112:115], v[196:199], v[204:207], v[112:115]
	v_mfma_f32_16x16x32_bf16 v[100:103], v[188:191], v[212:215], v[100:103]
	v_mfma_f32_16x16x32_bf16 v[96:99], v[196:199], v[212:215], v[96:99]
	v_mfma_f32_16x16x32_bf16 v[84:87], v[188:191], v[220:223], v[84:87]
	v_mfma_f32_16x16x32_bf16 v[80:83], v[196:199], v[220:223], v[80:83]
	v_mfma_f32_16x16x32_bf16 v[68:71], v[188:191], v[228:231], v[68:71]
	v_mfma_f32_16x16x32_bf16 v[64:67], v[196:199], v[228:231], v[64:67]
	v_mfma_f32_16x16x32_bf16 v[116:119], v[192:195], v[208:211], v[116:119]
	v_mfma_f32_16x16x32_bf16 v[112:115], v[200:203], v[208:211], v[112:115]
	v_mfma_f32_16x16x32_bf16 v[100:103], v[192:195], v[216:219], v[100:103]
	v_mfma_f32_16x16x32_bf16 v[96:99], v[200:203], v[216:219], v[96:99]
	v_mfma_f32_16x16x32_bf16 v[84:87], v[192:195], v[224:227], v[84:87]
	v_mfma_f32_16x16x32_bf16 v[80:83], v[200:203], v[224:227], v[80:83]
	v_mfma_f32_16x16x32_bf16 v[68:71], v[192:195], v[232:235], v[68:71]
	v_mfma_f32_16x16x32_bf16 v[64:67], v[200:203], v[232:235], v[64:67]
	s_setprio 0
	s_barrier
	s_add_i32 s0, s17, s60
	v_lshl_add_u64 v[168:169], v[168:169], 0, s[10:11]
	s_mov_b32 m0, s0
	ds_read_b128 v[204:207], v173 offset:49152
	ds_read_b128 v[208:211], v173 offset:50176
	ds_read_b128 v[212:215], v173 offset:51200
	ds_read_b128 v[216:219], v173 offset:52224
	ds_read_b128 v[220:223], v173 offset:53248
	ds_read_b128 v[224:227], v173 offset:54272
	ds_read_b128 v[228:231], v173 offset:55296
	ds_read_b128 v[232:235], v173 offset:56320
	global_load_lds_dwordx4 v[168:169], off
	s_add_i32 m0, s0, 0x2000
	s_add_u32 s0, s56, 0x40080
	v_lshl_add_u64 v[168:169], v[236:237], 0, s[10:11]
	s_addc_u32 s1, s57, 0
	s_add_i32 s17, s24, s60
	global_load_lds_dwordx4 v[168:169], off
	v_lshl_add_u64 v[168:169], s[0:1], 0, v[138:139]
	s_mov_b32 m0, s17
	s_nop 0
	global_load_lds_dwordx4 v[168:169], off
	v_lshl_add_u64 v[168:169], s[0:1], 0, v[142:143]
	s_add_i32 m0, s17, 0x2000
	s_nop 0
	global_load_lds_dwordx4 v[168:169], off
	v_lshl_add_u64 v[168:169], v[238:239], 0, s[10:11]
	s_mov_b32 m0, s64
	s_nop 0
	global_load_lds_dwordx4 v[168:169], off
	v_lshl_add_u64 v[168:169], v[240:241], 0, s[10:11]
	s_mov_b32 m0, s65
	s_nop 0
	global_load_lds_dwordx4 v[168:169], off
	s_waitcnt vmcnt(8)
	s_waitcnt lgkmcnt(0)
	s_setprio 1
	s_barrier

; #define PG8_STAGE(bufoff, gbase, voff) do { _Pragma("unroll") for (int _i = 0; _i < 2; ++_i) \
;         __builtin_amdgcn_global_load_lds((const unsigned*)((const char*)(gbase) + (voff)[_i]), (LAS unsigned*)(lds + (bufoff) + ldsw + _i * 8192), 16, 0, 0); } while (0)
; #define PG8_LDA(dst, b, h) do { _Pragma("unroll") for (int m = 0; m < 4; ++m) _Pragma("unroll") for (int k = 0; k < 2; ++k) dst[m][k] = *(const LAS bf16x8*)(lds + PG8_SA(b, h) + aoff + m * 2048 + k * 1024); } while (0)
; #define PG8_WAIT_V(n) asm volatile("s_waitcnt vmcnt(" #n ")" ::: "memory")
; #define PG8_WAIT_L(n) asm volatile("s_waitcnt lgkmcnt(" #n ")" ::: "memory")
; template <class Epi>
; __device__ __forceinline__ void gemm_phase(LAS unsigned char* lds, const Gemm g, const StaticOrder& S, const Epi& E) {
;     ...
;         for (int t = 0; t < nt; t += 2) {
;             const bool last = (t == nt - 2);
;             if constexpr (Epi::HAS_MID) { if (t == nt1) E.mid(acc, cur, wr, wc, fr, fq); }
;             const char* a1 = cA + ((Epi::HAS_MID && t >= nt1) ? dA2 : 0) + (size_t)(t + 1) * kstep;
;             const char* a2 = last ? nA : cA + ((Epi::HAS_MID && t + 2 >= nt1) ? dA2 : 0) + (size_t)(t + 2) * kstep; const char* b2 = last ? nB : cB + ((Epi::HAS_MID && t + 2 >= nt1) ? dB2 : 0) + (size_t)(t + 2) * kstep;
;             const char* a3 = a2 + kstep; const char* b3 = b2 + kstep;
;             PG8_LDB(B0, 0, 0); PG8_LDB(B1, 0, 1); PG8_SCHED; PG8_LDA(At, 0, 0); PG8_STAGE(PG8_SA(1, 1), a1 + hsA, voffA);
;             PG8_WAIT_V(8); PG8_WAIT_L(0); PG8_BAR; PG8_MMA(0, 0, At, B0); PG8_MMA(0, 1, At, B1); PG8_BAR; PG8_SCHED;
;             PG8_LDA(At, 0, 1); PG8_STAGE(PG8_SB(0, 0), b2, voffB); PG8_STAGE(PG8_SB(0, 1), b2 + hsB, voffB); PG8_STAGE(PG8_SA(0, 0), a2, voffA);
;             PG8_WAIT_V(8); PG8_WAIT_L(0); PG8_BAR; PG8_MMA(1, 0, At, B0); PG8_MMA(1, 1, At, B1); PG8_BAR; PG8_SCHED;
;             PG8_LDB(B0, 1, 0); PG8_LDB(B1, 1, 1); PG8_SCHED; PG8_LDA(At, 1, 0); PG8_STAGE(PG8_SA(0, 1), a2 + hsA, voffA);
;             PG8_WAIT_V(8); PG8_WAIT_L(0); PG8_BAR; PG8_MMA(0, 0, At, B0); PG8_MMA(0, 1, At, B1); PG8_BAR; PG8_SCHED;
;             PG8_LDA(At, 1, 1); PG8_STAGE(PG8_SB(1, 0), b3, voffB); PG8_STAGE(PG8_SB(1, 1), b3 + hsB, voffB); PG8_STAGE(PG8_SA(1, 0), a3, voffA);
;             PG8_WAIT_V(8); PG8_WAIT_L(0); PG8_BAR; PG8_MMA(1, 0, At, B0); PG8_MMA(1, 1, At, B1); PG8_BAR; PG8_SCHED;
;         }
	v_mfma_f32_16x16x32_bf16 v[60:63], v[128:131], v[204:207], v[60:63]
	v_mfma_f32_16x16x32_bf16 v[56:59], v[164:167], v[204:207], v[56:59]
	v_mfma_f32_16x16x32_bf16 v[44:47], v[128:131], v[212:215], v[44:47]
	v_mfma_f32_16x16x32_bf16 v[40:43], v[164:167], v[212:215], v[40:43]
	v_mfma_f32_16x16x32_bf16 v[28:31], v[128:131], v[220:223], v[28:31]
	v_mfma_f32_16x16x32_bf16 v[24:27], v[164:167], v[220:223], v[24:27]
	v_mfma_f32_16x16x32_bf16 v[12:15], v[128:131], v[228:231], v[12:15]
	v_mfma_f32_16x16x32_bf16 v[8:11], v[164:167], v[228:231], v[8:11]
	v_mfma_f32_16x16x32_bf16 v[60:63], v[132:135], v[208:211], v[60:63]
	v_mfma_f32_16x16x32_bf16 v[56:59], v[184:187], v[208:211], v[56:59]
	v_mfma_f32_16x16x32_bf16 v[44:47], v[132:135], v[216:219], v[44:47]
	v_mfma_f32_16x16x32_bf16 v[40:43], v[184:187], v[216:219], v[40:43]
	v_mfma_f32_16x16x32_bf16 v[28:31], v[132:135], v[224:227], v[28:31]
	v_mfma_f32_16x16x32_bf16 v[24:27], v[184:187], v[224:227], v[24:27]
	v_mfma_f32_16x16x32_bf16 v[12:15], v[132:135], v[232:235], v[12:15]
	v_mfma_f32_16x16x32_bf16 v[8:11], v[184:187], v[232:235], v[8:11]
	s_setprio 0
	s_setprio 1
	v_mfma_f32_16x16x32_bf16 v[52:55], v[188:191], v[204:207], v[52:55]
	v_mfma_f32_16x16x32_bf16 v[48:51], v[196:199], v[204:207], v[48:51]
	v_mfma_f32_16x16x32_bf16 v[36:39], v[188:191], v[212:215], v[36:39]
	v_mfma_f32_16x16x32_bf16 v[32:35], v[196:199], v[212:215], v[32:35]
	v_mfma_f32_16x16x32_bf16 v[20:23], v[188:191], v[220:223], v[20:23]
	v_mfma_f32_16x16x32_bf16 v[16:19], v[196:199], v[220:223], v[16:19]
	v_mfma_f32_16x16x32_bf16 v[4:7], v[188:191], v[228:231], v[4:7]
	v_mfma_f32_16x16x32_bf16 v[0:3], v[196:199], v[228:231], v[0:3]
	v_mfma_f32_16x16x32_bf16 v[52:55], v[192:195], v[208:211], v[52:55]
	v_mfma_f32_16x16x32_bf16 v[48:51], v[200:203], v[208:211], v[48:51]
	v_mfma_f32_16x16x32_bf16 v[36:39], v[192:195], v[216:219], v[36:39]
	v_mfma_f32_16x16x32_bf16 v[32:35], v[200:203], v[216:219], v[32:35]
	v_mfma_f32_16x16x32_bf16 v[20:23], v[192:195], v[224:227], v[20:23]
	v_mfma_f32_16x16x32_bf16 v[16:19], v[200:203], v[224:227], v[16:19]
	v_mfma_f32_16x16x32_bf16 v[4:7], v[192:195], v[232:235], v[4:7]
	v_mfma_f32_16x16x32_bf16 v[0:3], v[200:203], v[232:235], v[0:3]
	s_setprio 0
	s_barrier
	s_add_u32 s54, s54, 0x100
	s_addc_u32 s55, 0, s55
	s_cmp_gt_u32 s33, 29
	s_cbranch_scc1 .LBB0_1086

; #define PG8_STAGE(bufoff, gbase, voff) do { _Pragma("unroll") for (int _i = 0; _i < 2; ++_i) \
;         __builtin_amdgcn_global_load_lds((const unsigned*)((const char*)(gbase) + (voff)[_i]), (LAS unsigned*)(lds + (bufoff) + ldsw + _i * 8192), 16, 0, 0); } while (0)
; #define PG8_LDA(dst, b, h) do { _Pragma("unroll") for (int m = 0; m < 4; ++m) _Pragma("unroll") for (int k = 0; k < 2; ++k) dst[m][k] = *(const LAS bf16x8*)(lds + PG8_SA(b, h) + aoff + m * 2048 + k * 1024); } while (0)
; #define PG8_LDB(dst, b, h) do { _Pragma("unroll") for (int n = 0; n < 2; ++n) _Pragma("unroll") for (int k = 0; k < 2; ++k) dst[n][k] = *(const LAS bf16x8*)(lds + PG8_SB(b, h) + boff + n * 2048 + k * 1024); } while (0)
; #define PG8_MMA(ai, bj, At, Bt) do { __builtin_amdgcn_s_setprio(1); _Pragma("unroll") for (int m = 0; m < 4; ++m) _Pragma("unroll") for (int n = 0; n < 2; ++n) _Pragma("unroll") for (int k = 0; k < 2; ++k) \
;         acc[ai][bj][m][n] = __builtin_amdgcn_mfma_f32_16x16x32_bf16(Bt[n][k], At[m][k], acc[ai][bj][m][n], 0, 0, 0); __builtin_amdgcn_s_setprio(0); } while (0)
; #define PG8_WAIT_V(n) asm volatile("s_waitcnt vmcnt(" #n ")" ::: "memory")
; #define PG8_WAIT_L(n) asm volatile("s_waitcnt lgkmcnt(" #n ")" ::: "memory")
; #define PG8_BAR __builtin_amdgcn_s_barrier()
; #define PG8_SCHED __builtin_amdgcn_sched_barrier(0)
; template <class Epi>
; __device__ __forceinline__ void gemm_phase(LAS unsigned char* lds, const Gemm g, const StaticOrder& S, const Epi& E) {
;     ...
;             const bool last = (t == nt - 2);
;             if constexpr (Epi::HAS_MID) { if (t == nt1) E.mid(acc, cur, wr, wc, fr, fq); }
;             const char* a1 = cA + ((Epi::HAS_MID && t >= nt1) ? dA2 : 0) + (size_t)(t + 1) * kstep;
;             const char* a2 = last ? nA : cA + ((Epi::HAS_MID && t + 2 >= nt1) ? dA2 : 0) + (size_t)(t + 2) * kstep; const char* b2 = last ? nB : cB + ((Epi::HAS_MID && t + 2 >= nt1) ? dB2 : 0) + (size_t)(t + 2) * kstep;
;             const char* a3 = a2 + kstep; const char* b3 = b2 + kstep;
;             PG8_LDB(B0, 0, 0); PG8_LDB(B1, 0, 1); PG8_SCHED; PG8_LDA(At, 0, 0); PG8_STAGE(PG8_SA(1, 1), a1 + hsA, voffA);
;             PG8_WAIT_V(8); PG8_WAIT_L(0); PG8_BAR; PG8_MMA(0, 0, At, B0); PG8_MMA(0, 1, At, B1); PG8_BAR; PG8_SCHED;
.LBB0_1234:
	ds_read_b128 v[144:147], v155
	ds_read_b128 v[148:151], v155 offset:1024
	ds_read_b128 v[162:165], v155 offset:2048
	ds_read_b128 v[166:169], v155 offset:3072
	ds_read_b128 v[170:173], v156
	ds_read_b128 v[174:177], v156 offset:1024
	ds_read_b128 v[184:187], v156 offset:2048
	ds_read_b128 v[188:191], v156 offset:3072
	s_add_u32 s39, s48, 0xfffc0080
	s_addc_u32 s41, s49, -1
	s_cmp_eq_u32 s35, 12
	s_cselect_b32 s53, s0, s41
	s_cselect_b32 s52, s1, s39
	s_cselect_b32 s51, s6, s34
	s_cselect_b32 s50, s7, s13
	s_add_i32 m0, s5, 0xc000
	ds_read_b128 v[192:195], v157
	ds_read_b128 v[196:199], v157 offset:1024
	ds_read_b128 v[200:203], v157 offset:2048
	ds_read_b128 v[204:207], v157 offset:3072
	ds_read_b128 v[208:211], v157 offset:4096
	ds_read_b128 v[212:215], v157 offset:5120
	ds_read_b128 v[216:219], v157 offset:6144
	ds_read_b128 v[220:223], v157 offset:7168
	global_load_lds_dwordx4 v136, s[48:49]
	s_add_i32 m0, s5, 0xe000
	s_nop 0
	global_load_lds_dwordx4 v138, s[48:49]
	s_waitcnt vmcnt(8)
	s_waitcnt lgkmcnt(0)
	s_setprio 1
	s_barrier

; #define PG8_STAGE(bufoff, gbase, voff) do { _Pragma("unroll") for (int _i = 0; _i < 2; ++_i) \
;         __builtin_amdgcn_global_load_lds((const unsigned*)((const char*)(gbase) + (voff)[_i]), (LAS unsigned*)(lds + (bufoff) + ldsw + _i * 8192), 16, 0, 0); } while (0)
; #define PG8_LDA(dst, b, h) do { _Pragma("unroll") for (int m = 0; m < 4; ++m) _Pragma("unroll") for (int k = 0; k < 2; ++k) dst[m][k] = *(const LAS bf16x8*)(lds + PG8_SA(b, h) + aoff + m * 2048 + k * 1024); } while (0)
; #define PG8_MMA(ai, bj, At, Bt) do { __builtin_amdgcn_s_setprio(1); _Pragma("unroll") for (int m = 0; m < 4; ++m) _Pragma("unroll") for (int n = 0; n < 2; ++n) _Pragma("unroll") for (int k = 0; k < 2; ++k) \
;         acc[ai][bj][m][n] = __builtin_amdgcn_mfma_f32_16x16x32_bf16(Bt[n][k], At[m][k], acc[ai][bj][m][n], 0, 0, 0); __builtin_amdgcn_s_setprio(0); } while (0)
; #define PG8_WAIT_V(n) asm volatile("s_waitcnt vmcnt(" #n ")" ::: "memory")
; #define PG8_WAIT_L(n) asm volatile("s_waitcnt lgkmcnt(" #n ")" ::: "memory")
; #define PG8_BAR __builtin_amdgcn_s_barrier()
; #define PG8_SCHED __builtin_amdgcn_sched_barrier(0)
; template <class Epi>
; __device__ __forceinline__ void gemm_phase(LAS unsigned char* lds, const Gemm g, const StaticOrder& S, const Epi& E) {
;     ...
;             PG8_WAIT_V(8); PG8_WAIT_L(0); PG8_BAR; PG8_MMA(0, 0, At, B0); PG8_MMA(0, 1, At, B1); PG8_BAR; PG8_SCHED;
;             PG8_LDA(At, 0, 1); PG8_STAGE(PG8_SB(0, 0), b2, voffB); PG8_STAGE(PG8_SB(0, 1), b2 + hsB, voffB); PG8_STAGE(PG8_SA(0, 0), a2, voffA);
;             PG8_WAIT_V(8); PG8_WAIT_L(0); PG8_BAR; PG8_MMA(1, 0, At, B0); PG8_MMA(1, 1, At, B1); PG8_BAR; PG8_SCHED;
	v_mfma_f32_16x16x32_bf16 v[124:127], v[144:147], v[192:195], v[124:127]
	v_mfma_f32_16x16x32_bf16 v[120:123], v[162:165], v[192:195], v[120:123]
	v_mfma_f32_16x16x32_bf16 v[108:111], v[144:147], v[200:203], v[108:111]
	v_mfma_f32_16x16x32_bf16 v[104:107], v[162:165], v[200:203], v[104:107]
	v_mfma_f32_16x16x32_bf16 v[92:95], v[144:147], v[208:211], v[92:95]
	v_mfma_f32_16x16x32_bf16 v[88:91], v[162:165], v[208:211], v[88:91]
	v_mfma_f32_16x16x32_bf16 v[76:79], v[144:147], v[216:219], v[76:79]
	v_mfma_f32_16x16x32_bf16 v[72:75], v[162:165], v[216:219], v[72:75]
	v_mfma_f32_16x16x32_bf16 v[124:127], v[148:151], v[196:199], v[124:127]
	v_mfma_f32_16x16x32_bf16 v[120:123], v[166:169], v[196:199], v[120:123]
	v_mfma_f32_16x16x32_bf16 v[108:111], v[148:151], v[204:207], v[108:111]
	v_mfma_f32_16x16x32_bf16 v[104:107], v[166:169], v[204:207], v[104:107]
	v_mfma_f32_16x16x32_bf16 v[92:95], v[148:151], v[212:215], v[92:95]
	v_mfma_f32_16x16x32_bf16 v[88:91], v[166:169], v[212:215], v[88:91]
	v_mfma_f32_16x16x32_bf16 v[76:79], v[148:151], v[220:223], v[76:79]
	v_mfma_f32_16x16x32_bf16 v[72:75], v[166:169], v[220:223], v[72:75]
	s_setprio 0
	s_setprio 1
	v_mfma_f32_16x16x32_bf16 v[116:119], v[170:173], v[192:195], v[116:119]
	v_mfma_f32_16x16x32_bf16 v[112:115], v[184:187], v[192:195], v[112:115]
	v_mfma_f32_16x16x32_bf16 v[100:103], v[170:173], v[200:203], v[100:103]
	v_mfma_f32_16x16x32_bf16 v[96:99], v[184:187], v[200:203], v[96:99]
	v_mfma_f32_16x16x32_bf16 v[84:87], v[170:173], v[208:211], v[84:87]
	v_mfma_f32_16x16x32_bf16 v[80:83], v[184:187], v[208:211], v[80:83]
	v_mfma_f32_16x16x32_bf16 v[68:71], v[170:173], v[216:219], v[68:71]
	v_mfma_f32_16x16x32_bf16 v[64:67], v[184:187], v[216:219], v[64:67]
	v_mfma_f32_16x16x32_bf16 v[116:119], v[174:177], v[196:199], v[116:119]
	v_mfma_f32_16x16x32_bf16 v[112:115], v[188:191], v[196:199], v[112:115]
	v_mfma_f32_16x16x32_bf16 v[100:103], v[174:177], v[204:207], v[100:103]
	v_mfma_f32_16x16x32_bf16 v[96:99], v[188:191], v[204:207], v[96:99]
	v_mfma_f32_16x16x32_bf16 v[84:87], v[174:177], v[212:215], v[84:87]
	v_mfma_f32_16x16x32_bf16 v[80:83], v[188:191], v[212:215], v[80:83]
	v_mfma_f32_16x16x32_bf16 v[68:71], v[174:177], v[220:223], v[68:71]
	v_mfma_f32_16x16x32_bf16 v[64:67], v[188:191], v[220:223], v[64:67]
	s_setprio 0
	s_barrier
	s_add_i32 s39, s31, s4
	s_mov_b32 m0, s39
	ds_read_b128 v[192:195], v157 offset:16384
	ds_read_b128 v[196:199], v157 offset:17408
	ds_read_b128 v[200:203], v157 offset:18432
	ds_read_b128 v[204:207], v157 offset:19456
	ds_read_b128 v[208:211], v157 offset:20480
	ds_read_b128 v[212:215], v157 offset:21504
	ds_read_b128 v[216:219], v157 offset:22528
	ds_read_b128 v[220:223], v157 offset:23552
	global_load_lds_dwordx4 v130, s[50:51]
	s_add_i32 m0, s39, 0x2000
	s_add_u32 s54, s50, 0x40000
	s_addc_u32 s55, s51, 0
	s_add_i32 s39, s33, s4
	global_load_lds_dwordx4 v134, s[50:51]
	s_mov_b32 m0, s39
	s_nop 0
	global_load_lds_dwordx4 v130, s[54:55]
	s_add_i32 m0, s39, 0x2000
	s_nop 0
	global_load_lds_dwordx4 v134, s[54:55]
	s_mov_b32 m0, s5
	s_nop 0
	global_load_lds_dwordx4 v128, s[52:53]
	s_mov_b32 m0, s16
	s_nop 0
	global_load_lds_dwordx4 v132, s[52:53]
	s_waitcnt vmcnt(8)
	s_waitcnt lgkmcnt(0)
	s_setprio 1
	s_barrier

; #define PG8_STAGE(bufoff, gbase, voff) do { _Pragma("unroll") for (int _i = 0; _i < 2; ++_i) \
;         __builtin_amdgcn_global_load_lds((const unsigned*)((const char*)(gbase) + (voff)[_i]), (LAS unsigned*)(lds + (bufoff) + ldsw + _i * 8192), 16, 0, 0); } while (0)
; #define PG8_LDA(dst, b, h) do { _Pragma("unroll") for (int m = 0; m < 4; ++m) _Pragma("unroll") for (int k = 0; k < 2; ++k) dst[m][k] = *(const LAS bf16x8*)(lds + PG8_SA(b, h) + aoff + m * 2048 + k * 1024); } while (0)
; #define PG8_LDB(dst, b, h) do { _Pragma("unroll") for (int n = 0; n < 2; ++n) _Pragma("unroll") for (int k = 0; k < 2; ++k) dst[n][k] = *(const LAS bf16x8*)(lds + PG8_SB(b, h) + boff + n * 2048 + k * 1024); } while (0)
; #define PG8_MMA(ai, bj, At, Bt) do { __builtin_amdgcn_s_setprio(1); _Pragma("unroll") for (int m = 0; m < 4; ++m) _Pragma("unroll") for (int n = 0; n < 2; ++n) _Pragma("unroll") for (int k = 0; k < 2; ++k) \
;         acc[ai][bj][m][n] = __builtin_amdgcn_mfma_f32_16x16x32_bf16(Bt[n][k], At[m][k], acc[ai][bj][m][n], 0, 0, 0); __builtin_amdgcn_s_setprio(0); } while (0)
; #define PG8_WAIT_V(n) asm volatile("s_waitcnt vmcnt(" #n ")" ::: "memory")
; #define PG8_WAIT_L(n) asm volatile("s_waitcnt lgkmcnt(" #n ")" ::: "memory")
; #define PG8_BAR __builtin_amdgcn_s_barrier()
; #define PG8_SCHED __builtin_amdgcn_sched_barrier(0)
; template <class Epi>
; __device__ __forceinline__ void gemm_phase(LAS unsigned char* lds, const Gemm g, const StaticOrder& S, const Epi& E) {
;     ...
;             PG8_WAIT_V(8); PG8_WAIT_L(0); PG8_BAR; PG8_MMA(1, 0, At, B0); PG8_MMA(1, 1, At, B1); PG8_BAR; PG8_SCHED;
;             PG8_LDB(B0, 1, 0); PG8_LDB(B1, 1, 1); PG8_SCHED; PG8_LDA(At, 1, 0); PG8_STAGE(PG8_SA(0, 1), a2 + hsA, voffA);
;             PG8_WAIT_V(8); PG8_WAIT_L(0); PG8_BAR; PG8_MMA(0, 0, At, B0); PG8_MMA(0, 1, At, B1); PG8_BAR; PG8_SCHED;
	v_mfma_f32_16x16x32_bf16 v[60:63], v[144:147], v[192:195], v[60:63]
	v_mfma_f32_16x16x32_bf16 v[56:59], v[162:165], v[192:195], v[56:59]
	v_mfma_f32_16x16x32_bf16 v[44:47], v[144:147], v[200:203], v[44:47]
	v_mfma_f32_16x16x32_bf16 v[40:43], v[162:165], v[200:203], v[40:43]
	v_mfma_f32_16x16x32_bf16 v[28:31], v[144:147], v[208:211], v[28:31]
	v_mfma_f32_16x16x32_bf16 v[24:27], v[162:165], v[208:211], v[24:27]
	v_mfma_f32_16x16x32_bf16 v[12:15], v[144:147], v[216:219], v[12:15]
	v_mfma_f32_16x16x32_bf16 v[8:11], v[162:165], v[216:219], v[8:11]
	v_mfma_f32_16x16x32_bf16 v[60:63], v[148:151], v[196:199], v[60:63]
	v_mfma_f32_16x16x32_bf16 v[56:59], v[166:169], v[196:199], v[56:59]
	v_mfma_f32_16x16x32_bf16 v[44:47], v[148:151], v[204:207], v[44:47]
	v_mfma_f32_16x16x32_bf16 v[40:43], v[166:169], v[204:207], v[40:43]
	v_mfma_f32_16x16x32_bf16 v[28:31], v[148:151], v[212:215], v[28:31]
	v_mfma_f32_16x16x32_bf16 v[24:27], v[166:169], v[212:215], v[24:27]
	v_mfma_f32_16x16x32_bf16 v[12:15], v[148:151], v[220:223], v[12:15]
	v_mfma_f32_16x16x32_bf16 v[8:11], v[166:169], v[220:223], v[8:11]
	s_setprio 0
	s_setprio 1
	v_mfma_f32_16x16x32_bf16 v[52:55], v[170:173], v[192:195], v[52:55]
	v_mfma_f32_16x16x32_bf16 v[48:51], v[184:187], v[192:195], v[48:51]
	v_mfma_f32_16x16x32_bf16 v[36:39], v[170:173], v[200:203], v[36:39]
	v_mfma_f32_16x16x32_bf16 v[32:35], v[184:187], v[200:203], v[32:35]
	v_mfma_f32_16x16x32_bf16 v[20:23], v[170:173], v[208:211], v[20:23]
	v_mfma_f32_16x16x32_bf16 v[16:19], v[184:187], v[208:211], v[16:19]
	v_mfma_f32_16x16x32_bf16 v[4:7], v[170:173], v[216:219], v[4:7]
	v_mfma_f32_16x16x32_bf16 v[0:3], v[184:187], v[216:219], v[0:3]
	v_mfma_f32_16x16x32_bf16 v[52:55], v[174:177], v[196:199], v[52:55]
	v_mfma_f32_16x16x32_bf16 v[48:51], v[188:191], v[196:199], v[48:51]
	v_mfma_f32_16x16x32_bf16 v[36:39], v[174:177], v[204:207], v[36:39]
	v_mfma_f32_16x16x32_bf16 v[32:35], v[188:191], v[204:207], v[32:35]
	v_mfma_f32_16x16x32_bf16 v[20:23], v[174:177], v[212:215], v[20:23]
	v_mfma_f32_16x16x32_bf16 v[16:19], v[188:191], v[212:215], v[16:19]
	v_mfma_f32_16x16x32_bf16 v[4:7], v[174:177], v[220:223], v[4:7]
	v_mfma_f32_16x16x32_bf16 v[0:3], v[188:191], v[220:223], v[0:3]
	s_setprio 0
	s_barrier
	s_add_i32 s39, 0, 0x18000
	v_add_u32_e32 v160, s39, v153
	s_add_i32 s41, 0, 0x1c000
	ds_read_b128 v[144:147], v160
	ds_read_b128 v[148:151], v160 offset:1024
	ds_read_b128 v[162:165], v160 offset:2048
	ds_read_b128 v[166:169], v160 offset:3072
	v_add_u32_e32 v160, s41, v153
	ds_read_b128 v[170:173], v160
	ds_read_b128 v[174:177], v160 offset:1024
	ds_read_b128 v[184:187], v160 offset:2048
	ds_read_b128 v[188:191], v160 offset:3072
	s_add_u32 s52, s52, 0x40000
	s_addc_u32 s53, s53, 0
	s_mov_b32 m0, s17
	ds_read_b128 v[192:195], v157 offset:32768
	ds_read_b128 v[196:199], v157 offset:33792
	ds_read_b128 v[200:203], v157 offset:34816
	ds_read_b128 v[204:207], v157 offset:35840
	ds_read_b128 v[208:211], v157 offset:36864
	ds_read_b128 v[212:215], v157 offset:37888
	ds_read_b128 v[216:219], v157 offset:38912
	ds_read_b128 v[220:223], v157 offset:39936
	global_load_lds_dwordx4 v128, s[52:53]
	s_mov_b32 m0, s18
	s_nop 0
	global_load_lds_dwordx4 v132, s[52:53]
	s_waitcnt vmcnt(8)
	s_waitcnt lgkmcnt(0)
	s_setprio 1
	s_barrier

; #define PG8_STAGE(bufoff, gbase, voff) do { _Pragma("unroll") for (int _i = 0; _i < 2; ++_i) \
;         __builtin_amdgcn_global_load_lds((const unsigned*)((const char*)(gbase) + (voff)[_i]), (LAS unsigned*)(lds + (bufoff) + ldsw + _i * 8192), 16, 0, 0); } while (0)
; #define PG8_LDA(dst, b, h) do { _Pragma("unroll") for (int m = 0; m < 4; ++m) _Pragma("unroll") for (int k = 0; k < 2; ++k) dst[m][k] = *(const LAS bf16x8*)(lds + PG8_SA(b, h) + aoff + m * 2048 + k * 1024); } while (0)
; #define PG8_MMA(ai, bj, At, Bt) do { __builtin_amdgcn_s_setprio(1); _Pragma("unroll") for (int m = 0; m < 4; ++m) _Pragma("unroll") for (int n = 0; n < 2; ++n) _Pragma("unroll") for (int k = 0; k < 2; ++k) \
;         acc[ai][bj][m][n] = __builtin_amdgcn_mfma_f32_16x16x32_bf16(Bt[n][k], At[m][k], acc[ai][bj][m][n], 0, 0, 0); __builtin_amdgcn_s_setprio(0); } while (0)
; #define PG8_WAIT_V(n) asm volatile("s_waitcnt vmcnt(" #n ")" ::: "memory")
; #define PG8_WAIT_L(n) asm volatile("s_waitcnt lgkmcnt(" #n ")" ::: "memory")
; #define PG8_BAR __builtin_amdgcn_s_barrier()
; #define PG8_SCHED __builtin_amdgcn_sched_barrier(0)
; template <class Epi>
; __device__ __forceinline__ void gemm_phase(LAS unsigned char* lds, const Gemm g, const StaticOrder& S, const Epi& E) {
;     ...
;             PG8_WAIT_V(8); PG8_WAIT_L(0); PG8_BAR; PG8_MMA(0, 0, At, B0); PG8_MMA(0, 1, At, B1); PG8_BAR; PG8_SCHED;
;             PG8_LDA(At, 1, 1); PG8_STAGE(PG8_SB(1, 0), b3, voffB); PG8_STAGE(PG8_SB(1, 1), b3 + hsB, voffB); PG8_STAGE(PG8_SA(1, 0), a3, voffA);
;             PG8_WAIT_V(8); PG8_WAIT_L(0); PG8_BAR; PG8_MMA(1, 0, At, B0); PG8_MMA(1, 1, At, B1); PG8_BAR; PG8_SCHED;
	v_mfma_f32_16x16x32_bf16 v[124:127], v[144:147], v[192:195], v[124:127]
	v_mfma_f32_16x16x32_bf16 v[120:123], v[162:165], v[192:195], v[120:123]
	v_mfma_f32_16x16x32_bf16 v[108:111], v[144:147], v[200:203], v[108:111]
	v_mfma_f32_16x16x32_bf16 v[104:107], v[162:165], v[200:203], v[104:107]
	v_mfma_f32_16x16x32_bf16 v[92:95], v[144:147], v[208:211], v[92:95]
	v_mfma_f32_16x16x32_bf16 v[88:91], v[162:165], v[208:211], v[88:91]
	v_mfma_f32_16x16x32_bf16 v[76:79], v[144:147], v[216:219], v[76:79]
	v_mfma_f32_16x16x32_bf16 v[72:75], v[162:165], v[216:219], v[72:75]
	v_mfma_f32_16x16x32_bf16 v[124:127], v[148:151], v[196:199], v[124:127]
	v_mfma_f32_16x16x32_bf16 v[120:123], v[166:169], v[196:199], v[120:123]
	v_mfma_f32_16x16x32_bf16 v[108:111], v[148:151], v[204:207], v[108:111]
	v_mfma_f32_16x16x32_bf16 v[104:107], v[166:169], v[204:207], v[104:107]
	v_mfma_f32_16x16x32_bf16 v[92:95], v[148:151], v[212:215], v[92:95]
	v_mfma_f32_16x16x32_bf16 v[88:91], v[166:169], v[212:215], v[88:91]
	v_mfma_f32_16x16x32_bf16 v[76:79], v[148:151], v[220:223], v[76:79]
	v_mfma_f32_16x16x32_bf16 v[72:75], v[166:169], v[220:223], v[72:75]
	s_setprio 0
	s_setprio 1
	v_mfma_f32_16x16x32_bf16 v[116:119], v[170:173], v[192:195], v[116:119]
	v_mfma_f32_16x16x32_bf16 v[112:115], v[184:187], v[192:195], v[112:115]
	v_mfma_f32_16x16x32_bf16 v[100:103], v[170:173], v[200:203], v[100:103]
	v_mfma_f32_16x16x32_bf16 v[96:99], v[184:187], v[200:203], v[96:99]
	v_mfma_f32_16x16x32_bf16 v[84:87], v[170:173], v[208:211], v[84:87]
	v_mfma_f32_16x16x32_bf16 v[80:83], v[184:187], v[208:211], v[80:83]
	v_mfma_f32_16x16x32_bf16 v[68:71], v[170:173], v[216:219], v[68:71]
	v_mfma_f32_16x16x32_bf16 v[64:67], v[184:187], v[216:219], v[64:67]
	v_mfma_f32_16x16x32_bf16 v[116:119], v[174:177], v[196:199], v[116:119]
	v_mfma_f32_16x16x32_bf16 v[112:115], v[188:191], v[196:199], v[112:115]
	v_mfma_f32_16x16x32_bf16 v[100:103], v[174:177], v[204:207], v[100:103]
	v_mfma_f32_16x16x32_bf16 v[96:99], v[188:191], v[204:207], v[96:99]
	v_mfma_f32_16x16x32_bf16 v[84:87], v[174:177], v[212:215], v[84:87]
	v_mfma_f32_16x16x32_bf16 v[80:83], v[188:191], v[212:215], v[80:83]
	v_mfma_f32_16x16x32_bf16 v[68:71], v[174:177], v[220:223], v[68:71]
	v_mfma_f32_16x16x32_bf16 v[64:67], v[188:191], v[220:223], v[64:67]
	s_setprio 0
	s_barrier
	s_add_u32 s98, s50, 0x80
	s_addc_u32 s99, s51, 0
	s_add_u32 s100, s52, 0xfffc0080
	s_addc_u32 s101, s53, -1
	s_add_i32 s39, s39, s4
	s_mov_b32 m0, s39
	ds_read_b128 v[192:195], v157 offset:49152
	ds_read_b128 v[196:199], v157 offset:50176
	ds_read_b128 v[200:203], v157 offset:51200
	ds_read_b128 v[204:207], v157 offset:52224
	ds_read_b128 v[208:211], v157 offset:53248
	ds_read_b128 v[212:215], v157 offset:54272
	ds_read_b128 v[216:219], v157 offset:55296
	ds_read_b128 v[220:223], v157 offset:56320
	global_load_lds_dwordx4 v130, s[98:99]
	s_add_i32 m0, s39, 0x2000
	s_add_u32 s50, s50, 0x40080
	s_addc_u32 s51, s51, 0
	s_add_i32 s39, s41, s4
	global_load_lds_dwordx4 v134, s[98:99]
	s_mov_b32 m0, s39
	s_nop 0
	global_load_lds_dwordx4 v130, s[50:51]
	s_add_i32 m0, s39, 0x2000
	s_nop 0
	global_load_lds_dwordx4 v134, s[50:51]
	s_mov_b32 m0, s22
	s_nop 0
	global_load_lds_dwordx4 v128, s[100:101]
	s_mov_b32 m0, s23
	s_nop 0
	global_load_lds_dwordx4 v132, s[100:101]
	s_waitcnt vmcnt(8)
	s_waitcnt lgkmcnt(0)
	s_setprio 1
	s_barrier

; #define PG8_MMA(ai, bj, At, Bt) do { __builtin_amdgcn_s_setprio(1); _Pragma("unroll") for (int m = 0; m < 4; ++m) _Pragma("unroll") for (int n = 0; n < 2; ++n) _Pragma("unroll") for (int k = 0; k < 2; ++k) \
;         acc[ai][bj][m][n] = __builtin_amdgcn_mfma_f32_16x16x32_bf16(Bt[n][k], At[m][k], acc[ai][bj][m][n], 0, 0, 0); __builtin_amdgcn_s_setprio(0); } while (0)
; #define PG8_WAIT_V(n) asm volatile("s_waitcnt vmcnt(" #n ")" ::: "memory")
; #define PG8_WAIT_L(n) asm volatile("s_waitcnt lgkmcnt(" #n ")" ::: "memory")
; #define PG8_BAR __builtin_amdgcn_s_barrier()
; #define PG8_SCHED __builtin_amdgcn_sched_barrier(0)
; template <class Epi>
; __device__ __forceinline__ void gemm_phase(LAS unsigned char* lds, const Gemm g, const StaticOrder& S, const Epi& E) {
;     ...
;             PG8_WAIT_V(8); PG8_WAIT_L(0); PG8_BAR; PG8_MMA(1, 0, At, B0); PG8_MMA(1, 1, At, B1); PG8_BAR; PG8_SCHED;
;         }
;         if (wr == 0) PG8_BAR;
	v_mfma_f32_16x16x32_bf16 v[60:63], v[144:147], v[192:195], v[60:63]
	v_mfma_f32_16x16x32_bf16 v[56:59], v[162:165], v[192:195], v[56:59]
	v_mfma_f32_16x16x32_bf16 v[44:47], v[144:147], v[200:203], v[44:47]
	v_mfma_f32_16x16x32_bf16 v[40:43], v[162:165], v[200:203], v[40:43]
	v_mfma_f32_16x16x32_bf16 v[28:31], v[144:147], v[208:211], v[28:31]
	v_mfma_f32_16x16x32_bf16 v[24:27], v[162:165], v[208:211], v[24:27]
	v_mfma_f32_16x16x32_bf16 v[12:15], v[144:147], v[216:219], v[12:15]
	v_mfma_f32_16x16x32_bf16 v[8:11], v[162:165], v[216:219], v[8:11]
	v_mfma_f32_16x16x32_bf16 v[60:63], v[148:151], v[196:199], v[60:63]
	v_mfma_f32_16x16x32_bf16 v[56:59], v[166:169], v[196:199], v[56:59]
	v_mfma_f32_16x16x32_bf16 v[44:47], v[148:151], v[204:207], v[44:47]
	v_mfma_f32_16x16x32_bf16 v[40:43], v[166:169], v[204:207], v[40:43]
	v_mfma_f32_16x16x32_bf16 v[28:31], v[148:151], v[212:215], v[28:31]
	v_mfma_f32_16x16x32_bf16 v[24:27], v[166:169], v[212:215], v[24:27]
	v_mfma_f32_16x16x32_bf16 v[12:15], v[148:151], v[220:223], v[12:15]
	v_mfma_f32_16x16x32_bf16 v[8:11], v[166:169], v[220:223], v[8:11]
	s_setprio 0
	s_setprio 1
	v_mfma_f32_16x16x32_bf16 v[52:55], v[170:173], v[192:195], v[52:55]
	v_mfma_f32_16x16x32_bf16 v[48:51], v[184:187], v[192:195], v[48:51]
	v_mfma_f32_16x16x32_bf16 v[36:39], v[170:173], v[200:203], v[36:39]
	v_mfma_f32_16x16x32_bf16 v[32:35], v[184:187], v[200:203], v[32:35]
	v_mfma_f32_16x16x32_bf16 v[20:23], v[170:173], v[208:211], v[20:23]
	v_mfma_f32_16x16x32_bf16 v[16:19], v[184:187], v[208:211], v[16:19]
	v_mfma_f32_16x16x32_bf16 v[4:7], v[170:173], v[216:219], v[4:7]
	v_mfma_f32_16x16x32_bf16 v[0:3], v[184:187], v[216:219], v[0:3]
	v_mfma_f32_16x16x32_bf16 v[52:55], v[174:177], v[196:199], v[52:55]
	v_mfma_f32_16x16x32_bf16 v[48:51], v[188:191], v[196:199], v[48:51]
	v_mfma_f32_16x16x32_bf16 v[36:39], v[174:177], v[204:207], v[36:39]
	v_mfma_f32_16x16x32_bf16 v[32:35], v[188:191], v[204:207], v[32:35]
	v_mfma_f32_16x16x32_bf16 v[20:23], v[174:177], v[212:215], v[20:23]
	v_mfma_f32_16x16x32_bf16 v[16:19], v[188:191], v[212:215], v[16:19]
	v_mfma_f32_16x16x32_bf16 v[4:7], v[174:177], v[220:223], v[4:7]
	v_mfma_f32_16x16x32_bf16 v[0:3], v[188:191], v[220:223], v[0:3]
	s_setprio 0
	s_barrier
	s_add_i32 s35, s35, 2
	s_add_u32 s48, s48, 0x100
	s_addc_u32 s49, s49, 0
	s_add_u32 s13, s13, 0x100
	s_addc_u32 s34, s34, 0
	s_cmp_gt_u32 s35, 13
	s_cbranch_scc0 .LBB0_1234
	s_and_b64 vcc, exec, s[26:27]
	s_cbranch_vccz .LBB0_1237
	s_barrier

; #define PG8_STAGE(bufoff, gbase, voff) do { _Pragma("unroll") for (int _i = 0; _i < 2; ++_i) \
;         __builtin_amdgcn_global_load_lds((const unsigned*)((const char*)(gbase) + (voff)[_i]), (LAS unsigned*)(lds + (bufoff) + ldsw + _i * 8192), 16, 0, 0); } while (0)
; #define PG8_LDA(dst, b, h) do { _Pragma("unroll") for (int m = 0; m < 4; ++m) _Pragma("unroll") for (int k = 0; k < 2; ++k) dst[m][k] = *(const LAS bf16x8*)(lds + PG8_SA(b, h) + aoff + m * 2048 + k * 1024); } while (0)
; #define PG8_LDB(dst, b, h) do { _Pragma("unroll") for (int n = 0; n < 2; ++n) _Pragma("unroll") for (int k = 0; k < 2; ++k) dst[n][k] = *(const LAS bf16x8*)(lds + PG8_SB(b, h) + boff + n * 2048 + k * 1024); } while (0)
; #define PG8_MMA(ai, bj, At, Bt) do { __builtin_amdgcn_s_setprio(1); _Pragma("unroll") for (int m = 0; m < 4; ++m) _Pragma("unroll") for (int n = 0; n < 2; ++n) _Pragma("unroll") for (int k = 0; k < 2; ++k) \
;         acc[ai][bj][m][n] = __builtin_amdgcn_mfma_f32_16x16x32_bf16(Bt[n][k], At[m][k], acc[ai][bj][m][n], 0, 0, 0); __builtin_amdgcn_s_setprio(0); } while (0)
; #define PG8_WAIT_V(n) asm volatile("s_waitcnt vmcnt(" #n ")" ::: "memory")
; #define PG8_WAIT_L(n) asm volatile("s_waitcnt lgkmcnt(" #n ")" ::: "memory")
; #define PG8_BAR __builtin_amdgcn_s_barrier()
; #define PG8_SCHED __builtin_amdgcn_sched_barrier(0)
; template <class Epi>
; __device__ __forceinline__ void gemm_phase(LAS unsigned char* lds, const Gemm g, const StaticOrder& S, const Epi& E) {
;     ...
;             const bool last = (t == nt - 2);
;             if constexpr (Epi::HAS_MID) { if (t == nt1) E.mid(acc, cur, wr, wc, fr, fq); }
;             const char* a1 = cA + ((Epi::HAS_MID && t >= nt1) ? dA2 : 0) + (size_t)(t + 1) * kstep;
;             const char* a2 = last ? nA : cA + ((Epi::HAS_MID && t + 2 >= nt1) ? dA2 : 0) + (size_t)(t + 2) * kstep; const char* b2 = last ? nB : cB + ((Epi::HAS_MID && t + 2 >= nt1) ? dB2 : 0) + (size_t)(t + 2) * kstep;
;             const char* a3 = a2 + kstep; const char* b3 = b2 + kstep;
;             PG8_LDB(B0, 0, 0); PG8_LDB(B1, 0, 1); PG8_SCHED; PG8_LDA(At, 0, 0); PG8_STAGE(PG8_SA(1, 1), a1 + hsA, voffA);
;             PG8_WAIT_V(8); PG8_WAIT_L(0); PG8_BAR; PG8_MMA(0, 0, At, B0); PG8_MMA(0, 1, At, B1); PG8_BAR; PG8_SCHED;
.LBB0_1350:
	ds_read_b128 v[144:147], v155
	ds_read_b128 v[148:151], v155 offset:1024
	ds_read_b128 v[162:165], v155 offset:2048
	ds_read_b128 v[166:169], v155 offset:3072
	ds_read_b128 v[170:173], v156
	ds_read_b128 v[174:177], v156 offset:1024
	ds_read_b128 v[184:187], v156 offset:2048
	ds_read_b128 v[188:191], v156 offset:3072
	s_add_u32 s40, s38, 0xfffc0080
	s_addc_u32 s41, s39, -1
	s_cmp_eq_u32 s48, 12
	s_cselect_b32 s43, s25, s41
	s_cselect_b32 s42, s44, s40
	s_cselect_b32 s41, s15, s47
	s_cselect_b32 s40, s45, s46
	s_add_i32 m0, s17, 0xc000
	ds_read_b128 v[192:195], v157
	ds_read_b128 v[196:199], v157 offset:1024
	ds_read_b128 v[200:203], v157 offset:2048
	ds_read_b128 v[204:207], v157 offset:3072
	ds_read_b128 v[208:211], v157 offset:4096
	ds_read_b128 v[212:215], v157 offset:5120
	ds_read_b128 v[216:219], v157 offset:6144
	ds_read_b128 v[220:223], v157 offset:7168
	global_load_lds_dwordx4 v136, s[38:39]
	s_add_i32 m0, s17, 0xe000
	s_nop 0
	global_load_lds_dwordx4 v138, s[38:39]
	s_waitcnt vmcnt(8)
	s_waitcnt lgkmcnt(0)
	s_setprio 1
	s_barrier

; #define PG8_STAGE(bufoff, gbase, voff) do { _Pragma("unroll") for (int _i = 0; _i < 2; ++_i) \
;         __builtin_amdgcn_global_load_lds((const unsigned*)((const char*)(gbase) + (voff)[_i]), (LAS unsigned*)(lds + (bufoff) + ldsw + _i * 8192), 16, 0, 0); } while (0)
; #define PG8_LDA(dst, b, h) do { _Pragma("unroll") for (int m = 0; m < 4; ++m) _Pragma("unroll") for (int k = 0; k < 2; ++k) dst[m][k] = *(const LAS bf16x8*)(lds + PG8_SA(b, h) + aoff + m * 2048 + k * 1024); } while (0)
; #define PG8_MMA(ai, bj, At, Bt) do { __builtin_amdgcn_s_setprio(1); _Pragma("unroll") for (int m = 0; m < 4; ++m) _Pragma("unroll") for (int n = 0; n < 2; ++n) _Pragma("unroll") for (int k = 0; k < 2; ++k) \
;         acc[ai][bj][m][n] = __builtin_amdgcn_mfma_f32_16x16x32_bf16(Bt[n][k], At[m][k], acc[ai][bj][m][n], 0, 0, 0); __builtin_amdgcn_s_setprio(0); } while (0)
; #define PG8_WAIT_V(n) asm volatile("s_waitcnt vmcnt(" #n ")" ::: "memory")
; #define PG8_WAIT_L(n) asm volatile("s_waitcnt lgkmcnt(" #n ")" ::: "memory")
; #define PG8_BAR __builtin_amdgcn_s_barrier()
; #define PG8_SCHED __builtin_amdgcn_sched_barrier(0)
; template <class Epi>
; __device__ __forceinline__ void gemm_phase(LAS unsigned char* lds, const Gemm g, const StaticOrder& S, const Epi& E) {
;     ...
;             PG8_WAIT_V(8); PG8_WAIT_L(0); PG8_BAR; PG8_MMA(0, 0, At, B0); PG8_MMA(0, 1, At, B1); PG8_BAR; PG8_SCHED;
;             PG8_LDA(At, 0, 1); PG8_STAGE(PG8_SB(0, 0), b2, voffB); PG8_STAGE(PG8_SB(0, 1), b2 + hsB, voffB); PG8_STAGE(PG8_SA(0, 0), a2, voffA);
;             PG8_WAIT_V(8); PG8_WAIT_L(0); PG8_BAR; PG8_MMA(1, 0, At, B0); PG8_MMA(1, 1, At, B1); PG8_BAR; PG8_SCHED;
	v_mfma_f32_16x16x32_bf16 v[124:127], v[144:147], v[192:195], v[124:127]
	v_mfma_f32_16x16x32_bf16 v[120:123], v[162:165], v[192:195], v[120:123]
	v_mfma_f32_16x16x32_bf16 v[108:111], v[144:147], v[200:203], v[108:111]
	v_mfma_f32_16x16x32_bf16 v[104:107], v[162:165], v[200:203], v[104:107]
	v_mfma_f32_16x16x32_bf16 v[92:95], v[144:147], v[208:211], v[92:95]
	v_mfma_f32_16x16x32_bf16 v[88:91], v[162:165], v[208:211], v[88:91]
	v_mfma_f32_16x16x32_bf16 v[76:79], v[144:147], v[216:219], v[76:79]
	v_mfma_f32_16x16x32_bf16 v[72:75], v[162:165], v[216:219], v[72:75]
	v_mfma_f32_16x16x32_bf16 v[124:127], v[148:151], v[196:199], v[124:127]
	v_mfma_f32_16x16x32_bf16 v[120:123], v[166:169], v[196:199], v[120:123]
	v_mfma_f32_16x16x32_bf16 v[108:111], v[148:151], v[204:207], v[108:111]
	v_mfma_f32_16x16x32_bf16 v[104:107], v[166:169], v[204:207], v[104:107]
	v_mfma_f32_16x16x32_bf16 v[92:95], v[148:151], v[212:215], v[92:95]
	v_mfma_f32_16x16x32_bf16 v[88:91], v[166:169], v[212:215], v[88:91]
	v_mfma_f32_16x16x32_bf16 v[76:79], v[148:151], v[220:223], v[76:79]
	v_mfma_f32_16x16x32_bf16 v[72:75], v[166:169], v[220:223], v[72:75]
	s_setprio 0
	s_setprio 1
	v_mfma_f32_16x16x32_bf16 v[116:119], v[170:173], v[192:195], v[116:119]
	v_mfma_f32_16x16x32_bf16 v[112:115], v[184:187], v[192:195], v[112:115]
	v_mfma_f32_16x16x32_bf16 v[100:103], v[170:173], v[200:203], v[100:103]
	v_mfma_f32_16x16x32_bf16 v[96:99], v[184:187], v[200:203], v[96:99]
	v_mfma_f32_16x16x32_bf16 v[84:87], v[170:173], v[208:211], v[84:87]
	v_mfma_f32_16x16x32_bf16 v[80:83], v[184:187], v[208:211], v[80:83]
	v_mfma_f32_16x16x32_bf16 v[68:71], v[170:173], v[216:219], v[68:71]
	v_mfma_f32_16x16x32_bf16 v[64:67], v[184:187], v[216:219], v[64:67]
	v_mfma_f32_16x16x32_bf16 v[116:119], v[174:177], v[196:199], v[116:119]
	v_mfma_f32_16x16x32_bf16 v[112:115], v[188:191], v[196:199], v[112:115]
	v_mfma_f32_16x16x32_bf16 v[100:103], v[174:177], v[204:207], v[100:103]
	v_mfma_f32_16x16x32_bf16 v[96:99], v[188:191], v[204:207], v[96:99]
	v_mfma_f32_16x16x32_bf16 v[84:87], v[174:177], v[212:215], v[84:87]
	v_mfma_f32_16x16x32_bf16 v[80:83], v[188:191], v[212:215], v[80:83]
	v_mfma_f32_16x16x32_bf16 v[68:71], v[174:177], v[220:223], v[68:71]
	v_mfma_f32_16x16x32_bf16 v[64:67], v[188:191], v[220:223], v[64:67]
	s_setprio 0
	s_barrier
	s_add_i32 s49, s30, s4
	s_mov_b32 m0, s49
	ds_read_b128 v[192:195], v157 offset:16384
	ds_read_b128 v[196:199], v157 offset:17408
	ds_read_b128 v[200:203], v157 offset:18432
	ds_read_b128 v[204:207], v157 offset:19456
	ds_read_b128 v[208:211], v157 offset:20480
	ds_read_b128 v[212:215], v157 offset:21504
	ds_read_b128 v[216:219], v157 offset:22528
	ds_read_b128 v[220:223], v157 offset:23552
	global_load_lds_dwordx4 v132, s[40:41]
	s_add_i32 m0, s49, 0x2000
	s_add_u32 s50, s40, 0x40000
	s_addc_u32 s51, s41, 0
	s_add_i32 s49, s31, s4
	global_load_lds_dwordx4 v128, s[40:41]
	s_mov_b32 m0, s49
	s_nop 0
	global_load_lds_dwordx4 v132, s[50:51]
	s_add_i32 m0, s49, 0x2000
	s_nop 0
	global_load_lds_dwordx4 v128, s[50:51]
	s_mov_b32 m0, s17
	s_nop 0
	global_load_lds_dwordx4 v134, s[42:43]
	s_mov_b32 m0, s18
	s_nop 0
	global_load_lds_dwordx4 v130, s[42:43]
	s_waitcnt vmcnt(8)
	s_waitcnt lgkmcnt(0)
	s_setprio 1
	s_barrier

; #define PG8_STAGE(bufoff, gbase, voff) do { _Pragma("unroll") for (int _i = 0; _i < 2; ++_i) \
;         __builtin_amdgcn_global_load_lds((const unsigned*)((const char*)(gbase) + (voff)[_i]), (LAS unsigned*)(lds + (bufoff) + ldsw + _i * 8192), 16, 0, 0); } while (0)
; #define PG8_LDA(dst, b, h) do { _Pragma("unroll") for (int m = 0; m < 4; ++m) _Pragma("unroll") for (int k = 0; k < 2; ++k) dst[m][k] = *(const LAS bf16x8*)(lds + PG8_SA(b, h) + aoff + m * 2048 + k * 1024); } while (0)
; #define PG8_LDB(dst, b, h) do { _Pragma("unroll") for (int n = 0; n < 2; ++n) _Pragma("unroll") for (int k = 0; k < 2; ++k) dst[n][k] = *(const LAS bf16x8*)(lds + PG8_SB(b, h) + boff + n * 2048 + k * 1024); } while (0)
; #define PG8_MMA(ai, bj, At, Bt) do { __builtin_amdgcn_s_setprio(1); _Pragma("unroll") for (int m = 0; m < 4; ++m) _Pragma("unroll") for (int n = 0; n < 2; ++n) _Pragma("unroll") for (int k = 0; k < 2; ++k) \
;         acc[ai][bj][m][n] = __builtin_amdgcn_mfma_f32_16x16x32_bf16(Bt[n][k], At[m][k], acc[ai][bj][m][n], 0, 0, 0); __builtin_amdgcn_s_setprio(0); } while (0)
; #define PG8_WAIT_V(n) asm volatile("s_waitcnt vmcnt(" #n ")" ::: "memory")
; #define PG8_WAIT_L(n) asm volatile("s_waitcnt lgkmcnt(" #n ")" ::: "memory")
; #define PG8_BAR __builtin_amdgcn_s_barrier()
; #define PG8_SCHED __builtin_amdgcn_sched_barrier(0)
; template <class Epi>
; __device__ __forceinline__ void gemm_phase(LAS unsigned char* lds, const Gemm g, const StaticOrder& S, const Epi& E) {
;     ...
;             PG8_WAIT_V(8); PG8_WAIT_L(0); PG8_BAR; PG8_MMA(1, 0, At, B0); PG8_MMA(1, 1, At, B1); PG8_BAR; PG8_SCHED;
;             PG8_LDB(B0, 1, 0); PG8_LDB(B1, 1, 1); PG8_SCHED; PG8_LDA(At, 1, 0); PG8_STAGE(PG8_SA(0, 1), a2 + hsA, voffA);
;             PG8_WAIT_V(8); PG8_WAIT_L(0); PG8_BAR; PG8_MMA(0, 0, At, B0); PG8_MMA(0, 1, At, B1); PG8_BAR; PG8_SCHED;
	v_mfma_f32_16x16x32_bf16 v[60:63], v[144:147], v[192:195], v[60:63]
	v_mfma_f32_16x16x32_bf16 v[56:59], v[162:165], v[192:195], v[56:59]
	v_mfma_f32_16x16x32_bf16 v[44:47], v[144:147], v[200:203], v[44:47]
	v_mfma_f32_16x16x32_bf16 v[40:43], v[162:165], v[200:203], v[40:43]
	v_mfma_f32_16x16x32_bf16 v[28:31], v[144:147], v[208:211], v[28:31]
	v_mfma_f32_16x16x32_bf16 v[24:27], v[162:165], v[208:211], v[24:27]
	v_mfma_f32_16x16x32_bf16 v[12:15], v[144:147], v[216:219], v[12:15]
	v_mfma_f32_16x16x32_bf16 v[8:11], v[162:165], v[216:219], v[8:11]
	v_mfma_f32_16x16x32_bf16 v[60:63], v[148:151], v[196:199], v[60:63]
	v_mfma_f32_16x16x32_bf16 v[56:59], v[166:169], v[196:199], v[56:59]
	v_mfma_f32_16x16x32_bf16 v[44:47], v[148:151], v[204:207], v[44:47]
	v_mfma_f32_16x16x32_bf16 v[40:43], v[166:169], v[204:207], v[40:43]
	v_mfma_f32_16x16x32_bf16 v[28:31], v[148:151], v[212:215], v[28:31]
	v_mfma_f32_16x16x32_bf16 v[24:27], v[166:169], v[212:215], v[24:27]
	v_mfma_f32_16x16x32_bf16 v[12:15], v[148:151], v[220:223], v[12:15]
	v_mfma_f32_16x16x32_bf16 v[8:11], v[166:169], v[220:223], v[8:11]
	s_setprio 0
	s_setprio 1
	v_mfma_f32_16x16x32_bf16 v[52:55], v[170:173], v[192:195], v[52:55]
	v_mfma_f32_16x16x32_bf16 v[48:51], v[184:187], v[192:195], v[48:51]
	v_mfma_f32_16x16x32_bf16 v[36:39], v[170:173], v[200:203], v[36:39]
	v_mfma_f32_16x16x32_bf16 v[32:35], v[184:187], v[200:203], v[32:35]
	v_mfma_f32_16x16x32_bf16 v[20:23], v[170:173], v[208:211], v[20:23]
	v_mfma_f32_16x16x32_bf16 v[16:19], v[184:187], v[208:211], v[16:19]
	v_mfma_f32_16x16x32_bf16 v[4:7], v[170:173], v[216:219], v[4:7]
	v_mfma_f32_16x16x32_bf16 v[0:3], v[184:187], v[216:219], v[0:3]
	v_mfma_f32_16x16x32_bf16 v[52:55], v[174:177], v[196:199], v[52:55]
	v_mfma_f32_16x16x32_bf16 v[48:51], v[188:191], v[196:199], v[48:51]
	v_mfma_f32_16x16x32_bf16 v[36:39], v[174:177], v[204:207], v[36:39]
	v_mfma_f32_16x16x32_bf16 v[32:35], v[188:191], v[204:207], v[32:35]
	v_mfma_f32_16x16x32_bf16 v[20:23], v[174:177], v[212:215], v[20:23]
	v_mfma_f32_16x16x32_bf16 v[16:19], v[188:191], v[212:215], v[16:19]
	v_mfma_f32_16x16x32_bf16 v[4:7], v[174:177], v[220:223], v[4:7]
	v_mfma_f32_16x16x32_bf16 v[0:3], v[188:191], v[220:223], v[0:3]
	s_setprio 0
	s_barrier
	s_add_i32 s49, 0, 0x18000
	v_add_u32_e32 v159, s49, v153
	s_add_i32 s50, 0, 0x1c000
	ds_read_b128 v[144:147], v159
	ds_read_b128 v[148:151], v159 offset:1024
	ds_read_b128 v[162:165], v159 offset:2048
	ds_read_b128 v[166:169], v159 offset:3072
	v_add_u32_e32 v159, s50, v153
	ds_read_b128 v[170:173], v159
	ds_read_b128 v[174:177], v159 offset:1024
	ds_read_b128 v[184:187], v159 offset:2048
	ds_read_b128 v[188:191], v159 offset:3072
	s_add_u32 s42, s42, 0x40000
	s_addc_u32 s43, s43, 0
	s_mov_b32 m0, s19
	ds_read_b128 v[192:195], v157 offset:32768
	ds_read_b128 v[196:199], v157 offset:33792
	ds_read_b128 v[200:203], v157 offset:34816
	ds_read_b128 v[204:207], v157 offset:35840
	ds_read_b128 v[208:211], v157 offset:36864
	ds_read_b128 v[212:215], v157 offset:37888
	ds_read_b128 v[216:219], v157 offset:38912
	ds_read_b128 v[220:223], v157 offset:39936
	global_load_lds_dwordx4 v134, s[42:43]
	s_mov_b32 m0, s22
	s_nop 0
	global_load_lds_dwordx4 v130, s[42:43]
	s_waitcnt vmcnt(8)
	s_waitcnt lgkmcnt(0)
	s_setprio 1
	s_barrier

; #define PG8_STAGE(bufoff, gbase, voff) do { _Pragma("unroll") for (int _i = 0; _i < 2; ++_i) \
;         __builtin_amdgcn_global_load_lds((const unsigned*)((const char*)(gbase) + (voff)[_i]), (LAS unsigned*)(lds + (bufoff) + ldsw + _i * 8192), 16, 0, 0); } while (0)
; #define PG8_LDA(dst, b, h) do { _Pragma("unroll") for (int m = 0; m < 4; ++m) _Pragma("unroll") for (int k = 0; k < 2; ++k) dst[m][k] = *(const LAS bf16x8*)(lds + PG8_SA(b, h) + aoff + m * 2048 + k * 1024); } while (0)
; #define PG8_MMA(ai, bj, At, Bt) do { __builtin_amdgcn_s_setprio(1); _Pragma("unroll") for (int m = 0; m < 4; ++m) _Pragma("unroll") for (int n = 0; n < 2; ++n) _Pragma("unroll") for (int k = 0; k < 2; ++k) \
;         acc[ai][bj][m][n] = __builtin_amdgcn_mfma_f32_16x16x32_bf16(Bt[n][k], At[m][k], acc[ai][bj][m][n], 0, 0, 0); __builtin_amdgcn_s_setprio(0); } while (0)
; #define PG8_WAIT_V(n) asm volatile("s_waitcnt vmcnt(" #n ")" ::: "memory")
; #define PG8_WAIT_L(n) asm volatile("s_waitcnt lgkmcnt(" #n ")" ::: "memory")
; #define PG8_BAR __builtin_amdgcn_s_barrier()
; #define PG8_SCHED __builtin_amdgcn_sched_barrier(0)
; template <class Epi>
; __device__ __forceinline__ void gemm_phase(LAS unsigned char* lds, const Gemm g, const StaticOrder& S, const Epi& E) {
;     ...
;             PG8_WAIT_V(8); PG8_WAIT_L(0); PG8_BAR; PG8_MMA(0, 0, At, B0); PG8_MMA(0, 1, At, B1); PG8_BAR; PG8_SCHED;
;             PG8_LDA(At, 1, 1); PG8_STAGE(PG8_SB(1, 0), b3, voffB); PG8_STAGE(PG8_SB(1, 1), b3 + hsB, voffB); PG8_STAGE(PG8_SA(1, 0), a3, voffA);
;             PG8_WAIT_V(8); PG8_WAIT_L(0); PG8_BAR; PG8_MMA(1, 0, At, B0); PG8_MMA(1, 1, At, B1); PG8_BAR; PG8_SCHED;
	v_mfma_f32_16x16x32_bf16 v[124:127], v[144:147], v[192:195], v[124:127]
	v_mfma_f32_16x16x32_bf16 v[120:123], v[162:165], v[192:195], v[120:123]
	v_mfma_f32_16x16x32_bf16 v[108:111], v[144:147], v[200:203], v[108:111]
	v_mfma_f32_16x16x32_bf16 v[104:107], v[162:165], v[200:203], v[104:107]
	v_mfma_f32_16x16x32_bf16 v[92:95], v[144:147], v[208:211], v[92:95]
	v_mfma_f32_16x16x32_bf16 v[88:91], v[162:165], v[208:211], v[88:91]
	v_mfma_f32_16x16x32_bf16 v[76:79], v[144:147], v[216:219], v[76:79]
	v_mfma_f32_16x16x32_bf16 v[72:75], v[162:165], v[216:219], v[72:75]
	v_mfma_f32_16x16x32_bf16 v[124:127], v[148:151], v[196:199], v[124:127]
	v_mfma_f32_16x16x32_bf16 v[120:123], v[166:169], v[196:199], v[120:123]
	v_mfma_f32_16x16x32_bf16 v[108:111], v[148:151], v[204:207], v[108:111]
	v_mfma_f32_16x16x32_bf16 v[104:107], v[166:169], v[204:207], v[104:107]
	v_mfma_f32_16x16x32_bf16 v[92:95], v[148:151], v[212:215], v[92:95]
	v_mfma_f32_16x16x32_bf16 v[88:91], v[166:169], v[212:215], v[88:91]
	v_mfma_f32_16x16x32_bf16 v[76:79], v[148:151], v[220:223], v[76:79]
	v_mfma_f32_16x16x32_bf16 v[72:75], v[166:169], v[220:223], v[72:75]
	s_setprio 0
	s_setprio 1
	v_mfma_f32_16x16x32_bf16 v[116:119], v[170:173], v[192:195], v[116:119]
	v_mfma_f32_16x16x32_bf16 v[112:115], v[184:187], v[192:195], v[112:115]
	v_mfma_f32_16x16x32_bf16 v[100:103], v[170:173], v[200:203], v[100:103]
	v_mfma_f32_16x16x32_bf16 v[96:99], v[184:187], v[200:203], v[96:99]
	v_mfma_f32_16x16x32_bf16 v[84:87], v[170:173], v[208:211], v[84:87]
	v_mfma_f32_16x16x32_bf16 v[80:83], v[184:187], v[208:211], v[80:83]
	v_mfma_f32_16x16x32_bf16 v[68:71], v[170:173], v[216:219], v[68:71]
	v_mfma_f32_16x16x32_bf16 v[64:67], v[184:187], v[216:219], v[64:67]
	v_mfma_f32_16x16x32_bf16 v[116:119], v[174:177], v[196:199], v[116:119]
	v_mfma_f32_16x16x32_bf16 v[112:115], v[188:191], v[196:199], v[112:115]
	v_mfma_f32_16x16x32_bf16 v[100:103], v[174:177], v[204:207], v[100:103]
	v_mfma_f32_16x16x32_bf16 v[96:99], v[188:191], v[204:207], v[96:99]
	v_mfma_f32_16x16x32_bf16 v[84:87], v[174:177], v[212:215], v[84:87]
	v_mfma_f32_16x16x32_bf16 v[80:83], v[188:191], v[212:215], v[80:83]
	v_mfma_f32_16x16x32_bf16 v[68:71], v[174:177], v[220:223], v[68:71]
	v_mfma_f32_16x16x32_bf16 v[64:67], v[188:191], v[220:223], v[64:67]
	s_setprio 0
	s_barrier
	s_add_u32 s98, s40, 0x80
	s_addc_u32 s99, s41, 0
	s_add_u32 s100, s42, 0xfffc0080
	s_addc_u32 s101, s43, -1
	s_add_i32 s42, s49, s4
	s_mov_b32 m0, s42
	ds_read_b128 v[192:195], v157 offset:49152
	ds_read_b128 v[196:199], v157 offset:50176
	ds_read_b128 v[200:203], v157 offset:51200
	ds_read_b128 v[204:207], v157 offset:52224
	ds_read_b128 v[208:211], v157 offset:53248
	ds_read_b128 v[212:215], v157 offset:54272
	ds_read_b128 v[216:219], v157 offset:55296
	ds_read_b128 v[220:223], v157 offset:56320
	global_load_lds_dwordx4 v132, s[98:99]
	s_add_i32 m0, s42, 0x2000
	s_add_u32 s40, s40, 0x40080
	s_addc_u32 s41, s41, 0
	s_add_i32 s42, s50, s4
	global_load_lds_dwordx4 v128, s[98:99]
	s_mov_b32 m0, s42
	s_nop 0
	global_load_lds_dwordx4 v132, s[40:41]
	s_add_i32 m0, s42, 0x2000
	s_nop 0
	global_load_lds_dwordx4 v128, s[40:41]
	s_mov_b32 m0, s0
	s_nop 0
	global_load_lds_dwordx4 v134, s[100:101]
	s_mov_b32 m0, s1
	s_nop 0
	global_load_lds_dwordx4 v130, s[100:101]
	s_waitcnt vmcnt(8)
	s_waitcnt lgkmcnt(0)
	s_setprio 1
	s_barrier

; #define PG8_MMA(ai, bj, At, Bt) do { __builtin_amdgcn_s_setprio(1); _Pragma("unroll") for (int m = 0; m < 4; ++m) _Pragma("unroll") for (int n = 0; n < 2; ++n) _Pragma("unroll") for (int k = 0; k < 2; ++k) \
;         acc[ai][bj][m][n] = __builtin_amdgcn_mfma_f32_16x16x32_bf16(Bt[n][k], At[m][k], acc[ai][bj][m][n], 0, 0, 0); __builtin_amdgcn_s_setprio(0); } while (0)
; #define PG8_WAIT_V(n) asm volatile("s_waitcnt vmcnt(" #n ")" ::: "memory")
; #define PG8_WAIT_L(n) asm volatile("s_waitcnt lgkmcnt(" #n ")" ::: "memory")
; #define PG8_BAR __builtin_amdgcn_s_barrier()
; #define PG8_SCHED __builtin_amdgcn_sched_barrier(0)
; template <class Epi>
; __device__ __forceinline__ void gemm_phase(LAS unsigned char* lds, const Gemm g, const StaticOrder& S, const Epi& E) {
;     ...
;             PG8_WAIT_V(8); PG8_WAIT_L(0); PG8_BAR; PG8_MMA(1, 0, At, B0); PG8_MMA(1, 1, At, B1); PG8_BAR; PG8_SCHED;
;         }
;         if (wr == 0) PG8_BAR;
	v_mfma_f32_16x16x32_bf16 v[60:63], v[144:147], v[192:195], v[60:63]
	v_mfma_f32_16x16x32_bf16 v[56:59], v[162:165], v[192:195], v[56:59]
	v_mfma_f32_16x16x32_bf16 v[44:47], v[144:147], v[200:203], v[44:47]
	v_mfma_f32_16x16x32_bf16 v[40:43], v[162:165], v[200:203], v[40:43]
	v_mfma_f32_16x16x32_bf16 v[28:31], v[144:147], v[208:211], v[28:31]
	v_mfma_f32_16x16x32_bf16 v[24:27], v[162:165], v[208:211], v[24:27]
	v_mfma_f32_16x16x32_bf16 v[12:15], v[144:147], v[216:219], v[12:15]
	v_mfma_f32_16x16x32_bf16 v[8:11], v[162:165], v[216:219], v[8:11]
	v_mfma_f32_16x16x32_bf16 v[60:63], v[148:151], v[196:199], v[60:63]
	v_mfma_f32_16x16x32_bf16 v[56:59], v[166:169], v[196:199], v[56:59]
	v_mfma_f32_16x16x32_bf16 v[44:47], v[148:151], v[204:207], v[44:47]
	v_mfma_f32_16x16x32_bf16 v[40:43], v[166:169], v[204:207], v[40:43]
	v_mfma_f32_16x16x32_bf16 v[28:31], v[148:151], v[212:215], v[28:31]
	v_mfma_f32_16x16x32_bf16 v[24:27], v[166:169], v[212:215], v[24:27]
	v_mfma_f32_16x16x32_bf16 v[12:15], v[148:151], v[220:223], v[12:15]
	v_mfma_f32_16x16x32_bf16 v[8:11], v[166:169], v[220:223], v[8:11]
	s_setprio 0
	s_setprio 1
	v_mfma_f32_16x16x32_bf16 v[52:55], v[170:173], v[192:195], v[52:55]
	v_mfma_f32_16x16x32_bf16 v[48:51], v[184:187], v[192:195], v[48:51]
	v_mfma_f32_16x16x32_bf16 v[36:39], v[170:173], v[200:203], v[36:39]
	v_mfma_f32_16x16x32_bf16 v[32:35], v[184:187], v[200:203], v[32:35]
	v_mfma_f32_16x16x32_bf16 v[20:23], v[170:173], v[208:211], v[20:23]
	v_mfma_f32_16x16x32_bf16 v[16:19], v[184:187], v[208:211], v[16:19]
	v_mfma_f32_16x16x32_bf16 v[4:7], v[170:173], v[216:219], v[4:7]
	v_mfma_f32_16x16x32_bf16 v[0:3], v[184:187], v[216:219], v[0:3]
	v_mfma_f32_16x16x32_bf16 v[52:55], v[174:177], v[196:199], v[52:55]
	v_mfma_f32_16x16x32_bf16 v[48:51], v[188:191], v[196:199], v[48:51]
	v_mfma_f32_16x16x32_bf16 v[36:39], v[174:177], v[204:207], v[36:39]
	v_mfma_f32_16x16x32_bf16 v[32:35], v[188:191], v[204:207], v[32:35]
	v_mfma_f32_16x16x32_bf16 v[20:23], v[174:177], v[212:215], v[20:23]
	v_mfma_f32_16x16x32_bf16 v[16:19], v[188:191], v[212:215], v[16:19]
	v_mfma_f32_16x16x32_bf16 v[4:7], v[174:177], v[220:223], v[4:7]
	v_mfma_f32_16x16x32_bf16 v[0:3], v[188:191], v[220:223], v[0:3]
	s_setprio 0
	s_barrier
	s_add_i32 s48, s48, 2
	s_add_u32 s38, s38, 0x100
	s_addc_u32 s39, s39, 0
	s_add_u32 s46, s46, 0x100
	s_addc_u32 s47, s47, 0
	s_cmp_gt_u32 s48, 13
	s_cbranch_scc0 .LBB0_1350
	s_and_b64 vcc, exec, s[12:13]
	s_cbranch_vccz .LBB0_1353
	s_barrier

; #define PG8_STAGE(bufoff, gbase, voff) do { _Pragma("unroll") for (int _i = 0; _i < 2; ++_i) \
;         __builtin_amdgcn_global_load_lds((const unsigned*)((const char*)(gbase) + (voff)[_i]), (LAS unsigned*)(lds + (bufoff) + ldsw + _i * 8192), 16, 0, 0); } while (0)
; #define PG8_LDA(dst, b, h) do { _Pragma("unroll") for (int m = 0; m < 4; ++m) _Pragma("unroll") for (int k = 0; k < 2; ++k) dst[m][k] = *(const LAS bf16x8*)(lds + PG8_SA(b, h) + aoff + m * 2048 + k * 1024); } while (0)
; #define PG8_LDB(dst, b, h) do { _Pragma("unroll") for (int n = 0; n < 2; ++n) _Pragma("unroll") for (int k = 0; k < 2; ++k) dst[n][k] = *(const LAS bf16x8*)(lds + PG8_SB(b, h) + boff + n * 2048 + k * 1024); } while (0)
; #define PG8_MMA(ai, bj, At, Bt) do { __builtin_amdgcn_s_setprio(1); _Pragma("unroll") for (int m = 0; m < 4; ++m) _Pragma("unroll") for (int n = 0; n < 2; ++n) _Pragma("unroll") for (int k = 0; k < 2; ++k) \
;         acc[ai][bj][m][n] = __builtin_amdgcn_mfma_f32_16x16x32_bf16(Bt[n][k], At[m][k], acc[ai][bj][m][n], 0, 0, 0); __builtin_amdgcn_s_setprio(0); } while (0)
; #define PG8_WAIT_V(n) asm volatile("s_waitcnt vmcnt(" #n ")" ::: "memory")
; #define PG8_WAIT_L(n) asm volatile("s_waitcnt lgkmcnt(" #n ")" ::: "memory")
; #define PG8_BAR __builtin_amdgcn_s_barrier()
; #define PG8_SCHED __builtin_amdgcn_sched_barrier(0)
; template <class Epi>
; __device__ __forceinline__ void gemm_phase(LAS unsigned char* lds, const Gemm g, const StaticOrder& S, const Epi& E) {
;     ...
;             const bool last = (t == nt - 2);
;             if constexpr (Epi::HAS_MID) { if (t == nt1) E.mid(acc, cur, wr, wc, fr, fq); }
;             const char* a1 = cA + ((Epi::HAS_MID && t >= nt1) ? dA2 : 0) + (size_t)(t + 1) * kstep;
;             const char* a2 = last ? nA : cA + ((Epi::HAS_MID && t + 2 >= nt1) ? dA2 : 0) + (size_t)(t + 2) * kstep; const char* b2 = last ? nB : cB + ((Epi::HAS_MID && t + 2 >= nt1) ? dB2 : 0) + (size_t)(t + 2) * kstep;
;             const char* a3 = a2 + kstep; const char* b3 = b2 + kstep;
;             PG8_LDB(B0, 0, 0); PG8_LDB(B1, 0, 1); PG8_SCHED; PG8_LDA(At, 0, 0); PG8_STAGE(PG8_SA(1, 1), a1 + hsA, voffA);
;             PG8_WAIT_V(8); PG8_WAIT_L(0); PG8_BAR; PG8_MMA(0, 0, At, B0); PG8_MMA(0, 1, At, B1); PG8_BAR; PG8_SCHED;
.LBB0_1433:
	ds_read_b128 v[144:147], v202
	ds_read_b128 v[148:151], v202 offset:1024
	ds_read_b128 v[152:155], v202 offset:2048
	ds_read_b128 v[156:159], v202 offset:3072
	ds_read_b128 v[160:163], v203
	ds_read_b128 v[164:167], v203 offset:1024
	ds_read_b128 v[168:171], v203 offset:2048
	ds_read_b128 v[172:175], v203 offset:3072
	s_add_u32 s34, s26, 0x100
	s_addc_u32 s35, s27, 0
	s_cmp_eq_u32 s51, 40
	s_cselect_b32 s39, s1, s35
	s_cselect_b32 s38, s0, s34
	s_cselect_b32 s37, s23, s50
	s_cselect_b32 s36, s22, s25
	s_add_i32 m0, s17, 0xc000
	ds_read_b128 v[216:219], v204
	ds_read_b128 v[220:223], v204 offset:1024
	ds_read_b128 v[224:227], v204 offset:2048
	ds_read_b128 v[228:231], v204 offset:3072
	ds_read_b128 v[232:235], v204 offset:4096
	ds_read_b128 v[236:239], v204 offset:5120
	ds_read_b128 v[240:243], v204 offset:6144
	ds_read_b128 v[244:247], v204 offset:7168
	global_load_lds_dwordx4 v136, s[26:27]
	s_add_i32 m0, s17, 0xe000
	s_nop 0
	global_load_lds_dwordx4 v138, s[26:27]
	s_waitcnt vmcnt(8)
	s_waitcnt lgkmcnt(0)
	s_setprio 1
	s_barrier

; #define PG8_STAGE(bufoff, gbase, voff) do { _Pragma("unroll") for (int _i = 0; _i < 2; ++_i) \
;         __builtin_amdgcn_global_load_lds((const unsigned*)((const char*)(gbase) + (voff)[_i]), (LAS unsigned*)(lds + (bufoff) + ldsw + _i * 8192), 16, 0, 0); } while (0)
; #define PG8_LDA(dst, b, h) do { _Pragma("unroll") for (int m = 0; m < 4; ++m) _Pragma("unroll") for (int k = 0; k < 2; ++k) dst[m][k] = *(const LAS bf16x8*)(lds + PG8_SA(b, h) + aoff + m * 2048 + k * 1024); } while (0)
; #define PG8_MMA(ai, bj, At, Bt) do { __builtin_amdgcn_s_setprio(1); _Pragma("unroll") for (int m = 0; m < 4; ++m) _Pragma("unroll") for (int n = 0; n < 2; ++n) _Pragma("unroll") for (int k = 0; k < 2; ++k) \
;         acc[ai][bj][m][n] = __builtin_amdgcn_mfma_f32_16x16x32_bf16(Bt[n][k], At[m][k], acc[ai][bj][m][n], 0, 0, 0); __builtin_amdgcn_s_setprio(0); } while (0)
; #define PG8_WAIT_V(n) asm volatile("s_waitcnt vmcnt(" #n ")" ::: "memory")
; #define PG8_WAIT_L(n) asm volatile("s_waitcnt lgkmcnt(" #n ")" ::: "memory")
; #define PG8_BAR __builtin_amdgcn_s_barrier()
; #define PG8_SCHED __builtin_amdgcn_sched_barrier(0)
; template <class Epi>
; __device__ __forceinline__ void gemm_phase(LAS unsigned char* lds, const Gemm g, const StaticOrder& S, const Epi& E) {
;     ...
;             PG8_WAIT_V(8); PG8_WAIT_L(0); PG8_BAR; PG8_MMA(0, 0, At, B0); PG8_MMA(0, 1, At, B1); PG8_BAR; PG8_SCHED;
;             PG8_LDA(At, 0, 1); PG8_STAGE(PG8_SB(0, 0), b2, voffB); PG8_STAGE(PG8_SB(0, 1), b2 + hsB, voffB); PG8_STAGE(PG8_SA(0, 0), a2, voffA);
;             PG8_WAIT_V(8); PG8_WAIT_L(0); PG8_BAR; PG8_MMA(1, 0, At, B0); PG8_MMA(1, 1, At, B1); PG8_BAR; PG8_SCHED;
	v_mfma_f32_16x16x32_bf16 v[124:127], v[144:147], v[216:219], v[124:127]
	v_mfma_f32_16x16x32_bf16 v[120:123], v[152:155], v[216:219], v[120:123]
	v_mfma_f32_16x16x32_bf16 v[108:111], v[144:147], v[224:227], v[108:111]
	v_mfma_f32_16x16x32_bf16 v[104:107], v[152:155], v[224:227], v[104:107]
	v_mfma_f32_16x16x32_bf16 v[92:95], v[144:147], v[232:235], v[92:95]
	v_mfma_f32_16x16x32_bf16 v[88:91], v[152:155], v[232:235], v[88:91]
	v_mfma_f32_16x16x32_bf16 v[76:79], v[144:147], v[240:243], v[76:79]
	v_mfma_f32_16x16x32_bf16 v[72:75], v[152:155], v[240:243], v[72:75]
	v_mfma_f32_16x16x32_bf16 v[124:127], v[148:151], v[220:223], v[124:127]
	v_mfma_f32_16x16x32_bf16 v[120:123], v[156:159], v[220:223], v[120:123]
	v_mfma_f32_16x16x32_bf16 v[108:111], v[148:151], v[228:231], v[108:111]
	v_mfma_f32_16x16x32_bf16 v[104:107], v[156:159], v[228:231], v[104:107]
	v_mfma_f32_16x16x32_bf16 v[92:95], v[148:151], v[236:239], v[92:95]
	v_mfma_f32_16x16x32_bf16 v[88:91], v[156:159], v[236:239], v[88:91]
	v_mfma_f32_16x16x32_bf16 v[76:79], v[148:151], v[244:247], v[76:79]
	v_mfma_f32_16x16x32_bf16 v[72:75], v[156:159], v[244:247], v[72:75]
	s_setprio 0
	s_setprio 1
	v_mfma_f32_16x16x32_bf16 v[116:119], v[160:163], v[216:219], v[116:119]
	v_mfma_f32_16x16x32_bf16 v[112:115], v[168:171], v[216:219], v[112:115]
	v_mfma_f32_16x16x32_bf16 v[100:103], v[160:163], v[224:227], v[100:103]
	v_mfma_f32_16x16x32_bf16 v[96:99], v[168:171], v[224:227], v[96:99]
	v_mfma_f32_16x16x32_bf16 v[84:87], v[160:163], v[232:235], v[84:87]
	v_mfma_f32_16x16x32_bf16 v[80:83], v[168:171], v[232:235], v[80:83]
	v_mfma_f32_16x16x32_bf16 v[68:71], v[160:163], v[240:243], v[68:71]
	v_mfma_f32_16x16x32_bf16 v[64:67], v[168:171], v[240:243], v[64:67]
	v_mfma_f32_16x16x32_bf16 v[116:119], v[164:167], v[220:223], v[116:119]
	v_mfma_f32_16x16x32_bf16 v[112:115], v[172:175], v[220:223], v[112:115]
	v_mfma_f32_16x16x32_bf16 v[100:103], v[164:167], v[228:231], v[100:103]
	v_mfma_f32_16x16x32_bf16 v[96:99], v[172:175], v[228:231], v[96:99]
	v_mfma_f32_16x16x32_bf16 v[84:87], v[164:167], v[236:239], v[84:87]
	v_mfma_f32_16x16x32_bf16 v[80:83], v[172:175], v[236:239], v[80:83]
	v_mfma_f32_16x16x32_bf16 v[68:71], v[164:167], v[244:247], v[68:71]
	v_mfma_f32_16x16x32_bf16 v[64:67], v[172:175], v[244:247], v[64:67]
	s_setprio 0
	s_barrier
	s_add_i32 s26, s45, s16
	s_mov_b32 m0, s26
	ds_read_b128 v[216:219], v204 offset:16384
	ds_read_b128 v[220:223], v204 offset:17408
	ds_read_b128 v[224:227], v204 offset:18432
	ds_read_b128 v[228:231], v204 offset:19456
	ds_read_b128 v[232:235], v204 offset:20480
	ds_read_b128 v[236:239], v204 offset:21504
	ds_read_b128 v[240:243], v204 offset:22528
	ds_read_b128 v[244:247], v204 offset:23552
	global_load_lds_dwordx4 v130, s[36:37]
	s_add_i32 m0, s26, 0x2000
	s_add_u32 s26, s36, 0xb0000
	s_addc_u32 s27, s37, 0
	s_add_i32 s52, s46, s16
	global_load_lds_dwordx4 v134, s[36:37]
	s_mov_b32 m0, s52
	s_nop 0
	global_load_lds_dwordx4 v130, s[26:27]
	s_add_i32 m0, s52, 0x2000
	s_nop 0
	global_load_lds_dwordx4 v134, s[26:27]
	s_mov_b32 m0, s17
	s_nop 0
	global_load_lds_dwordx4 v128, s[38:39]
	s_mov_b32 m0, s28
	s_nop 0
	global_load_lds_dwordx4 v132, s[38:39]
	s_waitcnt vmcnt(8)
	s_waitcnt lgkmcnt(0)
	s_setprio 1
	s_barrier

; #define PG8_STAGE(bufoff, gbase, voff) do { _Pragma("unroll") for (int _i = 0; _i < 2; ++_i) \
;         __builtin_amdgcn_global_load_lds((const unsigned*)((const char*)(gbase) + (voff)[_i]), (LAS unsigned*)(lds + (bufoff) + ldsw + _i * 8192), 16, 0, 0); } while (0)
; #define PG8_LDA(dst, b, h) do { _Pragma("unroll") for (int m = 0; m < 4; ++m) _Pragma("unroll") for (int k = 0; k < 2; ++k) dst[m][k] = *(const LAS bf16x8*)(lds + PG8_SA(b, h) + aoff + m * 2048 + k * 1024); } while (0)
; #define PG8_LDB(dst, b, h) do { _Pragma("unroll") for (int n = 0; n < 2; ++n) _Pragma("unroll") for (int k = 0; k < 2; ++k) dst[n][k] = *(const LAS bf16x8*)(lds + PG8_SB(b, h) + boff + n * 2048 + k * 1024); } while (0)
; #define PG8_MMA(ai, bj, At, Bt) do { __builtin_amdgcn_s_setprio(1); _Pragma("unroll") for (int m = 0; m < 4; ++m) _Pragma("unroll") for (int n = 0; n < 2; ++n) _Pragma("unroll") for (int k = 0; k < 2; ++k) \
;         acc[ai][bj][m][n] = __builtin_amdgcn_mfma_f32_16x16x32_bf16(Bt[n][k], At[m][k], acc[ai][bj][m][n], 0, 0, 0); __builtin_amdgcn_s_setprio(0); } while (0)
; #define PG8_WAIT_V(n) asm volatile("s_waitcnt vmcnt(" #n ")" ::: "memory")
; #define PG8_WAIT_L(n) asm volatile("s_waitcnt lgkmcnt(" #n ")" ::: "memory")
; #define PG8_BAR __builtin_amdgcn_s_barrier()
; #define PG8_SCHED __builtin_amdgcn_sched_barrier(0)
; template <class Epi>
; __device__ __forceinline__ void gemm_phase(LAS unsigned char* lds, const Gemm g, const StaticOrder& S, const Epi& E) {
;     ...
;             PG8_WAIT_V(8); PG8_WAIT_L(0); PG8_BAR; PG8_MMA(1, 0, At, B0); PG8_MMA(1, 1, At, B1); PG8_BAR; PG8_SCHED;
;             PG8_LDB(B0, 1, 0); PG8_LDB(B1, 1, 1); PG8_SCHED; PG8_LDA(At, 1, 0); PG8_STAGE(PG8_SA(0, 1), a2 + hsA, voffA);
;             PG8_WAIT_V(8); PG8_WAIT_L(0); PG8_BAR; PG8_MMA(0, 0, At, B0); PG8_MMA(0, 1, At, B1); PG8_BAR; PG8_SCHED;
	v_mfma_f32_16x16x32_bf16 v[60:63], v[144:147], v[216:219], v[60:63]
	v_mfma_f32_16x16x32_bf16 v[56:59], v[152:155], v[216:219], v[56:59]
	v_mfma_f32_16x16x32_bf16 v[44:47], v[144:147], v[224:227], v[44:47]
	v_mfma_f32_16x16x32_bf16 v[40:43], v[152:155], v[224:227], v[40:43]
	v_mfma_f32_16x16x32_bf16 v[28:31], v[144:147], v[232:235], v[28:31]
	v_mfma_f32_16x16x32_bf16 v[24:27], v[152:155], v[232:235], v[24:27]
	v_mfma_f32_16x16x32_bf16 v[12:15], v[144:147], v[240:243], v[12:15]
	v_mfma_f32_16x16x32_bf16 v[8:11], v[152:155], v[240:243], v[8:11]
	v_mfma_f32_16x16x32_bf16 v[60:63], v[148:151], v[220:223], v[60:63]
	v_mfma_f32_16x16x32_bf16 v[56:59], v[156:159], v[220:223], v[56:59]
	v_mfma_f32_16x16x32_bf16 v[44:47], v[148:151], v[228:231], v[44:47]
	v_mfma_f32_16x16x32_bf16 v[40:43], v[156:159], v[228:231], v[40:43]
	v_mfma_f32_16x16x32_bf16 v[28:31], v[148:151], v[236:239], v[28:31]
	v_mfma_f32_16x16x32_bf16 v[24:27], v[156:159], v[236:239], v[24:27]
	v_mfma_f32_16x16x32_bf16 v[12:15], v[148:151], v[244:247], v[12:15]
	v_mfma_f32_16x16x32_bf16 v[8:11], v[156:159], v[244:247], v[8:11]
	s_setprio 0
	s_setprio 1
	v_mfma_f32_16x16x32_bf16 v[52:55], v[160:163], v[216:219], v[52:55]
	v_mfma_f32_16x16x32_bf16 v[48:51], v[168:171], v[216:219], v[48:51]
	v_mfma_f32_16x16x32_bf16 v[36:39], v[160:163], v[224:227], v[36:39]
	v_mfma_f32_16x16x32_bf16 v[32:35], v[168:171], v[224:227], v[32:35]
	v_mfma_f32_16x16x32_bf16 v[20:23], v[160:163], v[232:235], v[20:23]
	v_mfma_f32_16x16x32_bf16 v[16:19], v[168:171], v[232:235], v[16:19]
	v_mfma_f32_16x16x32_bf16 v[4:7], v[160:163], v[240:243], v[4:7]
	v_mfma_f32_16x16x32_bf16 v[0:3], v[168:171], v[240:243], v[0:3]
	v_mfma_f32_16x16x32_bf16 v[52:55], v[164:167], v[220:223], v[52:55]
	v_mfma_f32_16x16x32_bf16 v[48:51], v[172:175], v[220:223], v[48:51]
	v_mfma_f32_16x16x32_bf16 v[36:39], v[164:167], v[228:231], v[36:39]
	v_mfma_f32_16x16x32_bf16 v[32:35], v[172:175], v[228:231], v[32:35]
	v_mfma_f32_16x16x32_bf16 v[20:23], v[164:167], v[236:239], v[20:23]
	v_mfma_f32_16x16x32_bf16 v[16:19], v[172:175], v[236:239], v[16:19]
	v_mfma_f32_16x16x32_bf16 v[4:7], v[164:167], v[244:247], v[4:7]
	v_mfma_f32_16x16x32_bf16 v[0:3], v[172:175], v[244:247], v[0:3]
	s_setprio 0
	s_barrier
	s_add_i32 s52, 0, 0x18000
	s_add_i32 s53, 0, 0x1c000
	v_add_u32_e32 v156, s52, v184
	v_add_u32_e32 v172, s53, v184
	ds_read_b128 v[144:147], v156
	ds_read_b128 v[148:151], v156 offset:1024
	ds_read_b128 v[152:155], v156 offset:2048
	ds_read_b128 v[156:159], v156 offset:3072
	ds_read_b128 v[160:163], v172
	ds_read_b128 v[164:167], v172 offset:1024
	ds_read_b128 v[168:171], v172 offset:2048
	ds_read_b128 v[172:175], v172 offset:3072
	s_add_u32 s26, s38, 0xb0000
	s_addc_u32 s27, s39, 0
	s_mov_b32 m0, s29
	ds_read_b128 v[216:219], v204 offset:32768
	ds_read_b128 v[220:223], v204 offset:33792
	ds_read_b128 v[224:227], v204 offset:34816
	ds_read_b128 v[228:231], v204 offset:35840
	ds_read_b128 v[232:235], v204 offset:36864
	ds_read_b128 v[236:239], v204 offset:37888
	ds_read_b128 v[240:243], v204 offset:38912
	ds_read_b128 v[244:247], v204 offset:39936
	global_load_lds_dwordx4 v128, s[26:27]
	s_mov_b32 m0, s30
	s_nop 0
	global_load_lds_dwordx4 v132, s[26:27]
	s_waitcnt vmcnt(8)
	s_waitcnt lgkmcnt(0)
	s_setprio 1
	s_barrier

; #define PG8_STAGE(bufoff, gbase, voff) do { _Pragma("unroll") for (int _i = 0; _i < 2; ++_i) \
;         __builtin_amdgcn_global_load_lds((const unsigned*)((const char*)(gbase) + (voff)[_i]), (LAS unsigned*)(lds + (bufoff) + ldsw + _i * 8192), 16, 0, 0); } while (0)
; #define PG8_LDA(dst, b, h) do { _Pragma("unroll") for (int m = 0; m < 4; ++m) _Pragma("unroll") for (int k = 0; k < 2; ++k) dst[m][k] = *(const LAS bf16x8*)(lds + PG8_SA(b, h) + aoff + m * 2048 + k * 1024); } while (0)
; #define PG8_MMA(ai, bj, At, Bt) do { __builtin_amdgcn_s_setprio(1); _Pragma("unroll") for (int m = 0; m < 4; ++m) _Pragma("unroll") for (int n = 0; n < 2; ++n) _Pragma("unroll") for (int k = 0; k < 2; ++k) \
;         acc[ai][bj][m][n] = __builtin_amdgcn_mfma_f32_16x16x32_bf16(Bt[n][k], At[m][k], acc[ai][bj][m][n], 0, 0, 0); __builtin_amdgcn_s_setprio(0); } while (0)
; #define PG8_WAIT_V(n) asm volatile("s_waitcnt vmcnt(" #n ")" ::: "memory")
; #define PG8_WAIT_L(n) asm volatile("s_waitcnt lgkmcnt(" #n ")" ::: "memory")
; #define PG8_BAR __builtin_amdgcn_s_barrier()
; #define PG8_SCHED __builtin_amdgcn_sched_barrier(0)
; template <class Epi>
; __device__ __forceinline__ void gemm_phase(LAS unsigned char* lds, const Gemm g, const StaticOrder& S, const Epi& E) {
;     ...
;             PG8_WAIT_V(8); PG8_WAIT_L(0); PG8_BAR; PG8_MMA(0, 0, At, B0); PG8_MMA(0, 1, At, B1); PG8_BAR; PG8_SCHED;
;             PG8_LDA(At, 1, 1); PG8_STAGE(PG8_SB(1, 0), b3, voffB); PG8_STAGE(PG8_SB(1, 1), b3 + hsB, voffB); PG8_STAGE(PG8_SA(1, 0), a3, voffA);
;             PG8_WAIT_V(8); PG8_WAIT_L(0); PG8_BAR; PG8_MMA(1, 0, At, B0); PG8_MMA(1, 1, At, B1); PG8_BAR; PG8_SCHED;
	v_mfma_f32_16x16x32_bf16 v[124:127], v[144:147], v[216:219], v[124:127]
	v_mfma_f32_16x16x32_bf16 v[120:123], v[152:155], v[216:219], v[120:123]
	v_mfma_f32_16x16x32_bf16 v[108:111], v[144:147], v[224:227], v[108:111]
	v_mfma_f32_16x16x32_bf16 v[104:107], v[152:155], v[224:227], v[104:107]
	v_mfma_f32_16x16x32_bf16 v[92:95], v[144:147], v[232:235], v[92:95]
	v_mfma_f32_16x16x32_bf16 v[88:91], v[152:155], v[232:235], v[88:91]
	v_mfma_f32_16x16x32_bf16 v[76:79], v[144:147], v[240:243], v[76:79]
	v_mfma_f32_16x16x32_bf16 v[72:75], v[152:155], v[240:243], v[72:75]
	v_mfma_f32_16x16x32_bf16 v[124:127], v[148:151], v[220:223], v[124:127]
	v_mfma_f32_16x16x32_bf16 v[120:123], v[156:159], v[220:223], v[120:123]
	v_mfma_f32_16x16x32_bf16 v[108:111], v[148:151], v[228:231], v[108:111]
	v_mfma_f32_16x16x32_bf16 v[104:107], v[156:159], v[228:231], v[104:107]
	v_mfma_f32_16x16x32_bf16 v[92:95], v[148:151], v[236:239], v[92:95]
	v_mfma_f32_16x16x32_bf16 v[88:91], v[156:159], v[236:239], v[88:91]
	v_mfma_f32_16x16x32_bf16 v[76:79], v[148:151], v[244:247], v[76:79]
	v_mfma_f32_16x16x32_bf16 v[72:75], v[156:159], v[244:247], v[72:75]
	s_setprio 0
	s_setprio 1
	v_mfma_f32_16x16x32_bf16 v[116:119], v[160:163], v[216:219], v[116:119]
	v_mfma_f32_16x16x32_bf16 v[112:115], v[168:171], v[216:219], v[112:115]
	v_mfma_f32_16x16x32_bf16 v[100:103], v[160:163], v[224:227], v[100:103]
	v_mfma_f32_16x16x32_bf16 v[96:99], v[168:171], v[224:227], v[96:99]
	v_mfma_f32_16x16x32_bf16 v[84:87], v[160:163], v[232:235], v[84:87]
	v_mfma_f32_16x16x32_bf16 v[80:83], v[168:171], v[232:235], v[80:83]
	v_mfma_f32_16x16x32_bf16 v[68:71], v[160:163], v[240:243], v[68:71]
	v_mfma_f32_16x16x32_bf16 v[64:67], v[168:171], v[240:243], v[64:67]
	v_mfma_f32_16x16x32_bf16 v[116:119], v[164:167], v[220:223], v[116:119]
	v_mfma_f32_16x16x32_bf16 v[112:115], v[172:175], v[220:223], v[112:115]
	v_mfma_f32_16x16x32_bf16 v[100:103], v[164:167], v[228:231], v[100:103]
	v_mfma_f32_16x16x32_bf16 v[96:99], v[172:175], v[228:231], v[96:99]
	v_mfma_f32_16x16x32_bf16 v[84:87], v[164:167], v[236:239], v[84:87]
	v_mfma_f32_16x16x32_bf16 v[80:83], v[172:175], v[236:239], v[80:83]
	v_mfma_f32_16x16x32_bf16 v[68:71], v[164:167], v[244:247], v[68:71]
	v_mfma_f32_16x16x32_bf16 v[64:67], v[172:175], v[244:247], v[64:67]
	s_setprio 0
	s_barrier
	s_add_u32 s98, s36, 0x80
	s_addc_u32 s99, s37, 0
	s_add_u32 s100, s38, 0x80
	s_addc_u32 s101, s39, 0
	s_add_i32 s26, s52, s16
	s_mov_b32 m0, s26
	ds_read_b128 v[216:219], v204 offset:49152
	ds_read_b128 v[220:223], v204 offset:50176
	ds_read_b128 v[224:227], v204 offset:51200
	ds_read_b128 v[228:231], v204 offset:52224
	ds_read_b128 v[232:235], v204 offset:53248
	ds_read_b128 v[236:239], v204 offset:54272
	ds_read_b128 v[240:243], v204 offset:55296
	ds_read_b128 v[244:247], v204 offset:56320
	global_load_lds_dwordx4 v130, s[98:99]
	s_add_i32 m0, s26, 0x2000
	s_add_u32 s26, s36, 0xb0080
	s_addc_u32 s27, s37, 0
	s_add_i32 s36, s53, s16
	global_load_lds_dwordx4 v134, s[98:99]
	s_mov_b32 m0, s36
	s_nop 0
	global_load_lds_dwordx4 v130, s[26:27]
	s_add_i32 m0, s36, 0x2000
	s_nop 0
	global_load_lds_dwordx4 v134, s[26:27]
	s_mov_b32 m0, s41
	s_nop 0
	global_load_lds_dwordx4 v128, s[100:101]
	s_mov_b32 m0, s42
	s_nop 0
	global_load_lds_dwordx4 v132, s[100:101]
	s_waitcnt vmcnt(8)
	s_waitcnt lgkmcnt(0)
	s_setprio 1
	s_barrier

; #define PG8_MMA(ai, bj, At, Bt) do { __builtin_amdgcn_s_setprio(1); _Pragma("unroll") for (int m = 0; m < 4; ++m) _Pragma("unroll") for (int n = 0; n < 2; ++n) _Pragma("unroll") for (int k = 0; k < 2; ++k) \
;         acc[ai][bj][m][n] = __builtin_amdgcn_mfma_f32_16x16x32_bf16(Bt[n][k], At[m][k], acc[ai][bj][m][n], 0, 0, 0); __builtin_amdgcn_s_setprio(0); } while (0)
; #define PG8_WAIT_V(n) asm volatile("s_waitcnt vmcnt(" #n ")" ::: "memory")
; #define PG8_WAIT_L(n) asm volatile("s_waitcnt lgkmcnt(" #n ")" ::: "memory")
; #define PG8_BAR __builtin_amdgcn_s_barrier()
; #define PG8_SCHED __builtin_amdgcn_sched_barrier(0)
; template <class Epi>
; __device__ __forceinline__ void gemm_phase(LAS unsigned char* lds, const Gemm g, const StaticOrder& S, const Epi& E) {
;     ...
;             PG8_WAIT_V(8); PG8_WAIT_L(0); PG8_BAR; PG8_MMA(1, 0, At, B0); PG8_MMA(1, 1, At, B1); PG8_BAR; PG8_SCHED;
;         }
;         if (wr == 0) PG8_BAR;
	v_mfma_f32_16x16x32_bf16 v[60:63], v[144:147], v[216:219], v[60:63]
	v_mfma_f32_16x16x32_bf16 v[56:59], v[152:155], v[216:219], v[56:59]
	v_mfma_f32_16x16x32_bf16 v[44:47], v[144:147], v[224:227], v[44:47]
	v_mfma_f32_16x16x32_bf16 v[40:43], v[152:155], v[224:227], v[40:43]
	v_mfma_f32_16x16x32_bf16 v[28:31], v[144:147], v[232:235], v[28:31]
	v_mfma_f32_16x16x32_bf16 v[24:27], v[152:155], v[232:235], v[24:27]
	v_mfma_f32_16x16x32_bf16 v[12:15], v[144:147], v[240:243], v[12:15]
	v_mfma_f32_16x16x32_bf16 v[8:11], v[152:155], v[240:243], v[8:11]
	v_mfma_f32_16x16x32_bf16 v[60:63], v[148:151], v[220:223], v[60:63]
	v_mfma_f32_16x16x32_bf16 v[56:59], v[156:159], v[220:223], v[56:59]
	v_mfma_f32_16x16x32_bf16 v[44:47], v[148:151], v[228:231], v[44:47]
	v_mfma_f32_16x16x32_bf16 v[40:43], v[156:159], v[228:231], v[40:43]
	v_mfma_f32_16x16x32_bf16 v[28:31], v[148:151], v[236:239], v[28:31]
	v_mfma_f32_16x16x32_bf16 v[24:27], v[156:159], v[236:239], v[24:27]
	v_mfma_f32_16x16x32_bf16 v[12:15], v[148:151], v[244:247], v[12:15]
	v_mfma_f32_16x16x32_bf16 v[8:11], v[156:159], v[244:247], v[8:11]
	s_setprio 0
	s_setprio 1
	v_mfma_f32_16x16x32_bf16 v[52:55], v[160:163], v[216:219], v[52:55]
	v_mfma_f32_16x16x32_bf16 v[48:51], v[168:171], v[216:219], v[48:51]
	v_mfma_f32_16x16x32_bf16 v[36:39], v[160:163], v[224:227], v[36:39]
	v_mfma_f32_16x16x32_bf16 v[32:35], v[168:171], v[224:227], v[32:35]
	v_mfma_f32_16x16x32_bf16 v[20:23], v[160:163], v[232:235], v[20:23]
	v_mfma_f32_16x16x32_bf16 v[16:19], v[168:171], v[232:235], v[16:19]
	v_mfma_f32_16x16x32_bf16 v[4:7], v[160:163], v[240:243], v[4:7]
	v_mfma_f32_16x16x32_bf16 v[0:3], v[168:171], v[240:243], v[0:3]
	v_mfma_f32_16x16x32_bf16 v[52:55], v[164:167], v[220:223], v[52:55]
	v_mfma_f32_16x16x32_bf16 v[48:51], v[172:175], v[220:223], v[48:51]
	v_mfma_f32_16x16x32_bf16 v[36:39], v[164:167], v[228:231], v[36:39]
	v_mfma_f32_16x16x32_bf16 v[32:35], v[172:175], v[228:231], v[32:35]
	v_mfma_f32_16x16x32_bf16 v[20:23], v[164:167], v[236:239], v[20:23]
	v_mfma_f32_16x16x32_bf16 v[16:19], v[172:175], v[236:239], v[16:19]
	v_mfma_f32_16x16x32_bf16 v[4:7], v[164:167], v[244:247], v[4:7]
	v_mfma_f32_16x16x32_bf16 v[0:3], v[172:175], v[244:247], v[0:3]
	s_setprio 0
	s_barrier
	s_add_i32 s51, s51, 2
	s_add_u32 s25, s25, 0x100
	s_addc_u32 s50, s50, 0
	s_cmp_gt_u32 s51, 41
	s_mov_b64 s[26:27], s[34:35]
	s_cbranch_scc0 .LBB0_1433
	s_and_b64 vcc, exec, s[18:19]
	s_cbranch_vccz .LBB0_1436
	s_barrier
